# nmajor_S_S2
# speedup vs baseline: 1.0123x; 1.0123x over previous
;     __device__ bool next(int i, Unit& u) const { if (!base.next(i >> 1, u)) return false; u.sub = i & 1; return true; }
; #define PG8_STAGE(bufoff, gbase, voff) do { _Pragma("unroll") for (int _i = 0; _i < 2; ++_i) \
;         __builtin_amdgcn_global_load_lds((const unsigned*)((const char*)(gbase) + (voff)[_i]), (PG8_LAS unsigned*)(lds + (bufoff) + ldsw + _i * 8192), 16, 0, 0); } while (0)
; #define PG8_LDA(dst, b, h) do { _Pragma("unroll") for (int m = 0; m < 4; ++m) _Pragma("unroll") for (int k = 0; k < 2; ++k) dst[m][k] = *(const PG8_LAS bf16x8*)(lds + PG8_SA(b, h) + aoff + m * 2048 + k * 1024); } while (0)
; #define PG8_LDB(dst, b, h) do { _Pragma("unroll") for (int n = 0; n < 2; ++n) _Pragma("unroll") for (int k = 0; k < 2; ++k) dst[n][k] = *(const PG8_LAS bf16x8*)(lds + PG8_SB(b, h) + boff + n * 2048 + k * 1024); } while (0)
; #define PG8_WAIT_V(n) asm volatile("s_waitcnt vmcnt(" #n ")" ::: "memory")
; template <class Epi, class Sched, bool ALIGN_EPI = false, bool SP2 = false, bool DUAL = false>
; __device__ __forceinline__ void gemm_phase(PG8_LAS unsigned char* lds, const Gemm g, const Sched& S, const Epi& E) {
;     ...
;         const bool has_next = S.next(ui + 1, nxt);
;         const char* nA = has_next ? (const char*)((DUAL && nxt.sub) ? g.A2 : g.A) + (size_t)nxt.pm * tstep : cA; const char* nB = has_next ? (const char*)((DUAL && nxt.sub) ? g.Bt2 : g.Bt) + (size_t)nxt.pn * tstep : cB;
;         for (int t = 0; t < nt; t += 2) {
;             const bool last = (t == nt - 2);
;             const char* a1 = cA + (size_t)(t + 1) * kstep;
;             const char* a2 = last ? nA : cA + (size_t)(t + 2) * kstep; const char* b2 = last ? nB : cB + (size_t)(t + 2) * kstep;
;             const char* a3 = a2 + kstep; const char* b3 = b2 + kstep;
;             if (last && has_next) S.a_ready(nxt);
;             if constexpr (SP2) {
;             PG8_LDB(B0, 0, 0); PG8_LDB(B1, 0, 1); PG8_SCHED; PG8_LDA(At, 0, 0); PG8_STAGE(PG8_SA(1, 1), a1 + hstep, voffA);
;             PG8_WAIT_V(8); PG8_WAIT_L(0); PG8_BAR; PG8_MMA(0, 0, At, B0); PG8_MMA(0, 1, At, B1); PG8_BAR; PG8_SCHED;
;             PG8_LDA(At, 0, 1); PG8_STAGE(PG8_SB(0, 0), b2, voffB); PG8_STAGE(PG8_SB(0, 1), b2 + hstep, voffB); PG8_STAGE(PG8_SA(0, 0), a2, voffA);
;             PG8_WAIT_V(8); PG8_WAIT_L(0); PG8_BAR; PG8_MMA(1, 0, At, B0); PG8_MMA(1, 1, At, B1); PG8_BAR; PG8_SCHED;
.LBB0_251:
	s_ashr_i32 s87, s86, 31
	s_lshl_b64 s[16:17], s[86:87], 20
	s_add_u32 s92, s58, s16
	s_addc_u32 s93, s59, s17
	s_and_b64 s[16:17], s[4:5], exec
	s_cselect_b32 s7, s93, s11
	s_cselect_b32 s9, s92, s10
	s_ashr_i32 s1, s0, 31
	s_lshl_b64 s[16:17], s[0:1], 20
	s_add_u32 s88, s90, s16
	s_addc_u32 s89, s91, s17
	s_and_b64 s[16:17], s[4:5], exec
	s_cselect_b32 s1, s89, s15
	s_cselect_b32 s45, s88, s14
	s_add_u32 s10, s10, 0x80080
	s_addc_u32 s11, s11, 0
	s_add_u32 s46, s14, 0x100
	s_addc_u32 s47, s15, 0
	s_mov_b32 s48, -2
	s_add_u32 s14, s10, 0xfff80080
	s_addc_u32 s15, s11, -1
	s_cmp_eq_u32 s48, 28
	s_cselect_b32 s17, s7, s15
	s_cselect_b32 s16, s9, s14
	s_cselect_b32 s15, s1, s47
	s_cselect_b32 s14, s45, s46
	s_waitcnt vmcnt(8)
	s_waitcnt lgkmcnt(0)
	s_setprio 1
	s_barrier
	v_mfma_f32_16x16x32_bf16 v[140:143], v[80:83], v[208:211], 0
	v_mfma_f32_16x16x32_bf16 v[140:143], v[84:87], v[212:215], v[140:143]
	v_mfma_f32_16x16x32_bf16 v[124:127], v[80:83], v[216:219], 0
	v_mfma_f32_16x16x32_bf16 v[124:127], v[84:87], v[220:223], v[124:127]
	v_mfma_f32_16x16x32_bf16 v[108:111], v[80:83], v[232:235], 0
	v_mfma_f32_16x16x32_bf16 v[108:111], v[84:87], v[236:239], v[108:111]
	v_mfma_f32_16x16x32_bf16 v[76:79], v[80:83], v[240:243], 0
	v_mfma_f32_16x16x32_bf16 v[76:79], v[84:87], v[244:247], v[76:79]
	v_mfma_f32_16x16x32_bf16 v[132:135], v[88:91], v[208:211], 0
	v_mfma_f32_16x16x32_bf16 v[132:135], v[92:95], v[212:215], v[132:135]
	v_mfma_f32_16x16x32_bf16 v[120:123], v[88:91], v[216:219], 0
	v_mfma_f32_16x16x32_bf16 v[120:123], v[92:95], v[220:223], v[120:123]
	v_mfma_f32_16x16x32_bf16 v[104:107], v[88:91], v[232:235], 0
	v_mfma_f32_16x16x32_bf16 v[104:107], v[92:95], v[236:239], v[104:107]
	v_mfma_f32_16x16x32_bf16 v[72:75], v[88:91], v[240:243], 0
	v_mfma_f32_16x16x32_bf16 v[72:75], v[92:95], v[244:247], v[72:75]
	s_setprio 0
	s_setprio 1
	v_mfma_f32_16x16x32_bf16 v[136:139], v[144:147], v[208:211], 0
	v_mfma_f32_16x16x32_bf16 v[136:139], v[148:151], v[212:215], v[136:139]
	v_mfma_f32_16x16x32_bf16 v[116:119], v[144:147], v[216:219], 0
	v_mfma_f32_16x16x32_bf16 v[116:119], v[148:151], v[220:223], v[116:119]
	v_mfma_f32_16x16x32_bf16 v[100:103], v[144:147], v[232:235], 0
	v_mfma_f32_16x16x32_bf16 v[100:103], v[148:151], v[236:239], v[100:103]
	v_mfma_f32_16x16x32_bf16 v[68:71], v[144:147], v[240:243], 0
	v_mfma_f32_16x16x32_bf16 v[68:71], v[148:151], v[244:247], v[68:71]
	v_mfma_f32_16x16x32_bf16 v[128:131], v[152:155], v[208:211], 0
	v_mfma_f32_16x16x32_bf16 v[128:131], v[156:159], v[212:215], v[128:131]
	v_mfma_f32_16x16x32_bf16 v[112:115], v[152:155], v[216:219], 0
	v_mfma_f32_16x16x32_bf16 v[112:115], v[156:159], v[220:223], v[112:115]
	v_mfma_f32_16x16x32_bf16 v[96:99], v[152:155], v[232:235], 0
	v_mfma_f32_16x16x32_bf16 v[96:99], v[156:159], v[236:239], v[96:99]
	v_mfma_f32_16x16x32_bf16 v[64:67], v[152:155], v[240:243], 0
	v_mfma_f32_16x16x32_bf16 v[64:67], v[156:159], v[244:247], v[64:67]
	s_barrier
	s_setprio 0
	s_add_u32 s98, s14, 0x80
	s_addc_u32 s99, s15, 0
	s_add_u32 s100, s16, 0x80
	s_addc_u32 s101, s17, 0
	s_add_i32 m0, s19, 0xc000
	s_nop 0
	global_load_lds_dwordx4 v186, s[10:11]
	s_add_i32 m0, s19, 0xe000
	s_nop 0
	global_load_lds_dwordx4 v188, s[10:11]
	s_add_i32 s49, s31, s18
	s_mov_b32 m0, s49
	ds_read_b128 v[208:211], v203 offset:16384
	ds_read_b128 v[212:215], v203 offset:17408
	ds_read_b128 v[216:219], v203 offset:18432
	ds_read_b128 v[220:223], v203 offset:19456
	ds_read_b128 v[232:235], v203 offset:20480
	ds_read_b128 v[236:239], v203 offset:21504
	ds_read_b128 v[240:243], v203 offset:22528
	ds_read_b128 v[244:247], v203 offset:23552
	global_load_lds_dwordx4 v166, s[14:15]
	s_add_i32 m0, s49, 0x2000
	s_add_u32 s50, s14, 0x80000
	s_addc_u32 s51, s15, 0
	s_add_i32 s49, s34, s18
	global_load_lds_dwordx4 v170, s[14:15]
	s_mov_b32 m0, s49
	s_nop 0
	global_load_lds_dwordx4 v166, s[50:51]
	s_add_i32 m0, s49, 0x2000
	s_nop 0
	global_load_lds_dwordx4 v170, s[50:51]
	s_mov_b32 m0, s19
	s_nop 0
	global_load_lds_dwordx4 v164, s[16:17]
	s_mov_b32 m0, s20
	s_nop 0
	global_load_lds_dwordx4 v168, s[16:17]
	s_waitcnt vmcnt(8)
	s_waitcnt lgkmcnt(0)
	s_setprio 1
	s_barrier
	v_mfma_f32_16x16x32_bf16 v[60:63], v[80:83], v[208:211], 0
	v_mfma_f32_16x16x32_bf16 v[60:63], v[84:87], v[212:215], v[60:63]
	v_mfma_f32_16x16x32_bf16 v[44:47], v[80:83], v[216:219], 0
	v_mfma_f32_16x16x32_bf16 v[44:47], v[84:87], v[220:223], v[44:47]
	v_mfma_f32_16x16x32_bf16 v[28:31], v[80:83], v[232:235], 0
	v_mfma_f32_16x16x32_bf16 v[28:31], v[84:87], v[236:239], v[28:31]
	v_mfma_f32_16x16x32_bf16 v[12:15], v[80:83], v[240:243], 0
	v_mfma_f32_16x16x32_bf16 v[12:15], v[84:87], v[244:247], v[12:15]
	v_mfma_f32_16x16x32_bf16 v[56:59], v[88:91], v[208:211], 0
	v_mfma_f32_16x16x32_bf16 v[56:59], v[92:95], v[212:215], v[56:59]
	v_mfma_f32_16x16x32_bf16 v[40:43], v[88:91], v[216:219], 0
	v_mfma_f32_16x16x32_bf16 v[40:43], v[92:95], v[220:223], v[40:43]
	v_mfma_f32_16x16x32_bf16 v[24:27], v[88:91], v[232:235], 0
	v_mfma_f32_16x16x32_bf16 v[24:27], v[92:95], v[236:239], v[24:27]
	v_mfma_f32_16x16x32_bf16 v[8:11], v[88:91], v[240:243], 0
	v_mfma_f32_16x16x32_bf16 v[8:11], v[92:95], v[244:247], v[8:11]
	s_setprio 0
	s_setprio 1
	v_mfma_f32_16x16x32_bf16 v[52:55], v[144:147], v[208:211], 0
	v_mfma_f32_16x16x32_bf16 v[52:55], v[148:151], v[212:215], v[52:55]
	v_mfma_f32_16x16x32_bf16 v[36:39], v[144:147], v[216:219], 0
	v_mfma_f32_16x16x32_bf16 v[36:39], v[148:151], v[220:223], v[36:39]
	v_mfma_f32_16x16x32_bf16 v[20:23], v[144:147], v[232:235], 0
	v_mfma_f32_16x16x32_bf16 v[20:23], v[148:151], v[236:239], v[20:23]
	v_mfma_f32_16x16x32_bf16 v[4:7], v[144:147], v[240:243], 0
	v_mfma_f32_16x16x32_bf16 v[4:7], v[148:151], v[244:247], v[4:7]
	v_mfma_f32_16x16x32_bf16 v[48:51], v[152:155], v[208:211], 0
	v_mfma_f32_16x16x32_bf16 v[48:51], v[156:159], v[212:215], v[48:51]
	v_mfma_f32_16x16x32_bf16 v[32:35], v[152:155], v[216:219], 0
	v_mfma_f32_16x16x32_bf16 v[32:35], v[156:159], v[220:223], v[32:35]
	v_mfma_f32_16x16x32_bf16 v[16:19], v[152:155], v[232:235], 0
	v_mfma_f32_16x16x32_bf16 v[16:19], v[156:159], v[236:239], v[16:19]
	v_mfma_f32_16x16x32_bf16 v[0:3], v[152:155], v[240:243], 0
	v_mfma_f32_16x16x32_bf16 v[0:3], v[156:159], v[244:247], v[0:3]
	s_barrier
; #define PG8_STAGE(bufoff, gbase, voff) do { _Pragma("unroll") for (int _i = 0; _i < 2; ++_i) \
;         __builtin_amdgcn_global_load_lds((const unsigned*)((const char*)(gbase) + (voff)[_i]), (PG8_LAS unsigned*)(lds + (bufoff) + ldsw + _i * 8192), 16, 0, 0); } while (0)
; #define PG8_LDA(dst, b, h) do { _Pragma("unroll") for (int m = 0; m < 4; ++m) _Pragma("unroll") for (int k = 0; k < 2; ++k) dst[m][k] = *(const PG8_LAS bf16x8*)(lds + PG8_SA(b, h) + aoff + m * 2048 + k * 1024); } while (0)
; #define PG8_LDB(dst, b, h) do { _Pragma("unroll") for (int n = 0; n < 2; ++n) _Pragma("unroll") for (int k = 0; k < 2; ++k) dst[n][k] = *(const PG8_LAS bf16x8*)(lds + PG8_SB(b, h) + boff + n * 2048 + k * 1024); } while (0)
; #define PG8_MMA(ai, bj, At, Bt) do { __builtin_amdgcn_s_setprio(1); _Pragma("unroll") for (int m = 0; m < 4; ++m) _Pragma("unroll") for (int n = 0; n < 2; ++n) _Pragma("unroll") for (int k = 0; k < 2; ++k) \
;         acc[ai][bj][m][n] = __builtin_amdgcn_mfma_f32_16x16x32_bf16(Bt[n][k], At[m][k], acc[ai][bj][m][n], 0, 0, 0); __builtin_amdgcn_s_setprio(0); } while (0)
; #define PG8_WAIT_V(n) asm volatile("s_waitcnt vmcnt(" #n ")" ::: "memory")
; #define PG8_WAIT_L(n) asm volatile("s_waitcnt lgkmcnt(" #n ")" ::: "memory")
; #define PG8_BAR __builtin_amdgcn_s_barrier()
; #define PG8_SCHED __builtin_amdgcn_sched_barrier(0)
; template <class Epi, class Sched, bool ALIGN_EPI = false, bool SP2 = false, bool DUAL = false>
; __device__ __forceinline__ void gemm_phase(PG8_LAS unsigned char* lds, const Gemm g, const Sched& S, const Epi& E) {
;     ...
;             PG8_LDB(B0, 1, 0); PG8_LDB(B1, 1, 1); PG8_SCHED; PG8_LDA(At, 1, 0); PG8_STAGE(PG8_SA(0, 1), a2 + hstep, voffA);
;             PG8_WAIT_V(8); PG8_WAIT_L(0); PG8_BAR; PG8_MMA(0, 0, At, B0); PG8_MMA(0, 1, At, B1); PG8_BAR; PG8_SCHED;
;             PG8_LDA(At, 1, 1); PG8_STAGE(PG8_SB(1, 0), b3, voffB); PG8_STAGE(PG8_SB(1, 1), b3 + hstep, voffB); PG8_STAGE(PG8_SA(1, 0), a3, voffA);
;             PG8_WAIT_V(8); PG8_WAIT_L(0); PG8_BAR; PG8_MMA(1, 0, At, B0); PG8_MMA(1, 1, At, B1); PG8_BAR; PG8_SCHED;
	s_setprio 0
	s_add_i32 s49, 0, 0x18000
	s_add_i32 s50, 0, 0x1c000
	v_add_u32_e32 v92, s49, v196
	v_add_u32_e32 v156, s50, v196
	ds_read_b128 v[80:83], v92
	ds_read_b128 v[84:87], v92 offset:1024
	ds_read_b128 v[88:91], v92 offset:2048
	ds_read_b128 v[92:95], v92 offset:3072
	ds_read_b128 v[144:147], v156
	ds_read_b128 v[148:151], v156 offset:1024
	ds_read_b128 v[152:155], v156 offset:2048
	ds_read_b128 v[156:159], v156 offset:3072
	s_add_u32 s16, s16, 0x80000
	s_addc_u32 s17, s17, 0
	s_mov_b32 m0, s21
	ds_read_b128 v[208:211], v203 offset:32768
	ds_read_b128 v[212:215], v203 offset:33792
	ds_read_b128 v[216:219], v203 offset:34816
	ds_read_b128 v[220:223], v203 offset:35840
	ds_read_b128 v[232:235], v203 offset:36864
	ds_read_b128 v[236:239], v203 offset:37888
	ds_read_b128 v[240:243], v203 offset:38912
	ds_read_b128 v[244:247], v203 offset:39936
	global_load_lds_dwordx4 v164, s[16:17]
	s_mov_b32 m0, s22
	s_nop 0
	global_load_lds_dwordx4 v168, s[16:17]
	s_waitcnt vmcnt(8)
	s_waitcnt lgkmcnt(0)
	s_setprio 1
	s_barrier
	v_mfma_f32_16x16x32_bf16 v[140:143], v[80:83], v[208:211], v[140:143]
	v_mfma_f32_16x16x32_bf16 v[140:143], v[84:87], v[212:215], v[140:143]
	v_mfma_f32_16x16x32_bf16 v[124:127], v[80:83], v[216:219], v[124:127]
	v_mfma_f32_16x16x32_bf16 v[124:127], v[84:87], v[220:223], v[124:127]
	v_mfma_f32_16x16x32_bf16 v[108:111], v[80:83], v[232:235], v[108:111]
	v_mfma_f32_16x16x32_bf16 v[108:111], v[84:87], v[236:239], v[108:111]
	v_mfma_f32_16x16x32_bf16 v[76:79], v[80:83], v[240:243], v[76:79]
	v_mfma_f32_16x16x32_bf16 v[76:79], v[84:87], v[244:247], v[76:79]
	v_mfma_f32_16x16x32_bf16 v[132:135], v[88:91], v[208:211], v[132:135]
	v_mfma_f32_16x16x32_bf16 v[132:135], v[92:95], v[212:215], v[132:135]
	v_mfma_f32_16x16x32_bf16 v[120:123], v[88:91], v[216:219], v[120:123]
	v_mfma_f32_16x16x32_bf16 v[120:123], v[92:95], v[220:223], v[120:123]
	v_mfma_f32_16x16x32_bf16 v[104:107], v[88:91], v[232:235], v[104:107]
	v_mfma_f32_16x16x32_bf16 v[104:107], v[92:95], v[236:239], v[104:107]
	v_mfma_f32_16x16x32_bf16 v[72:75], v[88:91], v[240:243], v[72:75]
	v_mfma_f32_16x16x32_bf16 v[72:75], v[92:95], v[244:247], v[72:75]
	s_setprio 0
	s_setprio 1
	v_mfma_f32_16x16x32_bf16 v[136:139], v[144:147], v[208:211], v[136:139]
	v_mfma_f32_16x16x32_bf16 v[136:139], v[148:151], v[212:215], v[136:139]
	v_mfma_f32_16x16x32_bf16 v[116:119], v[144:147], v[216:219], v[116:119]
	v_mfma_f32_16x16x32_bf16 v[116:119], v[148:151], v[220:223], v[116:119]
	v_mfma_f32_16x16x32_bf16 v[100:103], v[144:147], v[232:235], v[100:103]
	v_mfma_f32_16x16x32_bf16 v[100:103], v[148:151], v[236:239], v[100:103]
	v_mfma_f32_16x16x32_bf16 v[68:71], v[144:147], v[240:243], v[68:71]
	v_mfma_f32_16x16x32_bf16 v[68:71], v[148:151], v[244:247], v[68:71]
	v_mfma_f32_16x16x32_bf16 v[128:131], v[152:155], v[208:211], v[128:131]
	v_mfma_f32_16x16x32_bf16 v[128:131], v[156:159], v[212:215], v[128:131]
	v_mfma_f32_16x16x32_bf16 v[112:115], v[152:155], v[216:219], v[112:115]
	v_mfma_f32_16x16x32_bf16 v[112:115], v[156:159], v[220:223], v[112:115]
	v_mfma_f32_16x16x32_bf16 v[96:99], v[152:155], v[232:235], v[96:99]
	v_mfma_f32_16x16x32_bf16 v[96:99], v[156:159], v[236:239], v[96:99]
	v_mfma_f32_16x16x32_bf16 v[64:67], v[152:155], v[240:243], v[64:67]
	v_mfma_f32_16x16x32_bf16 v[64:67], v[156:159], v[244:247], v[64:67]
	s_barrier
	s_setprio 0
	s_add_i32 s16, s49, s18
	s_mov_b32 m0, s16
	ds_read_b128 v[208:211], v203 offset:49152
	ds_read_b128 v[212:215], v203 offset:50176
	ds_read_b128 v[216:219], v203 offset:51200
	ds_read_b128 v[220:223], v203 offset:52224
	ds_read_b128 v[232:235], v203 offset:53248
	ds_read_b128 v[236:239], v203 offset:54272
	ds_read_b128 v[240:243], v203 offset:55296
	ds_read_b128 v[244:247], v203 offset:56320
	global_load_lds_dwordx4 v166, s[98:99]
	s_add_i32 m0, s16, 0x2000
	s_add_u32 s14, s14, 0x80080
	s_addc_u32 s15, s15, 0
	s_add_i32 s16, s50, s18
	global_load_lds_dwordx4 v170, s[98:99]
	s_mov_b32 m0, s16
	s_nop 0
	global_load_lds_dwordx4 v166, s[14:15]
	s_add_i32 m0, s16, 0x2000
	s_nop 0
	global_load_lds_dwordx4 v170, s[14:15]
	s_mov_b32 m0, s27
	s_nop 0
	global_load_lds_dwordx4 v164, s[100:101]
	s_mov_b32 m0, s28
	s_nop 0
	global_load_lds_dwordx4 v168, s[100:101]
	s_waitcnt vmcnt(8)
	s_waitcnt lgkmcnt(0)
	s_setprio 1
	s_barrier
	v_mfma_f32_16x16x32_bf16 v[60:63], v[80:83], v[208:211], v[60:63]
	v_mfma_f32_16x16x32_bf16 v[60:63], v[84:87], v[212:215], v[60:63]
	v_mfma_f32_16x16x32_bf16 v[44:47], v[80:83], v[216:219], v[44:47]
	v_mfma_f32_16x16x32_bf16 v[44:47], v[84:87], v[220:223], v[44:47]
	v_mfma_f32_16x16x32_bf16 v[28:31], v[80:83], v[232:235], v[28:31]
	v_mfma_f32_16x16x32_bf16 v[28:31], v[84:87], v[236:239], v[28:31]
	v_mfma_f32_16x16x32_bf16 v[12:15], v[80:83], v[240:243], v[12:15]
	v_mfma_f32_16x16x32_bf16 v[12:15], v[84:87], v[244:247], v[12:15]
	v_mfma_f32_16x16x32_bf16 v[56:59], v[88:91], v[208:211], v[56:59]
	v_mfma_f32_16x16x32_bf16 v[56:59], v[92:95], v[212:215], v[56:59]
	v_mfma_f32_16x16x32_bf16 v[40:43], v[88:91], v[216:219], v[40:43]
	v_mfma_f32_16x16x32_bf16 v[40:43], v[92:95], v[220:223], v[40:43]
	v_mfma_f32_16x16x32_bf16 v[24:27], v[88:91], v[232:235], v[24:27]
	v_mfma_f32_16x16x32_bf16 v[24:27], v[92:95], v[236:239], v[24:27]
	v_mfma_f32_16x16x32_bf16 v[8:11], v[88:91], v[240:243], v[8:11]
	v_mfma_f32_16x16x32_bf16 v[8:11], v[92:95], v[244:247], v[8:11]
	s_setprio 0
	s_setprio 1
	v_mfma_f32_16x16x32_bf16 v[52:55], v[144:147], v[208:211], v[52:55]
	v_mfma_f32_16x16x32_bf16 v[52:55], v[148:151], v[212:215], v[52:55]
	v_mfma_f32_16x16x32_bf16 v[36:39], v[144:147], v[216:219], v[36:39]
	v_mfma_f32_16x16x32_bf16 v[36:39], v[148:151], v[220:223], v[36:39]
	v_mfma_f32_16x16x32_bf16 v[20:23], v[144:147], v[232:235], v[20:23]
	v_mfma_f32_16x16x32_bf16 v[20:23], v[148:151], v[236:239], v[20:23]
	v_mfma_f32_16x16x32_bf16 v[4:7], v[144:147], v[240:243], v[4:7]
	v_mfma_f32_16x16x32_bf16 v[4:7], v[148:151], v[244:247], v[4:7]
	v_mfma_f32_16x16x32_bf16 v[48:51], v[152:155], v[208:211], v[48:51]
	v_mfma_f32_16x16x32_bf16 v[48:51], v[156:159], v[212:215], v[48:51]
	v_mfma_f32_16x16x32_bf16 v[32:35], v[152:155], v[216:219], v[32:35]
	v_mfma_f32_16x16x32_bf16 v[32:35], v[156:159], v[220:223], v[32:35]
	v_mfma_f32_16x16x32_bf16 v[16:19], v[152:155], v[232:235], v[16:19]
	v_mfma_f32_16x16x32_bf16 v[16:19], v[156:159], v[236:239], v[16:19]
	v_mfma_f32_16x16x32_bf16 v[0:3], v[152:155], v[240:243], v[0:3]
	v_mfma_f32_16x16x32_bf16 v[0:3], v[156:159], v[244:247], v[0:3]
	s_barrier
	s_setprio 0
	s_add_i32 s48, s48, 2
	s_add_u32 s10, s10, 0x100
	s_addc_u32 s11, s11, 0
	s_add_u32 s46, s46, 0x100
	s_addc_u32 s47, s47, 0
; #define PG8_STAGE(bufoff, gbase, voff) do { _Pragma("unroll") for (int _i = 0; _i < 2; ++_i) \
;         __builtin_amdgcn_global_load_lds((const unsigned*)((const char*)(gbase) + (voff)[_i]), (PG8_LAS unsigned*)(lds + (bufoff) + ldsw + _i * 8192), 16, 0, 0); } while (0)
; #define PG8_LDA(dst, b, h) do { _Pragma("unroll") for (int m = 0; m < 4; ++m) _Pragma("unroll") for (int k = 0; k < 2; ++k) dst[m][k] = *(const PG8_LAS bf16x8*)(lds + PG8_SA(b, h) + aoff + m * 2048 + k * 1024); } while (0)
; #define PG8_LDB(dst, b, h) do { _Pragma("unroll") for (int n = 0; n < 2; ++n) _Pragma("unroll") for (int k = 0; k < 2; ++k) dst[n][k] = *(const PG8_LAS bf16x8*)(lds + PG8_SB(b, h) + boff + n * 2048 + k * 1024); } while (0)
; #define PG8_MMA(ai, bj, At, Bt) do { __builtin_amdgcn_s_setprio(1); _Pragma("unroll") for (int m = 0; m < 4; ++m) _Pragma("unroll") for (int n = 0; n < 2; ++n) _Pragma("unroll") for (int k = 0; k < 2; ++k) \
;         acc[ai][bj][m][n] = __builtin_amdgcn_mfma_f32_16x16x32_bf16(Bt[n][k], At[m][k], acc[ai][bj][m][n], 0, 0, 0); __builtin_amdgcn_s_setprio(0); } while (0)
; #define PG8_WAIT_V(n) asm volatile("s_waitcnt vmcnt(" #n ")" ::: "memory")
; #define PG8_BAR __builtin_amdgcn_s_barrier()
; template <class Epi, class Sched, bool ALIGN_EPI = false, bool SP2 = false, bool DUAL = false>
; __device__ __forceinline__ void gemm_phase(PG8_LAS unsigned char* lds, const Gemm g, const Sched& S, const Epi& E) {
;     ...
;         for (int t = 0; t < nt; t += 2) {
;             const bool last = (t == nt - 2);
;             const char* a1 = cA + (size_t)(t + 1) * kstep;
;             const char* a2 = last ? nA : cA + (size_t)(t + 2) * kstep; const char* b2 = last ? nB : cB + (size_t)(t + 2) * kstep;
;             const char* a3 = a2 + kstep; const char* b3 = b2 + kstep;
;             if (last && has_next) S.a_ready(nxt);
;             if constexpr (SP2) {
;             PG8_LDB(B0, 0, 0); PG8_LDB(B1, 0, 1); PG8_SCHED; PG8_LDA(At, 0, 0); PG8_STAGE(PG8_SA(1, 1), a1 + hstep, voffA);
;             PG8_WAIT_V(8); PG8_WAIT_L(0); PG8_BAR; PG8_MMA(0, 0, At, B0); PG8_MMA(0, 1, At, B1); PG8_BAR; PG8_SCHED;
;             PG8_LDA(At, 0, 1); PG8_STAGE(PG8_SB(0, 0), b2, voffB); PG8_STAGE(PG8_SB(0, 1), b2 + hstep, voffB); PG8_STAGE(PG8_SA(0, 0), a2, voffA);
;             PG8_WAIT_V(8); PG8_WAIT_L(0); PG8_BAR; PG8_MMA(1, 0, At, B0); PG8_MMA(1, 1, At, B1); PG8_BAR; PG8_SCHED;
.LBB0_252:
	ds_read_b128 v[80:83], v199
	ds_read_b128 v[84:87], v199 offset:1024
	ds_read_b128 v[88:91], v199 offset:2048
	ds_read_b128 v[92:95], v199 offset:3072
	ds_read_b128 v[144:147], v202
	ds_read_b128 v[148:151], v202 offset:1024
	ds_read_b128 v[152:155], v202 offset:2048
	ds_read_b128 v[156:159], v202 offset:3072
	s_add_u32 s14, s10, 0xfff80080
	s_addc_u32 s15, s11, -1
	s_cmp_eq_u32 s48, 28
	s_cselect_b32 s17, s7, s15
	s_cselect_b32 s16, s9, s14
	s_cselect_b32 s15, s1, s47
	s_cselect_b32 s14, s45, s46
	s_add_i32 m0, s19, 0xc000
	ds_read_b128 v[208:211], v203
	ds_read_b128 v[212:215], v203 offset:1024
	ds_read_b128 v[216:219], v203 offset:2048
	ds_read_b128 v[220:223], v203 offset:3072
	ds_read_b128 v[232:235], v203 offset:4096
	ds_read_b128 v[236:239], v203 offset:5120
	ds_read_b128 v[240:243], v203 offset:6144
	ds_read_b128 v[244:247], v203 offset:7168
	global_load_lds_dwordx4 v186, s[10:11]
	s_add_i32 m0, s19, 0xe000
	s_nop 0
	global_load_lds_dwordx4 v188, s[10:11]
	s_waitcnt vmcnt(8)
	s_waitcnt lgkmcnt(0)
	s_setprio 1
	s_barrier
	v_mfma_f32_16x16x32_bf16 v[140:143], v[80:83], v[208:211], v[140:143]
	v_mfma_f32_16x16x32_bf16 v[140:143], v[84:87], v[212:215], v[140:143]
	v_mfma_f32_16x16x32_bf16 v[124:127], v[80:83], v[216:219], v[124:127]
	v_mfma_f32_16x16x32_bf16 v[124:127], v[84:87], v[220:223], v[124:127]
	v_mfma_f32_16x16x32_bf16 v[108:111], v[80:83], v[232:235], v[108:111]
	v_mfma_f32_16x16x32_bf16 v[108:111], v[84:87], v[236:239], v[108:111]
	v_mfma_f32_16x16x32_bf16 v[76:79], v[80:83], v[240:243], v[76:79]
	v_mfma_f32_16x16x32_bf16 v[76:79], v[84:87], v[244:247], v[76:79]
	v_mfma_f32_16x16x32_bf16 v[132:135], v[88:91], v[208:211], v[132:135]
	v_mfma_f32_16x16x32_bf16 v[132:135], v[92:95], v[212:215], v[132:135]
	v_mfma_f32_16x16x32_bf16 v[120:123], v[88:91], v[216:219], v[120:123]
	v_mfma_f32_16x16x32_bf16 v[120:123], v[92:95], v[220:223], v[120:123]
	v_mfma_f32_16x16x32_bf16 v[104:107], v[88:91], v[232:235], v[104:107]
	v_mfma_f32_16x16x32_bf16 v[104:107], v[92:95], v[236:239], v[104:107]
	v_mfma_f32_16x16x32_bf16 v[72:75], v[88:91], v[240:243], v[72:75]
	v_mfma_f32_16x16x32_bf16 v[72:75], v[92:95], v[244:247], v[72:75]
	s_setprio 0
	s_setprio 1
	v_mfma_f32_16x16x32_bf16 v[136:139], v[144:147], v[208:211], v[136:139]
	v_mfma_f32_16x16x32_bf16 v[136:139], v[148:151], v[212:215], v[136:139]
	v_mfma_f32_16x16x32_bf16 v[116:119], v[144:147], v[216:219], v[116:119]
	v_mfma_f32_16x16x32_bf16 v[116:119], v[148:151], v[220:223], v[116:119]
	v_mfma_f32_16x16x32_bf16 v[100:103], v[144:147], v[232:235], v[100:103]
	v_mfma_f32_16x16x32_bf16 v[100:103], v[148:151], v[236:239], v[100:103]
	v_mfma_f32_16x16x32_bf16 v[68:71], v[144:147], v[240:243], v[68:71]
	v_mfma_f32_16x16x32_bf16 v[68:71], v[148:151], v[244:247], v[68:71]
	v_mfma_f32_16x16x32_bf16 v[128:131], v[152:155], v[208:211], v[128:131]
	v_mfma_f32_16x16x32_bf16 v[128:131], v[156:159], v[212:215], v[128:131]
	v_mfma_f32_16x16x32_bf16 v[112:115], v[152:155], v[216:219], v[112:115]
	v_mfma_f32_16x16x32_bf16 v[112:115], v[156:159], v[220:223], v[112:115]
	v_mfma_f32_16x16x32_bf16 v[96:99], v[152:155], v[232:235], v[96:99]
	v_mfma_f32_16x16x32_bf16 v[96:99], v[156:159], v[236:239], v[96:99]
	v_mfma_f32_16x16x32_bf16 v[64:67], v[152:155], v[240:243], v[64:67]
	v_mfma_f32_16x16x32_bf16 v[64:67], v[156:159], v[244:247], v[64:67]
	s_barrier
	s_setprio 0
	s_add_u32 s98, s14, 0x80
	s_addc_u32 s99, s15, 0
	s_add_u32 s100, s16, 0x80
	s_addc_u32 s101, s17, 0
	s_add_i32 s49, s31, s18
	s_mov_b32 m0, s49
	ds_read_b128 v[208:211], v203 offset:16384
	ds_read_b128 v[212:215], v203 offset:17408
	ds_read_b128 v[216:219], v203 offset:18432
	ds_read_b128 v[220:223], v203 offset:19456
	ds_read_b128 v[232:235], v203 offset:20480
	ds_read_b128 v[236:239], v203 offset:21504
	ds_read_b128 v[240:243], v203 offset:22528
	ds_read_b128 v[244:247], v203 offset:23552
	global_load_lds_dwordx4 v166, s[14:15]
	s_add_i32 m0, s49, 0x2000
	s_add_u32 s50, s14, 0x80000
	s_addc_u32 s51, s15, 0
	s_add_i32 s49, s34, s18
	global_load_lds_dwordx4 v170, s[14:15]
	s_mov_b32 m0, s49
	s_nop 0
	global_load_lds_dwordx4 v166, s[50:51]
	s_add_i32 m0, s49, 0x2000
	s_nop 0
	global_load_lds_dwordx4 v170, s[50:51]
	s_mov_b32 m0, s19
	s_nop 0
	global_load_lds_dwordx4 v164, s[16:17]
	s_mov_b32 m0, s20
	s_nop 0
	global_load_lds_dwordx4 v168, s[16:17]
	s_waitcnt vmcnt(8)
	s_waitcnt lgkmcnt(0)
	s_setprio 1
	s_barrier
	v_mfma_f32_16x16x32_bf16 v[60:63], v[80:83], v[208:211], v[60:63]
	v_mfma_f32_16x16x32_bf16 v[60:63], v[84:87], v[212:215], v[60:63]
	v_mfma_f32_16x16x32_bf16 v[44:47], v[80:83], v[216:219], v[44:47]
	v_mfma_f32_16x16x32_bf16 v[44:47], v[84:87], v[220:223], v[44:47]
	v_mfma_f32_16x16x32_bf16 v[28:31], v[80:83], v[232:235], v[28:31]
	v_mfma_f32_16x16x32_bf16 v[28:31], v[84:87], v[236:239], v[28:31]
	v_mfma_f32_16x16x32_bf16 v[12:15], v[80:83], v[240:243], v[12:15]
	v_mfma_f32_16x16x32_bf16 v[12:15], v[84:87], v[244:247], v[12:15]
	v_mfma_f32_16x16x32_bf16 v[56:59], v[88:91], v[208:211], v[56:59]
	v_mfma_f32_16x16x32_bf16 v[56:59], v[92:95], v[212:215], v[56:59]
	v_mfma_f32_16x16x32_bf16 v[40:43], v[88:91], v[216:219], v[40:43]
	v_mfma_f32_16x16x32_bf16 v[40:43], v[92:95], v[220:223], v[40:43]
	v_mfma_f32_16x16x32_bf16 v[24:27], v[88:91], v[232:235], v[24:27]
	v_mfma_f32_16x16x32_bf16 v[24:27], v[92:95], v[236:239], v[24:27]
	v_mfma_f32_16x16x32_bf16 v[8:11], v[88:91], v[240:243], v[8:11]
	v_mfma_f32_16x16x32_bf16 v[8:11], v[92:95], v[244:247], v[8:11]
	s_setprio 0
	s_setprio 1
	v_mfma_f32_16x16x32_bf16 v[52:55], v[144:147], v[208:211], v[52:55]
	v_mfma_f32_16x16x32_bf16 v[52:55], v[148:151], v[212:215], v[52:55]
	v_mfma_f32_16x16x32_bf16 v[36:39], v[144:147], v[216:219], v[36:39]
	v_mfma_f32_16x16x32_bf16 v[36:39], v[148:151], v[220:223], v[36:39]
	v_mfma_f32_16x16x32_bf16 v[20:23], v[144:147], v[232:235], v[20:23]
	v_mfma_f32_16x16x32_bf16 v[20:23], v[148:151], v[236:239], v[20:23]
	v_mfma_f32_16x16x32_bf16 v[4:7], v[144:147], v[240:243], v[4:7]
	v_mfma_f32_16x16x32_bf16 v[4:7], v[148:151], v[244:247], v[4:7]
	v_mfma_f32_16x16x32_bf16 v[48:51], v[152:155], v[208:211], v[48:51]
	v_mfma_f32_16x16x32_bf16 v[48:51], v[156:159], v[212:215], v[48:51]
	v_mfma_f32_16x16x32_bf16 v[32:35], v[152:155], v[216:219], v[32:35]
	v_mfma_f32_16x16x32_bf16 v[32:35], v[156:159], v[220:223], v[32:35]
	v_mfma_f32_16x16x32_bf16 v[16:19], v[152:155], v[232:235], v[16:19]
	v_mfma_f32_16x16x32_bf16 v[16:19], v[156:159], v[236:239], v[16:19]
	v_mfma_f32_16x16x32_bf16 v[0:3], v[152:155], v[240:243], v[0:3]
	v_mfma_f32_16x16x32_bf16 v[0:3], v[156:159], v[244:247], v[0:3]
	s_barrier
; #define PG8_STAGE(bufoff, gbase, voff) do { _Pragma("unroll") for (int _i = 0; _i < 2; ++_i) \
;         __builtin_amdgcn_global_load_lds((const unsigned*)((const char*)(gbase) + (voff)[_i]), (PG8_LAS unsigned*)(lds + (bufoff) + ldsw + _i * 8192), 16, 0, 0); } while (0)
; #define PG8_LDA(dst, b, h) do { _Pragma("unroll") for (int m = 0; m < 4; ++m) _Pragma("unroll") for (int k = 0; k < 2; ++k) dst[m][k] = *(const PG8_LAS bf16x8*)(lds + PG8_SA(b, h) + aoff + m * 2048 + k * 1024); } while (0)
; #define PG8_LDB(dst, b, h) do { _Pragma("unroll") for (int n = 0; n < 2; ++n) _Pragma("unroll") for (int k = 0; k < 2; ++k) dst[n][k] = *(const PG8_LAS bf16x8*)(lds + PG8_SB(b, h) + boff + n * 2048 + k * 1024); } while (0)
; #define PG8_MMA(ai, bj, At, Bt) do { __builtin_amdgcn_s_setprio(1); _Pragma("unroll") for (int m = 0; m < 4; ++m) _Pragma("unroll") for (int n = 0; n < 2; ++n) _Pragma("unroll") for (int k = 0; k < 2; ++k) \
;         acc[ai][bj][m][n] = __builtin_amdgcn_mfma_f32_16x16x32_bf16(Bt[n][k], At[m][k], acc[ai][bj][m][n], 0, 0, 0); __builtin_amdgcn_s_setprio(0); } while (0)
; #define PG8_WAIT_V(n) asm volatile("s_waitcnt vmcnt(" #n ")" ::: "memory")
; #define PG8_WAIT_L(n) asm volatile("s_waitcnt lgkmcnt(" #n ")" ::: "memory")
; #define PG8_BAR __builtin_amdgcn_s_barrier()
; #define PG8_SCHED __builtin_amdgcn_sched_barrier(0)
; template <class Epi, class Sched, bool ALIGN_EPI = false, bool SP2 = false, bool DUAL = false>
; __device__ __forceinline__ void gemm_phase(PG8_LAS unsigned char* lds, const Gemm g, const Sched& S, const Epi& E) {
;     ...
;             PG8_LDB(B0, 1, 0); PG8_LDB(B1, 1, 1); PG8_SCHED; PG8_LDA(At, 1, 0); PG8_STAGE(PG8_SA(0, 1), a2 + hstep, voffA);
;             PG8_WAIT_V(8); PG8_WAIT_L(0); PG8_BAR; PG8_MMA(0, 0, At, B0); PG8_MMA(0, 1, At, B1); PG8_BAR; PG8_SCHED;
;             PG8_LDA(At, 1, 1); PG8_STAGE(PG8_SB(1, 0), b3, voffB); PG8_STAGE(PG8_SB(1, 1), b3 + hstep, voffB); PG8_STAGE(PG8_SA(1, 0), a3, voffA);
;             PG8_WAIT_V(8); PG8_WAIT_L(0); PG8_BAR; PG8_MMA(1, 0, At, B0); PG8_MMA(1, 1, At, B1); PG8_BAR; PG8_SCHED;
;     ...
;         if constexpr (ALIGN_EPI) { if (wr == 0) PG8_BAR; }
	s_setprio 0
	s_add_i32 s49, 0, 0x18000
	s_add_i32 s50, 0, 0x1c000
	v_add_u32_e32 v92, s49, v196
	v_add_u32_e32 v156, s50, v196
	ds_read_b128 v[80:83], v92
	ds_read_b128 v[84:87], v92 offset:1024
	ds_read_b128 v[88:91], v92 offset:2048
	ds_read_b128 v[92:95], v92 offset:3072
	ds_read_b128 v[144:147], v156
	ds_read_b128 v[148:151], v156 offset:1024
	ds_read_b128 v[152:155], v156 offset:2048
	ds_read_b128 v[156:159], v156 offset:3072
	s_add_u32 s16, s16, 0x80000
	s_addc_u32 s17, s17, 0
	s_mov_b32 m0, s21
	ds_read_b128 v[208:211], v203 offset:32768
	ds_read_b128 v[212:215], v203 offset:33792
	ds_read_b128 v[216:219], v203 offset:34816
	ds_read_b128 v[220:223], v203 offset:35840
	ds_read_b128 v[232:235], v203 offset:36864
	ds_read_b128 v[236:239], v203 offset:37888
	ds_read_b128 v[240:243], v203 offset:38912
	ds_read_b128 v[244:247], v203 offset:39936
	global_load_lds_dwordx4 v164, s[16:17]
	s_mov_b32 m0, s22
	s_nop 0
	global_load_lds_dwordx4 v168, s[16:17]
	s_waitcnt vmcnt(8)
	s_waitcnt lgkmcnt(0)
	s_setprio 1
	s_barrier
	v_mfma_f32_16x16x32_bf16 v[140:143], v[80:83], v[208:211], v[140:143]
	v_mfma_f32_16x16x32_bf16 v[140:143], v[84:87], v[212:215], v[140:143]
	v_mfma_f32_16x16x32_bf16 v[124:127], v[80:83], v[216:219], v[124:127]
	v_mfma_f32_16x16x32_bf16 v[124:127], v[84:87], v[220:223], v[124:127]
	v_mfma_f32_16x16x32_bf16 v[108:111], v[80:83], v[232:235], v[108:111]
	v_mfma_f32_16x16x32_bf16 v[108:111], v[84:87], v[236:239], v[108:111]
	v_mfma_f32_16x16x32_bf16 v[76:79], v[80:83], v[240:243], v[76:79]
	v_mfma_f32_16x16x32_bf16 v[76:79], v[84:87], v[244:247], v[76:79]
	v_mfma_f32_16x16x32_bf16 v[132:135], v[88:91], v[208:211], v[132:135]
	v_mfma_f32_16x16x32_bf16 v[132:135], v[92:95], v[212:215], v[132:135]
	v_mfma_f32_16x16x32_bf16 v[120:123], v[88:91], v[216:219], v[120:123]
	v_mfma_f32_16x16x32_bf16 v[120:123], v[92:95], v[220:223], v[120:123]
	v_mfma_f32_16x16x32_bf16 v[104:107], v[88:91], v[232:235], v[104:107]
	v_mfma_f32_16x16x32_bf16 v[104:107], v[92:95], v[236:239], v[104:107]
	v_mfma_f32_16x16x32_bf16 v[72:75], v[88:91], v[240:243], v[72:75]
	v_mfma_f32_16x16x32_bf16 v[72:75], v[92:95], v[244:247], v[72:75]
	s_setprio 0
	s_setprio 1
	v_mfma_f32_16x16x32_bf16 v[136:139], v[144:147], v[208:211], v[136:139]
	v_mfma_f32_16x16x32_bf16 v[136:139], v[148:151], v[212:215], v[136:139]
	v_mfma_f32_16x16x32_bf16 v[116:119], v[144:147], v[216:219], v[116:119]
	v_mfma_f32_16x16x32_bf16 v[116:119], v[148:151], v[220:223], v[116:119]
	v_mfma_f32_16x16x32_bf16 v[100:103], v[144:147], v[232:235], v[100:103]
	v_mfma_f32_16x16x32_bf16 v[100:103], v[148:151], v[236:239], v[100:103]
	v_mfma_f32_16x16x32_bf16 v[68:71], v[144:147], v[240:243], v[68:71]
	v_mfma_f32_16x16x32_bf16 v[68:71], v[148:151], v[244:247], v[68:71]
	v_mfma_f32_16x16x32_bf16 v[128:131], v[152:155], v[208:211], v[128:131]
	v_mfma_f32_16x16x32_bf16 v[128:131], v[156:159], v[212:215], v[128:131]
	v_mfma_f32_16x16x32_bf16 v[112:115], v[152:155], v[216:219], v[112:115]
	v_mfma_f32_16x16x32_bf16 v[112:115], v[156:159], v[220:223], v[112:115]
	v_mfma_f32_16x16x32_bf16 v[96:99], v[152:155], v[232:235], v[96:99]
	v_mfma_f32_16x16x32_bf16 v[96:99], v[156:159], v[236:239], v[96:99]
	v_mfma_f32_16x16x32_bf16 v[64:67], v[152:155], v[240:243], v[64:67]
	v_mfma_f32_16x16x32_bf16 v[64:67], v[156:159], v[244:247], v[64:67]
	s_barrier
	s_setprio 0
	s_add_i32 s16, s49, s18
	s_mov_b32 m0, s16
	ds_read_b128 v[208:211], v203 offset:49152
	ds_read_b128 v[212:215], v203 offset:50176
	ds_read_b128 v[216:219], v203 offset:51200
	ds_read_b128 v[220:223], v203 offset:52224
	ds_read_b128 v[232:235], v203 offset:53248
	ds_read_b128 v[236:239], v203 offset:54272
	ds_read_b128 v[240:243], v203 offset:55296
	ds_read_b128 v[244:247], v203 offset:56320
	global_load_lds_dwordx4 v166, s[98:99]
	s_add_i32 m0, s16, 0x2000
	s_add_u32 s14, s14, 0x80080
	s_addc_u32 s15, s15, 0
	s_add_i32 s16, s50, s18
	global_load_lds_dwordx4 v170, s[98:99]
	s_mov_b32 m0, s16
	s_nop 0
	global_load_lds_dwordx4 v166, s[14:15]
	s_add_i32 m0, s16, 0x2000
	s_nop 0
	global_load_lds_dwordx4 v170, s[14:15]
	s_mov_b32 m0, s27
	s_nop 0
	global_load_lds_dwordx4 v164, s[100:101]
	s_mov_b32 m0, s28
	s_nop 0
	global_load_lds_dwordx4 v168, s[100:101]
	s_waitcnt vmcnt(8)
	s_waitcnt lgkmcnt(0)
	s_setprio 1
	s_barrier
	v_mfma_f32_16x16x32_bf16 v[60:63], v[80:83], v[208:211], v[60:63]
	v_mfma_f32_16x16x32_bf16 v[60:63], v[84:87], v[212:215], v[60:63]
	v_mfma_f32_16x16x32_bf16 v[44:47], v[80:83], v[216:219], v[44:47]
	v_mfma_f32_16x16x32_bf16 v[44:47], v[84:87], v[220:223], v[44:47]
	v_mfma_f32_16x16x32_bf16 v[28:31], v[80:83], v[232:235], v[28:31]
	v_mfma_f32_16x16x32_bf16 v[28:31], v[84:87], v[236:239], v[28:31]
	v_mfma_f32_16x16x32_bf16 v[12:15], v[80:83], v[240:243], v[12:15]
	v_mfma_f32_16x16x32_bf16 v[12:15], v[84:87], v[244:247], v[12:15]
	v_mfma_f32_16x16x32_bf16 v[56:59], v[88:91], v[208:211], v[56:59]
	v_mfma_f32_16x16x32_bf16 v[56:59], v[92:95], v[212:215], v[56:59]
	v_mfma_f32_16x16x32_bf16 v[40:43], v[88:91], v[216:219], v[40:43]
	v_mfma_f32_16x16x32_bf16 v[40:43], v[92:95], v[220:223], v[40:43]
	v_mfma_f32_16x16x32_bf16 v[24:27], v[88:91], v[232:235], v[24:27]
	v_mfma_f32_16x16x32_bf16 v[24:27], v[92:95], v[236:239], v[24:27]
	v_mfma_f32_16x16x32_bf16 v[8:11], v[88:91], v[240:243], v[8:11]
	v_mfma_f32_16x16x32_bf16 v[8:11], v[92:95], v[244:247], v[8:11]
	s_setprio 0
	s_setprio 1
	v_mfma_f32_16x16x32_bf16 v[52:55], v[144:147], v[208:211], v[52:55]
	v_mfma_f32_16x16x32_bf16 v[52:55], v[148:151], v[212:215], v[52:55]
	v_mfma_f32_16x16x32_bf16 v[36:39], v[144:147], v[216:219], v[36:39]
	v_mfma_f32_16x16x32_bf16 v[36:39], v[148:151], v[220:223], v[36:39]
	v_mfma_f32_16x16x32_bf16 v[20:23], v[144:147], v[232:235], v[20:23]
	v_mfma_f32_16x16x32_bf16 v[20:23], v[148:151], v[236:239], v[20:23]
	v_mfma_f32_16x16x32_bf16 v[4:7], v[144:147], v[240:243], v[4:7]
	v_mfma_f32_16x16x32_bf16 v[4:7], v[148:151], v[244:247], v[4:7]
	v_mfma_f32_16x16x32_bf16 v[48:51], v[152:155], v[208:211], v[48:51]
	v_mfma_f32_16x16x32_bf16 v[48:51], v[156:159], v[212:215], v[48:51]
	v_mfma_f32_16x16x32_bf16 v[32:35], v[152:155], v[216:219], v[32:35]
	v_mfma_f32_16x16x32_bf16 v[32:35], v[156:159], v[220:223], v[32:35]
	v_mfma_f32_16x16x32_bf16 v[16:19], v[152:155], v[232:235], v[16:19]
	v_mfma_f32_16x16x32_bf16 v[16:19], v[156:159], v[236:239], v[16:19]
	v_mfma_f32_16x16x32_bf16 v[0:3], v[152:155], v[240:243], v[0:3]
	v_mfma_f32_16x16x32_bf16 v[0:3], v[156:159], v[244:247], v[0:3]
	s_barrier
	s_setprio 0
	s_add_i32 s48, s48, 2
	s_add_u32 s10, s10, 0x100
	s_addc_u32 s11, s11, 0
	s_add_u32 s46, s46, 0x100
	s_addc_u32 s47, s47, 0
	s_cmp_gt_u32 s48, 29
	s_cbranch_scc0 .LBB0_252
	s_and_b64 vcc, exec, s[38:39]
	s_cbranch_vccz .LBB0_255
	s_barrier

; #define PG8_STAGE(bufoff, gbase, voff) do { _Pragma("unroll") for (int _i = 0; _i < 2; ++_i) \
;         __builtin_amdgcn_global_load_lds((const unsigned*)((const char*)(gbase) + (voff)[_i]), (PG8_LAS unsigned*)(lds + (bufoff) + ldsw + _i * 8192), 16, 0, 0); } while (0)
; #define PG8_LDA(dst, b, h) do { _Pragma("unroll") for (int m = 0; m < 4; ++m) _Pragma("unroll") for (int k = 0; k < 2; ++k) dst[m][k] = *(const PG8_LAS bf16x8*)(lds + PG8_SA(b, h) + aoff + m * 2048 + k * 1024); } while (0)
; #define PG8_LDB(dst, b, h) do { _Pragma("unroll") for (int n = 0; n < 2; ++n) _Pragma("unroll") for (int k = 0; k < 2; ++k) dst[n][k] = *(const PG8_LAS bf16x8*)(lds + PG8_SB(b, h) + boff + n * 2048 + k * 1024); } while (0)
; #define PG8_MMA(ai, bj, At, Bt) do { __builtin_amdgcn_s_setprio(1); _Pragma("unroll") for (int m = 0; m < 4; ++m) _Pragma("unroll") for (int n = 0; n < 2; ++n) _Pragma("unroll") for (int k = 0; k < 2; ++k) \
;         acc[ai][bj][m][n] = __builtin_amdgcn_mfma_f32_16x16x32_bf16(Bt[n][k], At[m][k], acc[ai][bj][m][n], 0, 0, 0); __builtin_amdgcn_s_setprio(0); } while (0)
; #define PG8_WAIT_V(n) asm volatile("s_waitcnt vmcnt(" #n ")" ::: "memory")
; #define PG8_BAR __builtin_amdgcn_s_barrier()
; template <class Epi, class Sched, bool ALIGN_EPI = false, bool SP2 = false, bool DUAL = false>
; __device__ __forceinline__ void gemm_phase(PG8_LAS unsigned char* lds, const Gemm g, const Sched& S, const Epi& E) {
;     ...
;         for (int t = 0; t < nt; t += 2) {
;             const bool last = (t == nt - 2);
;             const char* a1 = cA + (size_t)(t + 1) * kstep;
;             const char* a2 = last ? nA : cA + (size_t)(t + 2) * kstep; const char* b2 = last ? nB : cB + (size_t)(t + 2) * kstep;
;             const char* a3 = a2 + kstep; const char* b3 = b2 + kstep;
;             if (last && has_next) S.a_ready(nxt);
;             if constexpr (SP2) {
;             PG8_LDB(B0, 0, 0); PG8_LDB(B1, 0, 1); PG8_SCHED; PG8_LDA(At, 0, 0); PG8_STAGE(PG8_SA(1, 1), a1 + hstep, voffA);
;             PG8_WAIT_V(8); PG8_WAIT_L(0); PG8_BAR; PG8_MMA(0, 0, At, B0); PG8_MMA(0, 1, At, B1); PG8_BAR; PG8_SCHED;
;             PG8_LDA(At, 0, 1); PG8_STAGE(PG8_SB(0, 0), b2, voffB); PG8_STAGE(PG8_SB(0, 1), b2 + hstep, voffB); PG8_STAGE(PG8_SA(0, 0), a2, voffA);
;             PG8_WAIT_V(8); PG8_WAIT_L(0); PG8_BAR; PG8_MMA(1, 0, At, B0); PG8_MMA(1, 1, At, B1); PG8_BAR; PG8_SCHED;
.LBB0_805:
	v_add_u32_e32 v1, s44, v235
	ds_read_b128 v[132:135], v1
	ds_read_b128 v[136:139], v1 offset:1024
	ds_read_b128 v[140:143], v1 offset:2048
	ds_read_b128 v[144:147], v1 offset:3072
	v_add_u32_e32 v1, s45, v235
	ds_read_b128 v[148:151], v1
	ds_read_b128 v[152:155], v1 offset:1024
	ds_read_b128 v[156:159], v1 offset:2048
	ds_read_b128 v[160:163], v1 offset:3072
	s_add_u32 s16, s14, 0xfff80080
	s_addc_u32 s17, s15, -1
	s_cmp_eq_u32 s75, 28
	s_cselect_b32 s19, s50, s17
	s_cselect_b32 s18, s51, s16
	s_cselect_b32 s17, s65, s73
	s_cselect_b32 s16, s67, s72
	s_add_i32 m0, s28, 0xc000
	ds_read_b128 v[164:167], v237
	ds_read_b128 v[168:171], v237 offset:1024
	ds_read_b128 v[172:175], v237 offset:2048
	ds_read_b128 v[176:179], v237 offset:3072
	ds_read_b128 v[180:183], v237 offset:4096
	ds_read_b128 v[202:205], v237 offset:5120
	ds_read_b128 v[206:209], v237 offset:6144
	ds_read_b128 v[210:213], v237 offset:7168
	global_load_lds_dwordx4 v192, s[14:15]
	s_add_i32 m0, s28, 0xe000
	s_nop 0
	global_load_lds_dwordx4 v194, s[14:15]
	s_waitcnt vmcnt(8)
	s_waitcnt lgkmcnt(0)
	s_setprio 1
	s_barrier
	v_mfma_f32_16x16x32_bf16 v[128:131], v[132:135], v[164:167], v[128:131]
	v_mfma_f32_16x16x32_bf16 v[128:131], v[136:139], v[168:171], v[128:131]
	v_mfma_f32_16x16x32_bf16 v[120:123], v[132:135], v[172:175], v[120:123]
	v_mfma_f32_16x16x32_bf16 v[120:123], v[136:139], v[176:179], v[120:123]
	v_mfma_f32_16x16x32_bf16 v[112:115], v[132:135], v[180:183], v[112:115]
	v_mfma_f32_16x16x32_bf16 v[112:115], v[136:139], v[202:205], v[112:115]
	v_mfma_f32_16x16x32_bf16 v[104:107], v[132:135], v[206:209], v[104:107]
	v_mfma_f32_16x16x32_bf16 v[104:107], v[136:139], v[210:213], v[104:107]
	v_mfma_f32_16x16x32_bf16 v[124:127], v[140:143], v[164:167], v[124:127]
	v_mfma_f32_16x16x32_bf16 v[124:127], v[144:147], v[168:171], v[124:127]
	v_mfma_f32_16x16x32_bf16 v[116:119], v[140:143], v[172:175], v[116:119]
	v_mfma_f32_16x16x32_bf16 v[116:119], v[144:147], v[176:179], v[116:119]
	v_mfma_f32_16x16x32_bf16 v[108:111], v[140:143], v[180:183], v[108:111]
	v_mfma_f32_16x16x32_bf16 v[108:111], v[144:147], v[202:205], v[108:111]
	v_mfma_f32_16x16x32_bf16 v[100:103], v[140:143], v[206:209], v[100:103]
	v_mfma_f32_16x16x32_bf16 v[100:103], v[144:147], v[210:213], v[100:103]
	s_setprio 0
	s_setprio 1
	v_mfma_f32_16x16x32_bf16 v[96:99], v[148:151], v[164:167], v[96:99]
	v_mfma_f32_16x16x32_bf16 v[96:99], v[152:155], v[168:171], v[96:99]
	v_mfma_f32_16x16x32_bf16 v[88:91], v[148:151], v[172:175], v[88:91]
	v_mfma_f32_16x16x32_bf16 v[88:91], v[152:155], v[176:179], v[88:91]
	v_mfma_f32_16x16x32_bf16 v[80:83], v[148:151], v[180:183], v[80:83]
	v_mfma_f32_16x16x32_bf16 v[80:83], v[152:155], v[202:205], v[80:83]
	v_mfma_f32_16x16x32_bf16 v[72:75], v[148:151], v[206:209], v[72:75]
	v_mfma_f32_16x16x32_bf16 v[72:75], v[152:155], v[210:213], v[72:75]
	v_mfma_f32_16x16x32_bf16 v[92:95], v[156:159], v[164:167], v[92:95]
	v_mfma_f32_16x16x32_bf16 v[92:95], v[160:163], v[168:171], v[92:95]
	v_mfma_f32_16x16x32_bf16 v[84:87], v[156:159], v[172:175], v[84:87]
	v_mfma_f32_16x16x32_bf16 v[84:87], v[160:163], v[176:179], v[84:87]
	v_mfma_f32_16x16x32_bf16 v[76:79], v[156:159], v[180:183], v[76:79]
	v_mfma_f32_16x16x32_bf16 v[76:79], v[160:163], v[202:205], v[76:79]
	v_mfma_f32_16x16x32_bf16 v[68:71], v[156:159], v[206:209], v[68:71]
	v_mfma_f32_16x16x32_bf16 v[68:71], v[160:163], v[210:213], v[68:71]
	s_barrier
	s_setprio 0
	s_add_u32 s98, s16, 0x80
	s_addc_u32 s99, s17, 0
	s_add_u32 s100, s18, 0x80
	s_addc_u32 s101, s19, 0
	s_add_i32 s76, s44, s27
	s_mov_b32 m0, s76
	ds_read_b128 v[164:167], v237 offset:16384
	ds_read_b128 v[168:171], v237 offset:17408
	ds_read_b128 v[172:175], v237 offset:18432
	ds_read_b128 v[176:179], v237 offset:19456
	ds_read_b128 v[180:183], v237 offset:20480
	ds_read_b128 v[202:205], v237 offset:21504
	ds_read_b128 v[206:209], v237 offset:22528
	ds_read_b128 v[210:213], v237 offset:23552
	global_load_lds_dwordx4 v186, s[16:17]
	s_add_i32 m0, s76, 0x2000
	s_add_u32 s76, s16, 0x80000
	s_addc_u32 s77, s17, 0
	s_add_i32 s78, s45, s27
	global_load_lds_dwordx4 v190, s[16:17]
	s_mov_b32 m0, s78
	s_nop 0
	global_load_lds_dwordx4 v186, s[76:77]
	v_lshl_add_u64 v[2:3], s[76:77], 0, v[190:191]
	s_add_i32 m0, s78, 0x2000
	s_nop 0
	global_load_lds_dwordx4 v[2:3], off
	s_mov_b32 m0, s28
	s_nop 0
	global_load_lds_dwordx4 v184, s[18:19]
	s_mov_b32 m0, s29
	s_nop 0
	global_load_lds_dwordx4 v188, s[18:19]
	s_waitcnt vmcnt(8)
	s_waitcnt lgkmcnt(0)
	s_setprio 1
	s_barrier
	v_mfma_f32_16x16x32_bf16 v[64:67], v[132:135], v[164:167], v[64:67]
	v_mfma_f32_16x16x32_bf16 v[64:67], v[136:139], v[168:171], v[64:67]
	v_mfma_f32_16x16x32_bf16 v[56:59], v[132:135], v[172:175], v[56:59]
	v_mfma_f32_16x16x32_bf16 v[56:59], v[136:139], v[176:179], v[56:59]
	v_mfma_f32_16x16x32_bf16 v[48:51], v[132:135], v[180:183], v[48:51]
	v_mfma_f32_16x16x32_bf16 v[48:51], v[136:139], v[202:205], v[48:51]
	v_mfma_f32_16x16x32_bf16 v[40:43], v[132:135], v[206:209], v[40:43]
	v_mfma_f32_16x16x32_bf16 v[40:43], v[136:139], v[210:213], v[40:43]
	v_mfma_f32_16x16x32_bf16 v[60:63], v[140:143], v[164:167], v[60:63]
	v_mfma_f32_16x16x32_bf16 v[60:63], v[144:147], v[168:171], v[60:63]
	v_mfma_f32_16x16x32_bf16 v[52:55], v[140:143], v[172:175], v[52:55]
	v_mfma_f32_16x16x32_bf16 v[52:55], v[144:147], v[176:179], v[52:55]
	v_mfma_f32_16x16x32_bf16 v[44:47], v[140:143], v[180:183], v[44:47]
	v_mfma_f32_16x16x32_bf16 v[44:47], v[144:147], v[202:205], v[44:47]
	v_mfma_f32_16x16x32_bf16 v[36:39], v[140:143], v[206:209], v[36:39]
	v_mfma_f32_16x16x32_bf16 v[36:39], v[144:147], v[210:213], v[36:39]
	s_setprio 0
	s_setprio 1
	v_mfma_f32_16x16x32_bf16 v[32:35], v[148:151], v[164:167], v[32:35]
	v_mfma_f32_16x16x32_bf16 v[32:35], v[152:155], v[168:171], v[32:35]
	v_mfma_f32_16x16x32_bf16 v[24:27], v[148:151], v[172:175], v[24:27]
	v_mfma_f32_16x16x32_bf16 v[24:27], v[152:155], v[176:179], v[24:27]
	v_mfma_f32_16x16x32_bf16 v[16:19], v[148:151], v[180:183], v[16:19]
	v_mfma_f32_16x16x32_bf16 v[16:19], v[152:155], v[202:205], v[16:19]
	v_mfma_f32_16x16x32_bf16 v[8:11], v[148:151], v[206:209], v[8:11]
	v_mfma_f32_16x16x32_bf16 v[8:11], v[152:155], v[210:213], v[8:11]
	v_mfma_f32_16x16x32_bf16 v[28:31], v[156:159], v[164:167], v[28:31]
	v_mfma_f32_16x16x32_bf16 v[28:31], v[160:163], v[168:171], v[28:31]
	v_mfma_f32_16x16x32_bf16 v[20:23], v[156:159], v[172:175], v[20:23]
	v_mfma_f32_16x16x32_bf16 v[20:23], v[160:163], v[176:179], v[20:23]
	v_mfma_f32_16x16x32_bf16 v[12:15], v[156:159], v[180:183], v[12:15]
	v_mfma_f32_16x16x32_bf16 v[12:15], v[160:163], v[202:205], v[12:15]
	v_mfma_f32_16x16x32_bf16 v[2:5], v[156:159], v[206:209], v[4:7]
	v_mfma_f32_16x16x32_bf16 v[2:5], v[160:163], v[210:213], v[2:5]
	s_barrier
; #define PG8_STAGE(bufoff, gbase, voff) do { _Pragma("unroll") for (int _i = 0; _i < 2; ++_i) \
;         __builtin_amdgcn_global_load_lds((const unsigned*)((const char*)(gbase) + (voff)[_i]), (PG8_LAS unsigned*)(lds + (bufoff) + ldsw + _i * 8192), 16, 0, 0); } while (0)
; #define PG8_LDA(dst, b, h) do { _Pragma("unroll") for (int m = 0; m < 4; ++m) _Pragma("unroll") for (int k = 0; k < 2; ++k) dst[m][k] = *(const PG8_LAS bf16x8*)(lds + PG8_SA(b, h) + aoff + m * 2048 + k * 1024); } while (0)
; #define PG8_LDB(dst, b, h) do { _Pragma("unroll") for (int n = 0; n < 2; ++n) _Pragma("unroll") for (int k = 0; k < 2; ++k) dst[n][k] = *(const PG8_LAS bf16x8*)(lds + PG8_SB(b, h) + boff + n * 2048 + k * 1024); } while (0)
; #define PG8_MMA(ai, bj, At, Bt) do { __builtin_amdgcn_s_setprio(1); _Pragma("unroll") for (int m = 0; m < 4; ++m) _Pragma("unroll") for (int n = 0; n < 2; ++n) _Pragma("unroll") for (int k = 0; k < 2; ++k) \
;         acc[ai][bj][m][n] = __builtin_amdgcn_mfma_f32_16x16x32_bf16(Bt[n][k], At[m][k], acc[ai][bj][m][n], 0, 0, 0); __builtin_amdgcn_s_setprio(0); } while (0)
; #define PG8_WAIT_V(n) asm volatile("s_waitcnt vmcnt(" #n ")" ::: "memory")
; #define PG8_WAIT_L(n) asm volatile("s_waitcnt lgkmcnt(" #n ")" ::: "memory")
; #define PG8_BAR __builtin_amdgcn_s_barrier()
; #define PG8_SCHED __builtin_amdgcn_sched_barrier(0)
; template <class Epi, class Sched, bool ALIGN_EPI = false, bool SP2 = false, bool DUAL = false>
; __device__ __forceinline__ void gemm_phase(PG8_LAS unsigned char* lds, const Gemm g, const Sched& S, const Epi& E) {
;     ...
;             PG8_LDB(B0, 1, 0); PG8_LDB(B1, 1, 1); PG8_SCHED; PG8_LDA(At, 1, 0); PG8_STAGE(PG8_SA(0, 1), a2 + hstep, voffA);
;             PG8_WAIT_V(8); PG8_WAIT_L(0); PG8_BAR; PG8_MMA(0, 0, At, B0); PG8_MMA(0, 1, At, B1); PG8_BAR; PG8_SCHED;
;             PG8_LDA(At, 1, 1); PG8_STAGE(PG8_SB(1, 0), b3, voffB); PG8_STAGE(PG8_SB(1, 1), b3 + hstep, voffB); PG8_STAGE(PG8_SA(1, 0), a3, voffA);
;             PG8_WAIT_V(8); PG8_WAIT_L(0); PG8_BAR; PG8_MMA(1, 0, At, B0); PG8_MMA(1, 1, At, B1); PG8_BAR; PG8_SCHED;
;     ...
;         if constexpr (ALIGN_EPI) { if (wr == 0) PG8_BAR; }
	s_setprio 0
	s_add_i32 s76, 0, 0x18000
	v_add_u32_e32 v1, s76, v235
	s_add_i32 s77, 0, 0x1c000
	ds_read_b128 v[132:135], v1
	ds_read_b128 v[136:139], v1 offset:1024
	ds_read_b128 v[140:143], v1 offset:2048
	ds_read_b128 v[144:147], v1 offset:3072
	v_add_u32_e32 v1, s77, v235
	ds_read_b128 v[148:151], v1
	ds_read_b128 v[152:155], v1 offset:1024
	ds_read_b128 v[156:159], v1 offset:2048
	ds_read_b128 v[160:163], v1 offset:3072
	s_add_u32 s18, s18, 0x80000
	s_addc_u32 s19, s19, 0
	s_mov_b32 m0, s34
	ds_read_b128 v[164:167], v237 offset:32768
	ds_read_b128 v[168:171], v237 offset:33792
	ds_read_b128 v[172:175], v237 offset:34816
	ds_read_b128 v[176:179], v237 offset:35840
	ds_read_b128 v[180:183], v237 offset:36864
	ds_read_b128 v[202:205], v237 offset:37888
	ds_read_b128 v[206:209], v237 offset:38912
	ds_read_b128 v[210:213], v237 offset:39936
	global_load_lds_dwordx4 v184, s[18:19]
	s_mov_b32 m0, s35
	s_nop 0
	global_load_lds_dwordx4 v188, s[18:19]
	s_waitcnt vmcnt(8)
	s_waitcnt lgkmcnt(0)
	s_setprio 1
	s_barrier
	v_mfma_f32_16x16x32_bf16 v[128:131], v[132:135], v[164:167], v[128:131]
	v_mfma_f32_16x16x32_bf16 v[128:131], v[136:139], v[168:171], v[128:131]
	v_mfma_f32_16x16x32_bf16 v[120:123], v[132:135], v[172:175], v[120:123]
	v_mfma_f32_16x16x32_bf16 v[120:123], v[136:139], v[176:179], v[120:123]
	v_mfma_f32_16x16x32_bf16 v[112:115], v[132:135], v[180:183], v[112:115]
	v_mfma_f32_16x16x32_bf16 v[112:115], v[136:139], v[202:205], v[112:115]
	v_mfma_f32_16x16x32_bf16 v[104:107], v[132:135], v[206:209], v[104:107]
	v_mfma_f32_16x16x32_bf16 v[104:107], v[136:139], v[210:213], v[104:107]
	v_mfma_f32_16x16x32_bf16 v[124:127], v[140:143], v[164:167], v[124:127]
	v_mfma_f32_16x16x32_bf16 v[124:127], v[144:147], v[168:171], v[124:127]
	v_mfma_f32_16x16x32_bf16 v[116:119], v[140:143], v[172:175], v[116:119]
	v_mfma_f32_16x16x32_bf16 v[116:119], v[144:147], v[176:179], v[116:119]
	v_mfma_f32_16x16x32_bf16 v[108:111], v[140:143], v[180:183], v[108:111]
	v_mfma_f32_16x16x32_bf16 v[108:111], v[144:147], v[202:205], v[108:111]
	v_mfma_f32_16x16x32_bf16 v[100:103], v[140:143], v[206:209], v[100:103]
	v_mfma_f32_16x16x32_bf16 v[100:103], v[144:147], v[210:213], v[100:103]
	s_setprio 0
	s_setprio 1
	v_mfma_f32_16x16x32_bf16 v[96:99], v[148:151], v[164:167], v[96:99]
	v_mfma_f32_16x16x32_bf16 v[96:99], v[152:155], v[168:171], v[96:99]
	v_mfma_f32_16x16x32_bf16 v[88:91], v[148:151], v[172:175], v[88:91]
	v_mfma_f32_16x16x32_bf16 v[88:91], v[152:155], v[176:179], v[88:91]
	v_mfma_f32_16x16x32_bf16 v[80:83], v[148:151], v[180:183], v[80:83]
	v_mfma_f32_16x16x32_bf16 v[80:83], v[152:155], v[202:205], v[80:83]
	v_mfma_f32_16x16x32_bf16 v[72:75], v[148:151], v[206:209], v[72:75]
	v_mfma_f32_16x16x32_bf16 v[72:75], v[152:155], v[210:213], v[72:75]
	v_mfma_f32_16x16x32_bf16 v[92:95], v[156:159], v[164:167], v[92:95]
	v_mfma_f32_16x16x32_bf16 v[92:95], v[160:163], v[168:171], v[92:95]
	v_mfma_f32_16x16x32_bf16 v[84:87], v[156:159], v[172:175], v[84:87]
	v_mfma_f32_16x16x32_bf16 v[84:87], v[160:163], v[176:179], v[84:87]
	v_mfma_f32_16x16x32_bf16 v[76:79], v[156:159], v[180:183], v[76:79]
	v_mfma_f32_16x16x32_bf16 v[76:79], v[160:163], v[202:205], v[76:79]
	v_mfma_f32_16x16x32_bf16 v[68:71], v[156:159], v[206:209], v[68:71]
	v_mfma_f32_16x16x32_bf16 v[68:71], v[160:163], v[210:213], v[68:71]
	s_barrier
	s_setprio 0
	s_add_i32 s18, s76, s27
	s_mov_b32 m0, s18
	ds_read_b128 v[164:167], v237 offset:49152
	ds_read_b128 v[168:171], v237 offset:50176
	ds_read_b128 v[172:175], v237 offset:51200
	ds_read_b128 v[176:179], v237 offset:52224
	ds_read_b128 v[180:183], v237 offset:53248
	ds_read_b128 v[202:205], v237 offset:54272
	ds_read_b128 v[206:209], v237 offset:55296
	ds_read_b128 v[210:213], v237 offset:56320
	global_load_lds_dwordx4 v186, s[98:99]
	s_add_i32 m0, s18, 0x2000
	s_add_u32 s16, s16, 0x80080
	s_addc_u32 s17, s17, 0
	s_add_i32 s18, s77, s27
	global_load_lds_dwordx4 v190, s[98:99]
	s_mov_b32 m0, s18
	s_nop 0
	global_load_lds_dwordx4 v186, s[16:17]
	s_add_i32 m0, s18, 0x2000
	s_nop 0
	global_load_lds_dwordx4 v190, s[16:17]
	s_mov_b32 m0, s42
	s_nop 0
	global_load_lds_dwordx4 v184, s[100:101]
	s_mov_b32 m0, s43
	s_nop 0
	global_load_lds_dwordx4 v188, s[100:101]
	s_waitcnt vmcnt(8)
	s_waitcnt lgkmcnt(0)
	s_setprio 1
	s_barrier
	v_mfma_f32_16x16x32_bf16 v[64:67], v[132:135], v[164:167], v[64:67]
	v_mfma_f32_16x16x32_bf16 v[64:67], v[136:139], v[168:171], v[64:67]
	v_mfma_f32_16x16x32_bf16 v[56:59], v[132:135], v[172:175], v[56:59]
	v_mfma_f32_16x16x32_bf16 v[56:59], v[136:139], v[176:179], v[56:59]
	v_mfma_f32_16x16x32_bf16 v[48:51], v[132:135], v[180:183], v[48:51]
	v_mfma_f32_16x16x32_bf16 v[48:51], v[136:139], v[202:205], v[48:51]
	v_mfma_f32_16x16x32_bf16 v[40:43], v[132:135], v[206:209], v[40:43]
	v_mfma_f32_16x16x32_bf16 v[40:43], v[136:139], v[210:213], v[40:43]
	v_mfma_f32_16x16x32_bf16 v[60:63], v[140:143], v[164:167], v[60:63]
	v_mfma_f32_16x16x32_bf16 v[60:63], v[144:147], v[168:171], v[60:63]
	v_mfma_f32_16x16x32_bf16 v[52:55], v[140:143], v[172:175], v[52:55]
	v_mfma_f32_16x16x32_bf16 v[52:55], v[144:147], v[176:179], v[52:55]
	v_mfma_f32_16x16x32_bf16 v[44:47], v[140:143], v[180:183], v[44:47]
	v_mfma_f32_16x16x32_bf16 v[44:47], v[144:147], v[202:205], v[44:47]
	v_mfma_f32_16x16x32_bf16 v[36:39], v[140:143], v[206:209], v[36:39]
	v_mfma_f32_16x16x32_bf16 v[36:39], v[144:147], v[210:213], v[36:39]
	s_setprio 0
	s_setprio 1
	v_mfma_f32_16x16x32_bf16 v[32:35], v[148:151], v[164:167], v[32:35]
	v_mfma_f32_16x16x32_bf16 v[28:31], v[156:159], v[164:167], v[28:31]
	v_mfma_f32_16x16x32_bf16 v[24:27], v[148:151], v[172:175], v[24:27]
	v_mfma_f32_16x16x32_bf16 v[20:23], v[156:159], v[172:175], v[20:23]
	v_mfma_f32_16x16x32_bf16 v[16:19], v[148:151], v[180:183], v[16:19]
	v_mfma_f32_16x16x32_bf16 v[12:15], v[156:159], v[180:183], v[12:15]
	v_mfma_f32_16x16x32_bf16 v[6:9], v[148:151], v[206:209], v[8:11]
	v_mfma_f32_16x16x32_bf16 v[2:5], v[156:159], v[206:209], v[2:5]
	v_mfma_f32_16x16x32_bf16 v[32:35], v[152:155], v[168:171], v[32:35]
	v_mfma_f32_16x16x32_bf16 v[28:31], v[160:163], v[168:171], v[28:31]
	v_mfma_f32_16x16x32_bf16 v[24:27], v[152:155], v[176:179], v[24:27]
	v_mfma_f32_16x16x32_bf16 v[20:23], v[160:163], v[176:179], v[20:23]
	v_mfma_f32_16x16x32_bf16 v[16:19], v[152:155], v[202:205], v[16:19]
	v_mfma_f32_16x16x32_bf16 v[12:15], v[160:163], v[202:205], v[12:15]
	v_mfma_f32_16x16x32_bf16 v[8:11], v[152:155], v[210:213], v[6:9]
	v_mfma_f32_16x16x32_bf16 v[4:7], v[160:163], v[210:213], v[2:5]
	s_barrier
	s_setprio 0
	s_add_i32 s75, s75, 2
	s_add_u32 s14, s14, 0x100
	s_addc_u32 s15, s15, 0
	s_add_u32 s72, s72, 0x100
	s_addc_u32 s73, s73, 0
	s_cmp_gt_u32 s75, 29
	s_cbranch_scc0 .LBB0_805
	s_and_b64 vcc, exec, s[38:39]
	s_cbranch_vccz .LBB0_808
	s_barrier

;     __device__ bool next(int i, Unit& u) const { if (!base.next(i >> 1, u)) return false; u.sub = i & 1; return true; }
; #define PG8_STAGE(bufoff, gbase, voff) do { _Pragma("unroll") for (int _i = 0; _i < 2; ++_i) \
;         __builtin_amdgcn_global_load_lds((const unsigned*)((const char*)(gbase) + (voff)[_i]), (PG8_LAS unsigned*)(lds + (bufoff) + ldsw + _i * 8192), 16, 0, 0); } while (0)
; #define PG8_LDA(dst, b, h) do { _Pragma("unroll") for (int m = 0; m < 4; ++m) _Pragma("unroll") for (int k = 0; k < 2; ++k) dst[m][k] = *(const PG8_LAS bf16x8*)(lds + PG8_SA(b, h) + aoff + m * 2048 + k * 1024); } while (0)
; #define PG8_LDB(dst, b, h) do { _Pragma("unroll") for (int n = 0; n < 2; ++n) _Pragma("unroll") for (int k = 0; k < 2; ++k) dst[n][k] = *(const PG8_LAS bf16x8*)(lds + PG8_SB(b, h) + boff + n * 2048 + k * 1024); } while (0)
; #define PG8_WAIT_V(n) asm volatile("s_waitcnt vmcnt(" #n ")" ::: "memory")
; template <class Epi, class Sched, bool ALIGN_EPI = false, bool SP2 = false, bool DUAL = false>
; __device__ __forceinline__ void gemm_phase(PG8_LAS unsigned char* lds, const Gemm g, const Sched& S, const Epi& E) {
;     ...
;         const bool has_next = S.next(ui + 1, nxt);
;         const char* nA = has_next ? (const char*)((DUAL && nxt.sub) ? g.A2 : g.A) + (size_t)nxt.pm * tstep : cA; const char* nB = has_next ? (const char*)((DUAL && nxt.sub) ? g.Bt2 : g.Bt) + (size_t)nxt.pn * tstep : cB;
;         for (int t = 0; t < nt; t += 2) {
;             const bool last = (t == nt - 2);
;             const char* a1 = cA + (size_t)(t + 1) * kstep;
;             const char* a2 = last ? nA : cA + (size_t)(t + 2) * kstep; const char* b2 = last ? nB : cB + (size_t)(t + 2) * kstep;
;             const char* a3 = a2 + kstep; const char* b3 = b2 + kstep;
;             if (last && has_next) S.a_ready(nxt);
;             if constexpr (SP2) {
;             PG8_LDB(B0, 0, 0); PG8_LDB(B1, 0, 1); PG8_SCHED; PG8_LDA(At, 0, 0); PG8_STAGE(PG8_SA(1, 1), a1 + hstep, voffA);
;             PG8_WAIT_V(8); PG8_WAIT_L(0); PG8_BAR; PG8_MMA(0, 0, At, B0); PG8_MMA(0, 1, At, B1); PG8_BAR; PG8_SCHED;
;             PG8_LDA(At, 0, 1); PG8_STAGE(PG8_SB(0, 0), b2, voffB); PG8_STAGE(PG8_SB(0, 1), b2 + hstep, voffB); PG8_STAGE(PG8_SA(0, 0), a2, voffA);
;             PG8_WAIT_V(8); PG8_WAIT_L(0); PG8_BAR; PG8_MMA(1, 0, At, B0); PG8_MMA(1, 1, At, B1); PG8_BAR; PG8_SCHED;
.LBB0_895:
	s_ashr_i32 s61, s60, 31
	s_lshl_b64 s[18:19], s[60:61], 20
	s_add_u32 s62, s10, s18
	s_addc_u32 s63, s11, s19
	s_and_b64 s[18:19], s[6:7], exec
	s_cselect_b32 s18, s63, s17
	s_cselect_b32 s19, s62, s16
	s_ashr_i32 s41, s40, 31
	s_lshl_b64 s[64:65], s[40:41], 20
	s_add_u32 s64, s12, s64
	s_addc_u32 s65, s13, s65
	s_and_b64 s[68:69], s[6:7], exec
	s_cselect_b32 s41, s65, s15
	s_cselect_b32 s61, s64, s14
	s_add_u32 s68, s16, 0x80080
	s_addc_u32 s69, s17, 0
	s_add_u32 s67, s14, 0x100
	s_addc_u32 s70, s15, 0
	s_mov_b32 s71, -2
	s_waitcnt lgkmcnt(0)
	s_add_u32 s14, s68, 0xfff80080
	s_addc_u32 s15, s69, -1
	s_cmp_eq_u32 s71, 28
	s_cselect_b32 s17, s18, s15
	s_cselect_b32 s16, s19, s14
	s_cselect_b32 s15, s41, s70
	s_cselect_b32 s14, s61, s67
	s_waitcnt vmcnt(8)
	s_waitcnt lgkmcnt(0)
	s_setprio 1
	s_barrier
	v_mfma_f32_16x16x32_bf16 v[124:127], v[128:131], v[160:163], 0
	v_mfma_f32_16x16x32_bf16 v[124:127], v[132:135], v[164:167], v[124:127]
	v_mfma_f32_16x16x32_bf16 v[108:111], v[128:131], v[168:171], 0
	v_mfma_f32_16x16x32_bf16 v[108:111], v[132:135], v[172:175], v[108:111]
	v_mfma_f32_16x16x32_bf16 v[92:95], v[128:131], v[196:199], 0
	v_mfma_f32_16x16x32_bf16 v[92:95], v[132:135], v[202:205], v[92:95]
	v_mfma_f32_16x16x32_bf16 v[76:79], v[128:131], v[206:209], 0
	v_mfma_f32_16x16x32_bf16 v[76:79], v[132:135], v[232:235], v[76:79]
	v_mfma_f32_16x16x32_bf16 v[120:123], v[136:139], v[160:163], 0
	v_mfma_f32_16x16x32_bf16 v[120:123], v[140:143], v[164:167], v[120:123]
	v_mfma_f32_16x16x32_bf16 v[104:107], v[136:139], v[168:171], 0
	v_mfma_f32_16x16x32_bf16 v[104:107], v[140:143], v[172:175], v[104:107]
	v_mfma_f32_16x16x32_bf16 v[88:91], v[136:139], v[196:199], 0
	v_mfma_f32_16x16x32_bf16 v[88:91], v[140:143], v[202:205], v[88:91]
	v_mfma_f32_16x16x32_bf16 v[72:75], v[136:139], v[206:209], 0
	v_mfma_f32_16x16x32_bf16 v[72:75], v[140:143], v[232:235], v[72:75]
	s_setprio 0
	s_setprio 1
	v_mfma_f32_16x16x32_bf16 v[116:119], v[144:147], v[160:163], 0
	v_mfma_f32_16x16x32_bf16 v[116:119], v[148:151], v[164:167], v[116:119]
	v_mfma_f32_16x16x32_bf16 v[100:103], v[144:147], v[168:171], 0
	v_mfma_f32_16x16x32_bf16 v[100:103], v[148:151], v[172:175], v[100:103]
	v_mfma_f32_16x16x32_bf16 v[84:87], v[144:147], v[196:199], 0
	v_mfma_f32_16x16x32_bf16 v[84:87], v[148:151], v[202:205], v[84:87]
	v_mfma_f32_16x16x32_bf16 v[68:71], v[144:147], v[206:209], 0
	v_mfma_f32_16x16x32_bf16 v[68:71], v[148:151], v[232:235], v[68:71]
	v_mfma_f32_16x16x32_bf16 v[112:115], v[152:155], v[160:163], 0
	v_mfma_f32_16x16x32_bf16 v[112:115], v[156:159], v[164:167], v[112:115]
	v_mfma_f32_16x16x32_bf16 v[96:99], v[152:155], v[168:171], 0
	v_mfma_f32_16x16x32_bf16 v[96:99], v[156:159], v[172:175], v[96:99]
	v_mfma_f32_16x16x32_bf16 v[80:83], v[152:155], v[196:199], 0
	v_mfma_f32_16x16x32_bf16 v[80:83], v[156:159], v[202:205], v[80:83]
	v_mfma_f32_16x16x32_bf16 v[64:67], v[152:155], v[206:209], 0
	v_mfma_f32_16x16x32_bf16 v[64:67], v[156:159], v[232:235], v[64:67]
	s_barrier
	s_setprio 0
	s_add_u32 s98, s14, 0x80
	s_addc_u32 s99, s15, 0
	s_add_u32 s100, s16, 0x80
	s_addc_u32 s101, s17, 0
	s_add_i32 m0, s27, 0xc000
	s_nop 0
	global_load_lds_dwordx4 v188, s[68:69]
	s_add_i32 m0, s27, 0xe000
	s_nop 0
	global_load_lds_dwordx4 v190, s[68:69]
	s_add_i32 s72, s48, s26
	s_mov_b32 m0, s72
	ds_read_b128 v[160:163], v220 offset:16384
	ds_read_b128 v[164:167], v220 offset:17408
	ds_read_b128 v[168:171], v220 offset:18432
	ds_read_b128 v[172:175], v220 offset:19456
	ds_read_b128 v[196:199], v220 offset:20480
	ds_read_b128 v[202:205], v220 offset:21504
	ds_read_b128 v[206:209], v220 offset:22528
	ds_read_b128 v[232:235], v220 offset:23552
	global_load_lds_dwordx4 v182, s[14:15]
	s_add_i32 m0, s72, 0x2000
	s_add_u32 s72, s14, 0x80000
	s_addc_u32 s73, s15, 0
	s_add_i32 s74, s49, s26
	global_load_lds_dwordx4 v186, s[14:15]
	s_mov_b32 m0, s74
	s_nop 0
	global_load_lds_dwordx4 v182, s[72:73]
	s_add_i32 m0, s74, 0x2000
	s_nop 0
	global_load_lds_dwordx4 v186, s[72:73]
	s_mov_b32 m0, s27
	s_nop 0
	global_load_lds_dwordx4 v180, s[16:17]
	s_mov_b32 m0, s28
	s_nop 0
	global_load_lds_dwordx4 v184, s[16:17]
	s_waitcnt vmcnt(8)
	s_waitcnt lgkmcnt(0)
	s_setprio 1
	s_barrier
	v_mfma_f32_16x16x32_bf16 v[60:63], v[128:131], v[160:163], 0
	v_mfma_f32_16x16x32_bf16 v[60:63], v[132:135], v[164:167], v[60:63]
	v_mfma_f32_16x16x32_bf16 v[44:47], v[128:131], v[168:171], 0
	v_mfma_f32_16x16x32_bf16 v[44:47], v[132:135], v[172:175], v[44:47]
	v_mfma_f32_16x16x32_bf16 v[28:31], v[128:131], v[196:199], 0
	v_mfma_f32_16x16x32_bf16 v[28:31], v[132:135], v[202:205], v[28:31]
	v_mfma_f32_16x16x32_bf16 v[12:15], v[128:131], v[206:209], 0
	v_mfma_f32_16x16x32_bf16 v[12:15], v[132:135], v[232:235], v[12:15]
	v_mfma_f32_16x16x32_bf16 v[56:59], v[136:139], v[160:163], 0
	v_mfma_f32_16x16x32_bf16 v[56:59], v[140:143], v[164:167], v[56:59]
	v_mfma_f32_16x16x32_bf16 v[40:43], v[136:139], v[168:171], 0
	v_mfma_f32_16x16x32_bf16 v[40:43], v[140:143], v[172:175], v[40:43]
	v_mfma_f32_16x16x32_bf16 v[24:27], v[136:139], v[196:199], 0
	v_mfma_f32_16x16x32_bf16 v[24:27], v[140:143], v[202:205], v[24:27]
	v_mfma_f32_16x16x32_bf16 v[8:11], v[136:139], v[206:209], 0
	v_mfma_f32_16x16x32_bf16 v[8:11], v[140:143], v[232:235], v[8:11]
	s_setprio 0
	s_setprio 1
	v_mfma_f32_16x16x32_bf16 v[52:55], v[144:147], v[160:163], 0
	v_mfma_f32_16x16x32_bf16 v[52:55], v[148:151], v[164:167], v[52:55]
	v_mfma_f32_16x16x32_bf16 v[36:39], v[144:147], v[168:171], 0
	v_mfma_f32_16x16x32_bf16 v[36:39], v[148:151], v[172:175], v[36:39]
	v_mfma_f32_16x16x32_bf16 v[20:23], v[144:147], v[196:199], 0
	v_mfma_f32_16x16x32_bf16 v[20:23], v[148:151], v[202:205], v[20:23]
	v_mfma_f32_16x16x32_bf16 v[4:7], v[144:147], v[206:209], 0
	v_mfma_f32_16x16x32_bf16 v[4:7], v[148:151], v[232:235], v[4:7]
	v_mfma_f32_16x16x32_bf16 v[48:51], v[152:155], v[160:163], 0
	v_mfma_f32_16x16x32_bf16 v[48:51], v[156:159], v[164:167], v[48:51]
	v_mfma_f32_16x16x32_bf16 v[32:35], v[152:155], v[168:171], 0
	v_mfma_f32_16x16x32_bf16 v[32:35], v[156:159], v[172:175], v[32:35]
	v_mfma_f32_16x16x32_bf16 v[16:19], v[152:155], v[196:199], 0
	v_mfma_f32_16x16x32_bf16 v[16:19], v[156:159], v[202:205], v[16:19]
	v_mfma_f32_16x16x32_bf16 v[0:3], v[152:155], v[206:209], 0
	v_mfma_f32_16x16x32_bf16 v[0:3], v[156:159], v[232:235], v[0:3]
	s_barrier
; #define PG8_STAGE(bufoff, gbase, voff) do { _Pragma("unroll") for (int _i = 0; _i < 2; ++_i) \
;         __builtin_amdgcn_global_load_lds((const unsigned*)((const char*)(gbase) + (voff)[_i]), (PG8_LAS unsigned*)(lds + (bufoff) + ldsw + _i * 8192), 16, 0, 0); } while (0)
; #define PG8_LDA(dst, b, h) do { _Pragma("unroll") for (int m = 0; m < 4; ++m) _Pragma("unroll") for (int k = 0; k < 2; ++k) dst[m][k] = *(const PG8_LAS bf16x8*)(lds + PG8_SA(b, h) + aoff + m * 2048 + k * 1024); } while (0)
; #define PG8_LDB(dst, b, h) do { _Pragma("unroll") for (int n = 0; n < 2; ++n) _Pragma("unroll") for (int k = 0; k < 2; ++k) dst[n][k] = *(const PG8_LAS bf16x8*)(lds + PG8_SB(b, h) + boff + n * 2048 + k * 1024); } while (0)
; #define PG8_MMA(ai, bj, At, Bt) do { __builtin_amdgcn_s_setprio(1); _Pragma("unroll") for (int m = 0; m < 4; ++m) _Pragma("unroll") for (int n = 0; n < 2; ++n) _Pragma("unroll") for (int k = 0; k < 2; ++k) \
;         acc[ai][bj][m][n] = __builtin_amdgcn_mfma_f32_16x16x32_bf16(Bt[n][k], At[m][k], acc[ai][bj][m][n], 0, 0, 0); __builtin_amdgcn_s_setprio(0); } while (0)
; #define PG8_WAIT_V(n) asm volatile("s_waitcnt vmcnt(" #n ")" ::: "memory")
; #define PG8_WAIT_L(n) asm volatile("s_waitcnt lgkmcnt(" #n ")" ::: "memory")
; #define PG8_BAR __builtin_amdgcn_s_barrier()
; #define PG8_SCHED __builtin_amdgcn_sched_barrier(0)
; template <class Epi, class Sched, bool ALIGN_EPI = false, bool SP2 = false, bool DUAL = false>
; __device__ __forceinline__ void gemm_phase(PG8_LAS unsigned char* lds, const Gemm g, const Sched& S, const Epi& E) {
;     ...
;             PG8_LDB(B0, 1, 0); PG8_LDB(B1, 1, 1); PG8_SCHED; PG8_LDA(At, 1, 0); PG8_STAGE(PG8_SA(0, 1), a2 + hstep, voffA);
;             PG8_WAIT_V(8); PG8_WAIT_L(0); PG8_BAR; PG8_MMA(0, 0, At, B0); PG8_MMA(0, 1, At, B1); PG8_BAR; PG8_SCHED;
;             PG8_LDA(At, 1, 1); PG8_STAGE(PG8_SB(1, 0), b3, voffB); PG8_STAGE(PG8_SB(1, 1), b3 + hstep, voffB); PG8_STAGE(PG8_SA(1, 0), a3, voffA);
;             PG8_WAIT_V(8); PG8_WAIT_L(0); PG8_BAR; PG8_MMA(1, 0, At, B0); PG8_MMA(1, 1, At, B1); PG8_BAR; PG8_SCHED;
	s_setprio 0
	s_add_i32 s72, 0, 0x18000
	s_add_i32 s73, 0, 0x1c000
	v_add_u32_e32 v140, s72, v216
	v_add_u32_e32 v156, s73, v216
	ds_read_b128 v[128:131], v140
	ds_read_b128 v[132:135], v140 offset:1024
	ds_read_b128 v[136:139], v140 offset:2048
	ds_read_b128 v[140:143], v140 offset:3072
	ds_read_b128 v[144:147], v156
	ds_read_b128 v[148:151], v156 offset:1024
	ds_read_b128 v[152:155], v156 offset:2048
	ds_read_b128 v[156:159], v156 offset:3072
	s_add_u32 s16, s16, 0x80000
	s_addc_u32 s17, s17, 0
	s_mov_b32 m0, s29
	ds_read_b128 v[160:163], v220 offset:32768
	ds_read_b128 v[164:167], v220 offset:33792
	ds_read_b128 v[168:171], v220 offset:34816
	ds_read_b128 v[172:175], v220 offset:35840
	ds_read_b128 v[196:199], v220 offset:36864
	ds_read_b128 v[202:205], v220 offset:37888
	ds_read_b128 v[206:209], v220 offset:38912
	ds_read_b128 v[232:235], v220 offset:39936
	global_load_lds_dwordx4 v180, s[16:17]
	s_mov_b32 m0, s34
	s_nop 0
	global_load_lds_dwordx4 v184, s[16:17]
	s_waitcnt vmcnt(8)
	s_waitcnt lgkmcnt(0)
	s_setprio 1
	s_barrier
	v_mfma_f32_16x16x32_bf16 v[124:127], v[128:131], v[160:163], v[124:127]
	v_mfma_f32_16x16x32_bf16 v[124:127], v[132:135], v[164:167], v[124:127]
	v_mfma_f32_16x16x32_bf16 v[108:111], v[128:131], v[168:171], v[108:111]
	v_mfma_f32_16x16x32_bf16 v[108:111], v[132:135], v[172:175], v[108:111]
	v_mfma_f32_16x16x32_bf16 v[92:95], v[128:131], v[196:199], v[92:95]
	v_mfma_f32_16x16x32_bf16 v[92:95], v[132:135], v[202:205], v[92:95]
	v_mfma_f32_16x16x32_bf16 v[76:79], v[128:131], v[206:209], v[76:79]
	v_mfma_f32_16x16x32_bf16 v[76:79], v[132:135], v[232:235], v[76:79]
	v_mfma_f32_16x16x32_bf16 v[120:123], v[136:139], v[160:163], v[120:123]
	v_mfma_f32_16x16x32_bf16 v[120:123], v[140:143], v[164:167], v[120:123]
	v_mfma_f32_16x16x32_bf16 v[104:107], v[136:139], v[168:171], v[104:107]
	v_mfma_f32_16x16x32_bf16 v[104:107], v[140:143], v[172:175], v[104:107]
	v_mfma_f32_16x16x32_bf16 v[88:91], v[136:139], v[196:199], v[88:91]
	v_mfma_f32_16x16x32_bf16 v[88:91], v[140:143], v[202:205], v[88:91]
	v_mfma_f32_16x16x32_bf16 v[72:75], v[136:139], v[206:209], v[72:75]
	v_mfma_f32_16x16x32_bf16 v[72:75], v[140:143], v[232:235], v[72:75]
	s_setprio 0
	s_setprio 1
	v_mfma_f32_16x16x32_bf16 v[116:119], v[144:147], v[160:163], v[116:119]
	v_mfma_f32_16x16x32_bf16 v[116:119], v[148:151], v[164:167], v[116:119]
	v_mfma_f32_16x16x32_bf16 v[100:103], v[144:147], v[168:171], v[100:103]
	v_mfma_f32_16x16x32_bf16 v[100:103], v[148:151], v[172:175], v[100:103]
	v_mfma_f32_16x16x32_bf16 v[84:87], v[144:147], v[196:199], v[84:87]
	v_mfma_f32_16x16x32_bf16 v[84:87], v[148:151], v[202:205], v[84:87]
	v_mfma_f32_16x16x32_bf16 v[68:71], v[144:147], v[206:209], v[68:71]
	v_mfma_f32_16x16x32_bf16 v[68:71], v[148:151], v[232:235], v[68:71]
	v_mfma_f32_16x16x32_bf16 v[112:115], v[152:155], v[160:163], v[112:115]
	v_mfma_f32_16x16x32_bf16 v[112:115], v[156:159], v[164:167], v[112:115]
	v_mfma_f32_16x16x32_bf16 v[96:99], v[152:155], v[168:171], v[96:99]
	v_mfma_f32_16x16x32_bf16 v[96:99], v[156:159], v[172:175], v[96:99]
	v_mfma_f32_16x16x32_bf16 v[80:83], v[152:155], v[196:199], v[80:83]
	v_mfma_f32_16x16x32_bf16 v[80:83], v[156:159], v[202:205], v[80:83]
	v_mfma_f32_16x16x32_bf16 v[64:67], v[152:155], v[206:209], v[64:67]
	v_mfma_f32_16x16x32_bf16 v[64:67], v[156:159], v[232:235], v[64:67]
	s_barrier
	s_setprio 0
	s_add_i32 s16, s72, s26
	s_mov_b32 m0, s16
	ds_read_b128 v[160:163], v220 offset:49152
	ds_read_b128 v[164:167], v220 offset:50176
	ds_read_b128 v[168:171], v220 offset:51200
	ds_read_b128 v[172:175], v220 offset:52224
	ds_read_b128 v[196:199], v220 offset:53248
	ds_read_b128 v[202:205], v220 offset:54272
	ds_read_b128 v[206:209], v220 offset:55296
	ds_read_b128 v[232:235], v220 offset:56320
	global_load_lds_dwordx4 v182, s[98:99]
	s_add_i32 m0, s16, 0x2000
	s_add_u32 s14, s14, 0x80080
	s_addc_u32 s15, s15, 0
	s_add_i32 s16, s73, s26
	global_load_lds_dwordx4 v186, s[98:99]
	s_mov_b32 m0, s16
	s_nop 0
	global_load_lds_dwordx4 v182, s[14:15]
	s_add_i32 m0, s16, 0x2000
	s_nop 0
	global_load_lds_dwordx4 v186, s[14:15]
	s_mov_b32 m0, s44
	s_nop 0
	global_load_lds_dwordx4 v180, s[100:101]
	s_mov_b32 m0, s45
	s_nop 0
	global_load_lds_dwordx4 v184, s[100:101]
	s_waitcnt vmcnt(8)
	s_waitcnt lgkmcnt(0)
	s_setprio 1
	s_barrier
	v_mfma_f32_16x16x32_bf16 v[60:63], v[128:131], v[160:163], v[60:63]
	v_mfma_f32_16x16x32_bf16 v[60:63], v[132:135], v[164:167], v[60:63]
	v_mfma_f32_16x16x32_bf16 v[44:47], v[128:131], v[168:171], v[44:47]
	v_mfma_f32_16x16x32_bf16 v[44:47], v[132:135], v[172:175], v[44:47]
	v_mfma_f32_16x16x32_bf16 v[28:31], v[128:131], v[196:199], v[28:31]
	v_mfma_f32_16x16x32_bf16 v[28:31], v[132:135], v[202:205], v[28:31]
	v_mfma_f32_16x16x32_bf16 v[12:15], v[128:131], v[206:209], v[12:15]
	v_mfma_f32_16x16x32_bf16 v[12:15], v[132:135], v[232:235], v[12:15]
	v_mfma_f32_16x16x32_bf16 v[56:59], v[136:139], v[160:163], v[56:59]
	v_mfma_f32_16x16x32_bf16 v[56:59], v[140:143], v[164:167], v[56:59]
	v_mfma_f32_16x16x32_bf16 v[40:43], v[136:139], v[168:171], v[40:43]
	v_mfma_f32_16x16x32_bf16 v[40:43], v[140:143], v[172:175], v[40:43]
	v_mfma_f32_16x16x32_bf16 v[24:27], v[136:139], v[196:199], v[24:27]
	v_mfma_f32_16x16x32_bf16 v[24:27], v[140:143], v[202:205], v[24:27]
	v_mfma_f32_16x16x32_bf16 v[8:11], v[136:139], v[206:209], v[8:11]
	v_mfma_f32_16x16x32_bf16 v[8:11], v[140:143], v[232:235], v[8:11]
	s_setprio 0
	s_setprio 1
	v_mfma_f32_16x16x32_bf16 v[52:55], v[144:147], v[160:163], v[52:55]
	v_mfma_f32_16x16x32_bf16 v[52:55], v[148:151], v[164:167], v[52:55]
	v_mfma_f32_16x16x32_bf16 v[36:39], v[144:147], v[168:171], v[36:39]
	v_mfma_f32_16x16x32_bf16 v[36:39], v[148:151], v[172:175], v[36:39]
	v_mfma_f32_16x16x32_bf16 v[20:23], v[144:147], v[196:199], v[20:23]
	v_mfma_f32_16x16x32_bf16 v[20:23], v[148:151], v[202:205], v[20:23]
	v_mfma_f32_16x16x32_bf16 v[4:7], v[144:147], v[206:209], v[4:7]
	v_mfma_f32_16x16x32_bf16 v[4:7], v[148:151], v[232:235], v[4:7]
	v_mfma_f32_16x16x32_bf16 v[48:51], v[152:155], v[160:163], v[48:51]
	v_mfma_f32_16x16x32_bf16 v[48:51], v[156:159], v[164:167], v[48:51]
	v_mfma_f32_16x16x32_bf16 v[32:35], v[152:155], v[168:171], v[32:35]
	v_mfma_f32_16x16x32_bf16 v[32:35], v[156:159], v[172:175], v[32:35]
	v_mfma_f32_16x16x32_bf16 v[16:19], v[152:155], v[196:199], v[16:19]
	v_mfma_f32_16x16x32_bf16 v[16:19], v[156:159], v[202:205], v[16:19]
	v_mfma_f32_16x16x32_bf16 v[0:3], v[152:155], v[206:209], v[0:3]
	v_mfma_f32_16x16x32_bf16 v[0:3], v[156:159], v[232:235], v[0:3]
	s_barrier
	s_setprio 0
	s_add_i32 s71, s71, 2
	s_add_u32 s68, s68, 0x100
	s_addc_u32 s69, s69, 0
	s_add_u32 s67, s67, 0x100
	s_addc_u32 s70, s70, 0
; #define PG8_STAGE(bufoff, gbase, voff) do { _Pragma("unroll") for (int _i = 0; _i < 2; ++_i) \
;         __builtin_amdgcn_global_load_lds((const unsigned*)((const char*)(gbase) + (voff)[_i]), (PG8_LAS unsigned*)(lds + (bufoff) + ldsw + _i * 8192), 16, 0, 0); } while (0)
; #define PG8_LDA(dst, b, h) do { _Pragma("unroll") for (int m = 0; m < 4; ++m) _Pragma("unroll") for (int k = 0; k < 2; ++k) dst[m][k] = *(const PG8_LAS bf16x8*)(lds + PG8_SA(b, h) + aoff + m * 2048 + k * 1024); } while (0)
; #define PG8_LDB(dst, b, h) do { _Pragma("unroll") for (int n = 0; n < 2; ++n) _Pragma("unroll") for (int k = 0; k < 2; ++k) dst[n][k] = *(const PG8_LAS bf16x8*)(lds + PG8_SB(b, h) + boff + n * 2048 + k * 1024); } while (0)
; #define PG8_MMA(ai, bj, At, Bt) do { __builtin_amdgcn_s_setprio(1); _Pragma("unroll") for (int m = 0; m < 4; ++m) _Pragma("unroll") for (int n = 0; n < 2; ++n) _Pragma("unroll") for (int k = 0; k < 2; ++k) \
;         acc[ai][bj][m][n] = __builtin_amdgcn_mfma_f32_16x16x32_bf16(Bt[n][k], At[m][k], acc[ai][bj][m][n], 0, 0, 0); __builtin_amdgcn_s_setprio(0); } while (0)
; #define PG8_WAIT_V(n) asm volatile("s_waitcnt vmcnt(" #n ")" ::: "memory")
; #define PG8_BAR __builtin_amdgcn_s_barrier()
; template <class Epi, class Sched, bool ALIGN_EPI = false, bool SP2 = false, bool DUAL = false>
; __device__ __forceinline__ void gemm_phase(PG8_LAS unsigned char* lds, const Gemm g, const Sched& S, const Epi& E) {
;     ...
;         for (int t = 0; t < nt; t += 2) {
;             const bool last = (t == nt - 2);
;             const char* a1 = cA + (size_t)(t + 1) * kstep;
;             const char* a2 = last ? nA : cA + (size_t)(t + 2) * kstep; const char* b2 = last ? nB : cB + (size_t)(t + 2) * kstep;
;             const char* a3 = a2 + kstep; const char* b3 = b2 + kstep;
;             if (last && has_next) S.a_ready(nxt);
;             if constexpr (SP2) {
;             PG8_LDB(B0, 0, 0); PG8_LDB(B1, 0, 1); PG8_SCHED; PG8_LDA(At, 0, 0); PG8_STAGE(PG8_SA(1, 1), a1 + hstep, voffA);
;             PG8_WAIT_V(8); PG8_WAIT_L(0); PG8_BAR; PG8_MMA(0, 0, At, B0); PG8_MMA(0, 1, At, B1); PG8_BAR; PG8_SCHED;
;             PG8_LDA(At, 0, 1); PG8_STAGE(PG8_SB(0, 0), b2, voffB); PG8_STAGE(PG8_SB(0, 1), b2 + hstep, voffB); PG8_STAGE(PG8_SA(0, 0), a2, voffA);
;             PG8_WAIT_V(8); PG8_WAIT_L(0); PG8_BAR; PG8_MMA(1, 0, At, B0); PG8_MMA(1, 1, At, B1); PG8_BAR; PG8_SCHED;
.LBB0_896:
	ds_read_b128 v[128:131], v218
	ds_read_b128 v[132:135], v218 offset:1024
	ds_read_b128 v[136:139], v218 offset:2048
	ds_read_b128 v[140:143], v218 offset:3072
	ds_read_b128 v[144:147], v219
	ds_read_b128 v[148:151], v219 offset:1024
	ds_read_b128 v[152:155], v219 offset:2048
	ds_read_b128 v[156:159], v219 offset:3072
	s_add_u32 s14, s68, 0xfff80080
	s_addc_u32 s15, s69, -1
	s_cmp_eq_u32 s71, 28
	s_cselect_b32 s17, s18, s15
	s_cselect_b32 s16, s19, s14
	s_cselect_b32 s15, s41, s70
	s_cselect_b32 s14, s61, s67
	s_add_i32 m0, s27, 0xc000
	ds_read_b128 v[160:163], v220
	ds_read_b128 v[164:167], v220 offset:1024
	ds_read_b128 v[168:171], v220 offset:2048
	ds_read_b128 v[172:175], v220 offset:3072
	ds_read_b128 v[196:199], v220 offset:4096
	ds_read_b128 v[202:205], v220 offset:5120
	ds_read_b128 v[206:209], v220 offset:6144
	ds_read_b128 v[232:235], v220 offset:7168
	global_load_lds_dwordx4 v188, s[68:69]
	s_add_i32 m0, s27, 0xe000
	s_nop 0
	global_load_lds_dwordx4 v190, s[68:69]
	s_waitcnt vmcnt(8)
	s_waitcnt lgkmcnt(0)
	s_setprio 1
	s_barrier
	v_mfma_f32_16x16x32_bf16 v[124:127], v[128:131], v[160:163], v[124:127]
	v_mfma_f32_16x16x32_bf16 v[124:127], v[132:135], v[164:167], v[124:127]
	v_mfma_f32_16x16x32_bf16 v[108:111], v[128:131], v[168:171], v[108:111]
	v_mfma_f32_16x16x32_bf16 v[108:111], v[132:135], v[172:175], v[108:111]
	v_mfma_f32_16x16x32_bf16 v[92:95], v[128:131], v[196:199], v[92:95]
	v_mfma_f32_16x16x32_bf16 v[92:95], v[132:135], v[202:205], v[92:95]
	v_mfma_f32_16x16x32_bf16 v[76:79], v[128:131], v[206:209], v[76:79]
	v_mfma_f32_16x16x32_bf16 v[76:79], v[132:135], v[232:235], v[76:79]
	v_mfma_f32_16x16x32_bf16 v[120:123], v[136:139], v[160:163], v[120:123]
	v_mfma_f32_16x16x32_bf16 v[120:123], v[140:143], v[164:167], v[120:123]
	v_mfma_f32_16x16x32_bf16 v[104:107], v[136:139], v[168:171], v[104:107]
	v_mfma_f32_16x16x32_bf16 v[104:107], v[140:143], v[172:175], v[104:107]
	v_mfma_f32_16x16x32_bf16 v[88:91], v[136:139], v[196:199], v[88:91]
	v_mfma_f32_16x16x32_bf16 v[88:91], v[140:143], v[202:205], v[88:91]
	v_mfma_f32_16x16x32_bf16 v[72:75], v[136:139], v[206:209], v[72:75]
	v_mfma_f32_16x16x32_bf16 v[72:75], v[140:143], v[232:235], v[72:75]
	s_setprio 0
	s_setprio 1
	v_mfma_f32_16x16x32_bf16 v[116:119], v[144:147], v[160:163], v[116:119]
	v_mfma_f32_16x16x32_bf16 v[116:119], v[148:151], v[164:167], v[116:119]
	v_mfma_f32_16x16x32_bf16 v[100:103], v[144:147], v[168:171], v[100:103]
	v_mfma_f32_16x16x32_bf16 v[100:103], v[148:151], v[172:175], v[100:103]
	v_mfma_f32_16x16x32_bf16 v[84:87], v[144:147], v[196:199], v[84:87]
	v_mfma_f32_16x16x32_bf16 v[84:87], v[148:151], v[202:205], v[84:87]
	v_mfma_f32_16x16x32_bf16 v[68:71], v[144:147], v[206:209], v[68:71]
	v_mfma_f32_16x16x32_bf16 v[68:71], v[148:151], v[232:235], v[68:71]
	v_mfma_f32_16x16x32_bf16 v[112:115], v[152:155], v[160:163], v[112:115]
	v_mfma_f32_16x16x32_bf16 v[112:115], v[156:159], v[164:167], v[112:115]
	v_mfma_f32_16x16x32_bf16 v[96:99], v[152:155], v[168:171], v[96:99]
	v_mfma_f32_16x16x32_bf16 v[96:99], v[156:159], v[172:175], v[96:99]
	v_mfma_f32_16x16x32_bf16 v[80:83], v[152:155], v[196:199], v[80:83]
	v_mfma_f32_16x16x32_bf16 v[80:83], v[156:159], v[202:205], v[80:83]
	v_mfma_f32_16x16x32_bf16 v[64:67], v[152:155], v[206:209], v[64:67]
	v_mfma_f32_16x16x32_bf16 v[64:67], v[156:159], v[232:235], v[64:67]
	s_barrier
	s_setprio 0
	s_add_u32 s98, s14, 0x80
	s_addc_u32 s99, s15, 0
	s_add_u32 s100, s16, 0x80
	s_addc_u32 s101, s17, 0
	s_add_i32 s72, s48, s26
	s_mov_b32 m0, s72
	ds_read_b128 v[160:163], v220 offset:16384
	ds_read_b128 v[164:167], v220 offset:17408
	ds_read_b128 v[168:171], v220 offset:18432
	ds_read_b128 v[172:175], v220 offset:19456
	ds_read_b128 v[196:199], v220 offset:20480
	ds_read_b128 v[202:205], v220 offset:21504
	ds_read_b128 v[206:209], v220 offset:22528
	ds_read_b128 v[232:235], v220 offset:23552
	global_load_lds_dwordx4 v182, s[14:15]
	s_add_i32 m0, s72, 0x2000
	s_add_u32 s72, s14, 0x80000
	s_addc_u32 s73, s15, 0
	s_add_i32 s74, s49, s26
	global_load_lds_dwordx4 v186, s[14:15]
	s_mov_b32 m0, s74
	s_nop 0
	global_load_lds_dwordx4 v182, s[72:73]
	s_add_i32 m0, s74, 0x2000
	s_nop 0
	global_load_lds_dwordx4 v186, s[72:73]
	s_mov_b32 m0, s27
	s_nop 0
	global_load_lds_dwordx4 v180, s[16:17]
	s_mov_b32 m0, s28
	s_nop 0
	global_load_lds_dwordx4 v184, s[16:17]
	s_waitcnt vmcnt(8)
	s_waitcnt lgkmcnt(0)
	s_setprio 1
	s_barrier
	v_mfma_f32_16x16x32_bf16 v[60:63], v[128:131], v[160:163], v[60:63]
	v_mfma_f32_16x16x32_bf16 v[60:63], v[132:135], v[164:167], v[60:63]
	v_mfma_f32_16x16x32_bf16 v[44:47], v[128:131], v[168:171], v[44:47]
	v_mfma_f32_16x16x32_bf16 v[44:47], v[132:135], v[172:175], v[44:47]
	v_mfma_f32_16x16x32_bf16 v[28:31], v[128:131], v[196:199], v[28:31]
	v_mfma_f32_16x16x32_bf16 v[28:31], v[132:135], v[202:205], v[28:31]
	v_mfma_f32_16x16x32_bf16 v[12:15], v[128:131], v[206:209], v[12:15]
	v_mfma_f32_16x16x32_bf16 v[12:15], v[132:135], v[232:235], v[12:15]
	v_mfma_f32_16x16x32_bf16 v[56:59], v[136:139], v[160:163], v[56:59]
	v_mfma_f32_16x16x32_bf16 v[56:59], v[140:143], v[164:167], v[56:59]
	v_mfma_f32_16x16x32_bf16 v[40:43], v[136:139], v[168:171], v[40:43]
	v_mfma_f32_16x16x32_bf16 v[40:43], v[140:143], v[172:175], v[40:43]
	v_mfma_f32_16x16x32_bf16 v[24:27], v[136:139], v[196:199], v[24:27]
	v_mfma_f32_16x16x32_bf16 v[24:27], v[140:143], v[202:205], v[24:27]
	v_mfma_f32_16x16x32_bf16 v[8:11], v[136:139], v[206:209], v[8:11]
	v_mfma_f32_16x16x32_bf16 v[8:11], v[140:143], v[232:235], v[8:11]
	s_setprio 0
	s_setprio 1
	v_mfma_f32_16x16x32_bf16 v[52:55], v[144:147], v[160:163], v[52:55]
	v_mfma_f32_16x16x32_bf16 v[52:55], v[148:151], v[164:167], v[52:55]
	v_mfma_f32_16x16x32_bf16 v[36:39], v[144:147], v[168:171], v[36:39]
	v_mfma_f32_16x16x32_bf16 v[36:39], v[148:151], v[172:175], v[36:39]
	v_mfma_f32_16x16x32_bf16 v[20:23], v[144:147], v[196:199], v[20:23]
	v_mfma_f32_16x16x32_bf16 v[20:23], v[148:151], v[202:205], v[20:23]
	v_mfma_f32_16x16x32_bf16 v[4:7], v[144:147], v[206:209], v[4:7]
	v_mfma_f32_16x16x32_bf16 v[4:7], v[148:151], v[232:235], v[4:7]
	v_mfma_f32_16x16x32_bf16 v[48:51], v[152:155], v[160:163], v[48:51]
	v_mfma_f32_16x16x32_bf16 v[48:51], v[156:159], v[164:167], v[48:51]
	v_mfma_f32_16x16x32_bf16 v[32:35], v[152:155], v[168:171], v[32:35]
	v_mfma_f32_16x16x32_bf16 v[32:35], v[156:159], v[172:175], v[32:35]
	v_mfma_f32_16x16x32_bf16 v[16:19], v[152:155], v[196:199], v[16:19]
	v_mfma_f32_16x16x32_bf16 v[16:19], v[156:159], v[202:205], v[16:19]
	v_mfma_f32_16x16x32_bf16 v[0:3], v[152:155], v[206:209], v[0:3]
	v_mfma_f32_16x16x32_bf16 v[0:3], v[156:159], v[232:235], v[0:3]
	s_barrier
; #define PG8_STAGE(bufoff, gbase, voff) do { _Pragma("unroll") for (int _i = 0; _i < 2; ++_i) \
;         __builtin_amdgcn_global_load_lds((const unsigned*)((const char*)(gbase) + (voff)[_i]), (PG8_LAS unsigned*)(lds + (bufoff) + ldsw + _i * 8192), 16, 0, 0); } while (0)
; #define PG8_LDA(dst, b, h) do { _Pragma("unroll") for (int m = 0; m < 4; ++m) _Pragma("unroll") for (int k = 0; k < 2; ++k) dst[m][k] = *(const PG8_LAS bf16x8*)(lds + PG8_SA(b, h) + aoff + m * 2048 + k * 1024); } while (0)
; #define PG8_LDB(dst, b, h) do { _Pragma("unroll") for (int n = 0; n < 2; ++n) _Pragma("unroll") for (int k = 0; k < 2; ++k) dst[n][k] = *(const PG8_LAS bf16x8*)(lds + PG8_SB(b, h) + boff + n * 2048 + k * 1024); } while (0)
; #define PG8_MMA(ai, bj, At, Bt) do { __builtin_amdgcn_s_setprio(1); _Pragma("unroll") for (int m = 0; m < 4; ++m) _Pragma("unroll") for (int n = 0; n < 2; ++n) _Pragma("unroll") for (int k = 0; k < 2; ++k) \
;         acc[ai][bj][m][n] = __builtin_amdgcn_mfma_f32_16x16x32_bf16(Bt[n][k], At[m][k], acc[ai][bj][m][n], 0, 0, 0); __builtin_amdgcn_s_setprio(0); } while (0)
; #define PG8_WAIT_V(n) asm volatile("s_waitcnt vmcnt(" #n ")" ::: "memory")
; #define PG8_WAIT_L(n) asm volatile("s_waitcnt lgkmcnt(" #n ")" ::: "memory")
; #define PG8_BAR __builtin_amdgcn_s_barrier()
; #define PG8_SCHED __builtin_amdgcn_sched_barrier(0)
; template <class Epi, class Sched, bool ALIGN_EPI = false, bool SP2 = false, bool DUAL = false>
; __device__ __forceinline__ void gemm_phase(PG8_LAS unsigned char* lds, const Gemm g, const Sched& S, const Epi& E) {
;     ...
;             PG8_LDB(B0, 1, 0); PG8_LDB(B1, 1, 1); PG8_SCHED; PG8_LDA(At, 1, 0); PG8_STAGE(PG8_SA(0, 1), a2 + hstep, voffA);
;             PG8_WAIT_V(8); PG8_WAIT_L(0); PG8_BAR; PG8_MMA(0, 0, At, B0); PG8_MMA(0, 1, At, B1); PG8_BAR; PG8_SCHED;
;             PG8_LDA(At, 1, 1); PG8_STAGE(PG8_SB(1, 0), b3, voffB); PG8_STAGE(PG8_SB(1, 1), b3 + hstep, voffB); PG8_STAGE(PG8_SA(1, 0), a3, voffA);
;             PG8_WAIT_V(8); PG8_WAIT_L(0); PG8_BAR; PG8_MMA(1, 0, At, B0); PG8_MMA(1, 1, At, B1); PG8_BAR; PG8_SCHED;
;     ...
;         if constexpr (ALIGN_EPI) { if (wr == 0) PG8_BAR; }
	s_setprio 0
	s_add_i32 s72, 0, 0x18000
	s_add_i32 s73, 0, 0x1c000
	v_add_u32_e32 v140, s72, v216
	v_add_u32_e32 v156, s73, v216
	ds_read_b128 v[128:131], v140
	ds_read_b128 v[132:135], v140 offset:1024
	ds_read_b128 v[136:139], v140 offset:2048
	ds_read_b128 v[140:143], v140 offset:3072
	ds_read_b128 v[144:147], v156
	ds_read_b128 v[148:151], v156 offset:1024
	ds_read_b128 v[152:155], v156 offset:2048
	ds_read_b128 v[156:159], v156 offset:3072
	s_add_u32 s16, s16, 0x80000
	s_addc_u32 s17, s17, 0
	s_mov_b32 m0, s29
	ds_read_b128 v[160:163], v220 offset:32768
	ds_read_b128 v[164:167], v220 offset:33792
	ds_read_b128 v[168:171], v220 offset:34816
	ds_read_b128 v[172:175], v220 offset:35840
	ds_read_b128 v[196:199], v220 offset:36864
	ds_read_b128 v[202:205], v220 offset:37888
	ds_read_b128 v[206:209], v220 offset:38912
	ds_read_b128 v[232:235], v220 offset:39936
	global_load_lds_dwordx4 v180, s[16:17]
	s_mov_b32 m0, s34
	s_nop 0
	global_load_lds_dwordx4 v184, s[16:17]
	s_waitcnt vmcnt(8)
	s_waitcnt lgkmcnt(0)
	s_setprio 1
	s_barrier
	v_mfma_f32_16x16x32_bf16 v[124:127], v[128:131], v[160:163], v[124:127]
	v_mfma_f32_16x16x32_bf16 v[124:127], v[132:135], v[164:167], v[124:127]
	v_mfma_f32_16x16x32_bf16 v[108:111], v[128:131], v[168:171], v[108:111]
	v_mfma_f32_16x16x32_bf16 v[108:111], v[132:135], v[172:175], v[108:111]
	v_mfma_f32_16x16x32_bf16 v[92:95], v[128:131], v[196:199], v[92:95]
	v_mfma_f32_16x16x32_bf16 v[92:95], v[132:135], v[202:205], v[92:95]
	v_mfma_f32_16x16x32_bf16 v[76:79], v[128:131], v[206:209], v[76:79]
	v_mfma_f32_16x16x32_bf16 v[76:79], v[132:135], v[232:235], v[76:79]
	v_mfma_f32_16x16x32_bf16 v[120:123], v[136:139], v[160:163], v[120:123]
	v_mfma_f32_16x16x32_bf16 v[120:123], v[140:143], v[164:167], v[120:123]
	v_mfma_f32_16x16x32_bf16 v[104:107], v[136:139], v[168:171], v[104:107]
	v_mfma_f32_16x16x32_bf16 v[104:107], v[140:143], v[172:175], v[104:107]
	v_mfma_f32_16x16x32_bf16 v[88:91], v[136:139], v[196:199], v[88:91]
	v_mfma_f32_16x16x32_bf16 v[88:91], v[140:143], v[202:205], v[88:91]
	v_mfma_f32_16x16x32_bf16 v[72:75], v[136:139], v[206:209], v[72:75]
	v_mfma_f32_16x16x32_bf16 v[72:75], v[140:143], v[232:235], v[72:75]
	s_setprio 0
	s_setprio 1
	v_mfma_f32_16x16x32_bf16 v[116:119], v[144:147], v[160:163], v[116:119]
	v_mfma_f32_16x16x32_bf16 v[116:119], v[148:151], v[164:167], v[116:119]
	v_mfma_f32_16x16x32_bf16 v[100:103], v[144:147], v[168:171], v[100:103]
	v_mfma_f32_16x16x32_bf16 v[100:103], v[148:151], v[172:175], v[100:103]
	v_mfma_f32_16x16x32_bf16 v[84:87], v[144:147], v[196:199], v[84:87]
	v_mfma_f32_16x16x32_bf16 v[84:87], v[148:151], v[202:205], v[84:87]
	v_mfma_f32_16x16x32_bf16 v[68:71], v[144:147], v[206:209], v[68:71]
	v_mfma_f32_16x16x32_bf16 v[68:71], v[148:151], v[232:235], v[68:71]
	v_mfma_f32_16x16x32_bf16 v[112:115], v[152:155], v[160:163], v[112:115]
	v_mfma_f32_16x16x32_bf16 v[112:115], v[156:159], v[164:167], v[112:115]
	v_mfma_f32_16x16x32_bf16 v[96:99], v[152:155], v[168:171], v[96:99]
	v_mfma_f32_16x16x32_bf16 v[96:99], v[156:159], v[172:175], v[96:99]
	v_mfma_f32_16x16x32_bf16 v[80:83], v[152:155], v[196:199], v[80:83]
	v_mfma_f32_16x16x32_bf16 v[80:83], v[156:159], v[202:205], v[80:83]
	v_mfma_f32_16x16x32_bf16 v[64:67], v[152:155], v[206:209], v[64:67]
	v_mfma_f32_16x16x32_bf16 v[64:67], v[156:159], v[232:235], v[64:67]
	s_barrier
	s_setprio 0
	s_add_i32 s16, s72, s26
	s_mov_b32 m0, s16
	ds_read_b128 v[160:163], v220 offset:49152
	ds_read_b128 v[164:167], v220 offset:50176
	ds_read_b128 v[168:171], v220 offset:51200
	ds_read_b128 v[172:175], v220 offset:52224
	ds_read_b128 v[196:199], v220 offset:53248
	ds_read_b128 v[202:205], v220 offset:54272
	ds_read_b128 v[206:209], v220 offset:55296
	ds_read_b128 v[232:235], v220 offset:56320
	global_load_lds_dwordx4 v182, s[98:99]
	s_add_i32 m0, s16, 0x2000
	s_add_u32 s14, s14, 0x80080
	s_addc_u32 s15, s15, 0
	s_add_i32 s16, s73, s26
	global_load_lds_dwordx4 v186, s[98:99]
	s_mov_b32 m0, s16
	s_nop 0
	global_load_lds_dwordx4 v182, s[14:15]
	s_add_i32 m0, s16, 0x2000
	s_nop 0
	global_load_lds_dwordx4 v186, s[14:15]
	s_mov_b32 m0, s44
	s_nop 0
	global_load_lds_dwordx4 v180, s[100:101]
	s_mov_b32 m0, s45
	s_nop 0
	global_load_lds_dwordx4 v184, s[100:101]
	s_waitcnt vmcnt(8)
	s_waitcnt lgkmcnt(0)
	s_setprio 1
	s_barrier
	v_mfma_f32_16x16x32_bf16 v[60:63], v[128:131], v[160:163], v[60:63]
	v_mfma_f32_16x16x32_bf16 v[60:63], v[132:135], v[164:167], v[60:63]
	v_mfma_f32_16x16x32_bf16 v[44:47], v[128:131], v[168:171], v[44:47]
	v_mfma_f32_16x16x32_bf16 v[44:47], v[132:135], v[172:175], v[44:47]
	v_mfma_f32_16x16x32_bf16 v[28:31], v[128:131], v[196:199], v[28:31]
	v_mfma_f32_16x16x32_bf16 v[28:31], v[132:135], v[202:205], v[28:31]
	v_mfma_f32_16x16x32_bf16 v[12:15], v[128:131], v[206:209], v[12:15]
	v_mfma_f32_16x16x32_bf16 v[12:15], v[132:135], v[232:235], v[12:15]
	v_mfma_f32_16x16x32_bf16 v[56:59], v[136:139], v[160:163], v[56:59]
	v_mfma_f32_16x16x32_bf16 v[56:59], v[140:143], v[164:167], v[56:59]
	v_mfma_f32_16x16x32_bf16 v[40:43], v[136:139], v[168:171], v[40:43]
	v_mfma_f32_16x16x32_bf16 v[40:43], v[140:143], v[172:175], v[40:43]
	v_mfma_f32_16x16x32_bf16 v[24:27], v[136:139], v[196:199], v[24:27]
	v_mfma_f32_16x16x32_bf16 v[24:27], v[140:143], v[202:205], v[24:27]
	v_mfma_f32_16x16x32_bf16 v[8:11], v[136:139], v[206:209], v[8:11]
	v_mfma_f32_16x16x32_bf16 v[8:11], v[140:143], v[232:235], v[8:11]
	s_setprio 0
	s_setprio 1
	v_mfma_f32_16x16x32_bf16 v[52:55], v[144:147], v[160:163], v[52:55]
	v_mfma_f32_16x16x32_bf16 v[52:55], v[148:151], v[164:167], v[52:55]
	v_mfma_f32_16x16x32_bf16 v[36:39], v[144:147], v[168:171], v[36:39]
	v_mfma_f32_16x16x32_bf16 v[36:39], v[148:151], v[172:175], v[36:39]
	v_mfma_f32_16x16x32_bf16 v[20:23], v[144:147], v[196:199], v[20:23]
	v_mfma_f32_16x16x32_bf16 v[20:23], v[148:151], v[202:205], v[20:23]
	v_mfma_f32_16x16x32_bf16 v[4:7], v[144:147], v[206:209], v[4:7]
	v_mfma_f32_16x16x32_bf16 v[4:7], v[148:151], v[232:235], v[4:7]
	v_mfma_f32_16x16x32_bf16 v[48:51], v[152:155], v[160:163], v[48:51]
	v_mfma_f32_16x16x32_bf16 v[48:51], v[156:159], v[164:167], v[48:51]
	v_mfma_f32_16x16x32_bf16 v[32:35], v[152:155], v[168:171], v[32:35]
	v_mfma_f32_16x16x32_bf16 v[32:35], v[156:159], v[172:175], v[32:35]
	v_mfma_f32_16x16x32_bf16 v[16:19], v[152:155], v[196:199], v[16:19]
	v_mfma_f32_16x16x32_bf16 v[16:19], v[156:159], v[202:205], v[16:19]
	v_mfma_f32_16x16x32_bf16 v[0:3], v[152:155], v[206:209], v[0:3]
	v_mfma_f32_16x16x32_bf16 v[0:3], v[156:159], v[232:235], v[0:3]
	s_barrier
	s_setprio 0
	s_add_i32 s71, s71, 2
	s_add_u32 s68, s68, 0x100
	s_addc_u32 s69, s69, 0
	s_add_u32 s67, s67, 0x100
	s_addc_u32 s70, s70, 0
	s_cmp_gt_u32 s71, 29
	s_cbranch_scc0 .LBB0_896
	s_and_b64 vcc, exec, s[38:39]
	s_cbranch_vccz .LBB0_899
	s_barrier

;     __device__ bool next(int i, Unit& u) const { if (!base.next(i >> 1, u)) return false; u.sub = i & 1; return true; }
; #define PG8_STAGE(bufoff, gbase, voff) do { _Pragma("unroll") for (int _i = 0; _i < 2; ++_i) \
;         __builtin_amdgcn_global_load_lds((const unsigned*)((const char*)(gbase) + (voff)[_i]), (PG8_LAS unsigned*)(lds + (bufoff) + ldsw + _i * 8192), 16, 0, 0); } while (0)
; #define PG8_LDA(dst, b, h) do { _Pragma("unroll") for (int m = 0; m < 4; ++m) _Pragma("unroll") for (int k = 0; k < 2; ++k) dst[m][k] = *(const PG8_LAS bf16x8*)(lds + PG8_SA(b, h) + aoff + m * 2048 + k * 1024); } while (0)
; #define PG8_LDB(dst, b, h) do { _Pragma("unroll") for (int n = 0; n < 2; ++n) _Pragma("unroll") for (int k = 0; k < 2; ++k) dst[n][k] = *(const PG8_LAS bf16x8*)(lds + PG8_SB(b, h) + boff + n * 2048 + k * 1024); } while (0)
; #define PG8_WAIT_V(n) asm volatile("s_waitcnt vmcnt(" #n ")" ::: "memory")
; template <class Epi, class Sched, bool ALIGN_EPI = false, bool SP2 = false, bool DUAL = false>
; __device__ __forceinline__ void gemm_phase(PG8_LAS unsigned char* lds, const Gemm g, const Sched& S, const Epi& E) {
;     ...
;         const bool has_next = S.next(ui + 1, nxt);
;         const char* nA = has_next ? (const char*)((DUAL && nxt.sub) ? g.A2 : g.A) + (size_t)nxt.pm * tstep : cA; const char* nB = has_next ? (const char*)((DUAL && nxt.sub) ? g.Bt2 : g.Bt) + (size_t)nxt.pn * tstep : cB;
;         for (int t = 0; t < nt; t += 2) {
;             const bool last = (t == nt - 2);
;             const char* a1 = cA + (size_t)(t + 1) * kstep;
;             const char* a2 = last ? nA : cA + (size_t)(t + 2) * kstep; const char* b2 = last ? nB : cB + (size_t)(t + 2) * kstep;
;             const char* a3 = a2 + kstep; const char* b3 = b2 + kstep;
;             if (last && has_next) S.a_ready(nxt);
;             if constexpr (SP2) {
;             PG8_LDB(B0, 0, 0); PG8_LDB(B1, 0, 1); PG8_SCHED; PG8_LDA(At, 0, 0); PG8_STAGE(PG8_SA(1, 1), a1 + hstep, voffA);
;             PG8_WAIT_V(8); PG8_WAIT_L(0); PG8_BAR; PG8_MMA(0, 0, At, B0); PG8_MMA(0, 1, At, B1); PG8_BAR; PG8_SCHED;
;             PG8_LDA(At, 0, 1); PG8_STAGE(PG8_SB(0, 0), b2, voffB); PG8_STAGE(PG8_SB(0, 1), b2 + hstep, voffB); PG8_STAGE(PG8_SA(0, 0), a2, voffA);
;             PG8_WAIT_V(8); PG8_WAIT_L(0); PG8_BAR; PG8_MMA(1, 0, At, B0); PG8_MMA(1, 1, At, B1); PG8_BAR; PG8_SCHED;
.LBB0_991:
	s_ashr_i32 s25, s24, 31
	s_lshl_b64 s[28:29], s[24:25], 20
	s_add_u32 s30, s19, s28
	s_addc_u32 s31, s21, s29
	s_and_b64 s[28:29], s[4:5], exec
	s_cselect_b32 s25, s31, s27
	s_cselect_b32 s28, s30, s26
	s_ashr_i32 s23, s22, 31
	s_lshl_b64 s[36:37], s[22:23], 20
	s_add_u32 s36, s8, s36
	s_addc_u32 s37, s9, s37
	s_and_b64 s[40:41], s[4:5], exec
	s_cselect_b32 s23, s37, s15
	s_cselect_b32 s29, s36, s14
	s_add_u32 s40, s26, 0x80080
	s_addc_u32 s41, s27, 0
	s_add_u32 s63, s14, 0x100
	s_addc_u32 s64, s15, 0
	s_mov_b32 s65, -2
	s_add_u32 s14, s40, 0xfff80080
	s_addc_u32 s15, s41, -1
	s_cmp_eq_u32 s65, 28
	s_cselect_b32 s27, s25, s15
	s_cselect_b32 s26, s28, s14
	s_cselect_b32 s15, s23, s64
	s_cselect_b32 s14, s29, s63
	s_waitcnt vmcnt(8)
	s_waitcnt lgkmcnt(0)
	s_setprio 1
	s_barrier
	v_mfma_f32_16x16x32_bf16 v[124:127], v[128:131], v[160:163], 0
	v_mfma_f32_16x16x32_bf16 v[124:127], v[132:135], v[164:167], v[124:127]
	v_mfma_f32_16x16x32_bf16 v[108:111], v[128:131], v[188:191], 0
	v_mfma_f32_16x16x32_bf16 v[108:111], v[132:135], v[192:195], v[108:111]
	v_mfma_f32_16x16x32_bf16 v[92:95], v[128:131], v[196:199], 0
	v_mfma_f32_16x16x32_bf16 v[92:95], v[132:135], v[202:205], v[92:95]
	v_mfma_f32_16x16x32_bf16 v[76:79], v[128:131], v[206:209], 0
	v_mfma_f32_16x16x32_bf16 v[76:79], v[132:135], v[220:223], v[76:79]
	v_mfma_f32_16x16x32_bf16 v[120:123], v[136:139], v[160:163], 0
	v_mfma_f32_16x16x32_bf16 v[120:123], v[140:143], v[164:167], v[120:123]
	v_mfma_f32_16x16x32_bf16 v[104:107], v[136:139], v[188:191], 0
	v_mfma_f32_16x16x32_bf16 v[104:107], v[140:143], v[192:195], v[104:107]
	v_mfma_f32_16x16x32_bf16 v[88:91], v[136:139], v[196:199], 0
	v_mfma_f32_16x16x32_bf16 v[88:91], v[140:143], v[202:205], v[88:91]
	v_mfma_f32_16x16x32_bf16 v[72:75], v[136:139], v[206:209], 0
	v_mfma_f32_16x16x32_bf16 v[72:75], v[140:143], v[220:223], v[72:75]
	s_setprio 0
	s_setprio 1
	v_mfma_f32_16x16x32_bf16 v[116:119], v[144:147], v[160:163], 0
	v_mfma_f32_16x16x32_bf16 v[116:119], v[148:151], v[164:167], v[116:119]
	v_mfma_f32_16x16x32_bf16 v[100:103], v[144:147], v[188:191], 0
	v_mfma_f32_16x16x32_bf16 v[100:103], v[148:151], v[192:195], v[100:103]
	v_mfma_f32_16x16x32_bf16 v[84:87], v[144:147], v[196:199], 0
	v_mfma_f32_16x16x32_bf16 v[84:87], v[148:151], v[202:205], v[84:87]
	v_mfma_f32_16x16x32_bf16 v[68:71], v[144:147], v[206:209], 0
	v_mfma_f32_16x16x32_bf16 v[68:71], v[148:151], v[220:223], v[68:71]
	v_mfma_f32_16x16x32_bf16 v[112:115], v[152:155], v[160:163], 0
	v_mfma_f32_16x16x32_bf16 v[112:115], v[156:159], v[164:167], v[112:115]
	v_mfma_f32_16x16x32_bf16 v[96:99], v[152:155], v[188:191], 0
	v_mfma_f32_16x16x32_bf16 v[96:99], v[156:159], v[192:195], v[96:99]
	v_mfma_f32_16x16x32_bf16 v[80:83], v[152:155], v[196:199], 0
	v_mfma_f32_16x16x32_bf16 v[80:83], v[156:159], v[202:205], v[80:83]
	v_mfma_f32_16x16x32_bf16 v[64:67], v[152:155], v[206:209], 0
	v_mfma_f32_16x16x32_bf16 v[64:67], v[156:159], v[220:223], v[64:67]
	s_barrier
	s_setprio 0
	s_add_u32 s98, s14, 0x80
	s_addc_u32 s99, s15, 0
	s_add_u32 s100, s26, 0x80
	s_addc_u32 s101, s27, 0
	s_add_i32 m0, s39, 0xc000
	s_nop 0
	global_load_lds_dwordx4 v180, s[40:41]
	s_add_i32 m0, s39, 0xe000
	s_nop 0
	global_load_lds_dwordx4 v182, s[40:41]
	s_add_i32 s66, s50, s34
	s_mov_b32 m0, s66
	ds_read_b128 v[160:163], v217 offset:16384
	ds_read_b128 v[164:167], v217 offset:17408
	ds_read_b128 v[188:191], v217 offset:18432
	ds_read_b128 v[192:195], v217 offset:19456
	ds_read_b128 v[196:199], v217 offset:20480
	ds_read_b128 v[202:205], v217 offset:21504
	ds_read_b128 v[206:209], v217 offset:22528
	ds_read_b128 v[220:223], v217 offset:23552
	global_load_lds_dwordx4 v170, s[14:15]
	s_add_i32 m0, s66, 0x2000
	s_add_u32 s66, s14, 0x80000
	s_addc_u32 s67, s15, 0
	s_add_i32 s68, s51, s34
	global_load_lds_dwordx4 v174, s[14:15]
	s_mov_b32 m0, s68
	s_nop 0
	global_load_lds_dwordx4 v170, s[66:67]
	s_add_i32 m0, s68, 0x2000
	s_nop 0
	global_load_lds_dwordx4 v174, s[66:67]
	s_mov_b32 m0, s39
	s_nop 0
	global_load_lds_dwordx4 v168, s[26:27]
	s_mov_b32 m0, s42
	s_nop 0
	global_load_lds_dwordx4 v172, s[26:27]
	s_waitcnt vmcnt(8)
	s_waitcnt lgkmcnt(0)
	s_setprio 1
	s_barrier
	v_mfma_f32_16x16x32_bf16 v[60:63], v[128:131], v[160:163], 0
	v_mfma_f32_16x16x32_bf16 v[60:63], v[132:135], v[164:167], v[60:63]
	v_mfma_f32_16x16x32_bf16 v[44:47], v[128:131], v[188:191], 0
	v_mfma_f32_16x16x32_bf16 v[44:47], v[132:135], v[192:195], v[44:47]
	v_mfma_f32_16x16x32_bf16 v[28:31], v[128:131], v[196:199], 0
	v_mfma_f32_16x16x32_bf16 v[28:31], v[132:135], v[202:205], v[28:31]
	v_mfma_f32_16x16x32_bf16 v[12:15], v[128:131], v[206:209], 0
	v_mfma_f32_16x16x32_bf16 v[12:15], v[132:135], v[220:223], v[12:15]
	v_mfma_f32_16x16x32_bf16 v[56:59], v[136:139], v[160:163], 0
	v_mfma_f32_16x16x32_bf16 v[56:59], v[140:143], v[164:167], v[56:59]
	v_mfma_f32_16x16x32_bf16 v[40:43], v[136:139], v[188:191], 0
	v_mfma_f32_16x16x32_bf16 v[40:43], v[140:143], v[192:195], v[40:43]
	v_mfma_f32_16x16x32_bf16 v[24:27], v[136:139], v[196:199], 0
	v_mfma_f32_16x16x32_bf16 v[24:27], v[140:143], v[202:205], v[24:27]
	v_mfma_f32_16x16x32_bf16 v[8:11], v[136:139], v[206:209], 0
	v_mfma_f32_16x16x32_bf16 v[8:11], v[140:143], v[220:223], v[8:11]
	s_setprio 0
	s_setprio 1
	v_mfma_f32_16x16x32_bf16 v[52:55], v[144:147], v[160:163], 0
	v_mfma_f32_16x16x32_bf16 v[52:55], v[148:151], v[164:167], v[52:55]
	v_mfma_f32_16x16x32_bf16 v[36:39], v[144:147], v[188:191], 0
	v_mfma_f32_16x16x32_bf16 v[36:39], v[148:151], v[192:195], v[36:39]
	v_mfma_f32_16x16x32_bf16 v[20:23], v[144:147], v[196:199], 0
	v_mfma_f32_16x16x32_bf16 v[20:23], v[148:151], v[202:205], v[20:23]
	v_mfma_f32_16x16x32_bf16 v[4:7], v[144:147], v[206:209], 0
	v_mfma_f32_16x16x32_bf16 v[4:7], v[148:151], v[220:223], v[4:7]
	v_mfma_f32_16x16x32_bf16 v[48:51], v[152:155], v[160:163], 0
	v_mfma_f32_16x16x32_bf16 v[48:51], v[156:159], v[164:167], v[48:51]
	v_mfma_f32_16x16x32_bf16 v[32:35], v[152:155], v[188:191], 0
	v_mfma_f32_16x16x32_bf16 v[32:35], v[156:159], v[192:195], v[32:35]
	v_mfma_f32_16x16x32_bf16 v[16:19], v[152:155], v[196:199], 0
	v_mfma_f32_16x16x32_bf16 v[16:19], v[156:159], v[202:205], v[16:19]
	v_mfma_f32_16x16x32_bf16 v[0:3], v[152:155], v[206:209], 0
	v_mfma_f32_16x16x32_bf16 v[0:3], v[156:159], v[220:223], v[0:3]
	s_barrier
; #define PG8_STAGE(bufoff, gbase, voff) do { _Pragma("unroll") for (int _i = 0; _i < 2; ++_i) \
;         __builtin_amdgcn_global_load_lds((const unsigned*)((const char*)(gbase) + (voff)[_i]), (PG8_LAS unsigned*)(lds + (bufoff) + ldsw + _i * 8192), 16, 0, 0); } while (0)
; #define PG8_LDA(dst, b, h) do { _Pragma("unroll") for (int m = 0; m < 4; ++m) _Pragma("unroll") for (int k = 0; k < 2; ++k) dst[m][k] = *(const PG8_LAS bf16x8*)(lds + PG8_SA(b, h) + aoff + m * 2048 + k * 1024); } while (0)
; #define PG8_LDB(dst, b, h) do { _Pragma("unroll") for (int n = 0; n < 2; ++n) _Pragma("unroll") for (int k = 0; k < 2; ++k) dst[n][k] = *(const PG8_LAS bf16x8*)(lds + PG8_SB(b, h) + boff + n * 2048 + k * 1024); } while (0)
; #define PG8_MMA(ai, bj, At, Bt) do { __builtin_amdgcn_s_setprio(1); _Pragma("unroll") for (int m = 0; m < 4; ++m) _Pragma("unroll") for (int n = 0; n < 2; ++n) _Pragma("unroll") for (int k = 0; k < 2; ++k) \
;         acc[ai][bj][m][n] = __builtin_amdgcn_mfma_f32_16x16x32_bf16(Bt[n][k], At[m][k], acc[ai][bj][m][n], 0, 0, 0); __builtin_amdgcn_s_setprio(0); } while (0)
; #define PG8_WAIT_V(n) asm volatile("s_waitcnt vmcnt(" #n ")" ::: "memory")
; #define PG8_WAIT_L(n) asm volatile("s_waitcnt lgkmcnt(" #n ")" ::: "memory")
; #define PG8_BAR __builtin_amdgcn_s_barrier()
; #define PG8_SCHED __builtin_amdgcn_sched_barrier(0)
; template <class Epi, class Sched, bool ALIGN_EPI = false, bool SP2 = false, bool DUAL = false>
; __device__ __forceinline__ void gemm_phase(PG8_LAS unsigned char* lds, const Gemm g, const Sched& S, const Epi& E) {
;     ...
;             PG8_LDB(B0, 1, 0); PG8_LDB(B1, 1, 1); PG8_SCHED; PG8_LDA(At, 1, 0); PG8_STAGE(PG8_SA(0, 1), a2 + hstep, voffA);
;             PG8_WAIT_V(8); PG8_WAIT_L(0); PG8_BAR; PG8_MMA(0, 0, At, B0); PG8_MMA(0, 1, At, B1); PG8_BAR; PG8_SCHED;
;             PG8_LDA(At, 1, 1); PG8_STAGE(PG8_SB(1, 0), b3, voffB); PG8_STAGE(PG8_SB(1, 1), b3 + hstep, voffB); PG8_STAGE(PG8_SA(1, 0), a3, voffA);
;             PG8_WAIT_V(8); PG8_WAIT_L(0); PG8_BAR; PG8_MMA(1, 0, At, B0); PG8_MMA(1, 1, At, B1); PG8_BAR; PG8_SCHED;
	s_setprio 0
	s_add_i32 s66, 0, 0x18000
	s_add_i32 s67, 0, 0x1c000
	v_add_u32_e32 v140, s66, v213
	v_add_u32_e32 v156, s67, v213
	ds_read_b128 v[128:131], v140
	ds_read_b128 v[132:135], v140 offset:1024
	ds_read_b128 v[136:139], v140 offset:2048
	ds_read_b128 v[140:143], v140 offset:3072
	ds_read_b128 v[144:147], v156
	ds_read_b128 v[148:151], v156 offset:1024
	ds_read_b128 v[152:155], v156 offset:2048
	ds_read_b128 v[156:159], v156 offset:3072
	s_add_u32 s26, s26, 0x80000
	s_addc_u32 s27, s27, 0
	s_mov_b32 m0, s43
	ds_read_b128 v[160:163], v217 offset:32768
	ds_read_b128 v[164:167], v217 offset:33792
	ds_read_b128 v[188:191], v217 offset:34816
	ds_read_b128 v[192:195], v217 offset:35840
	ds_read_b128 v[196:199], v217 offset:36864
	ds_read_b128 v[202:205], v217 offset:37888
	ds_read_b128 v[206:209], v217 offset:38912
	ds_read_b128 v[220:223], v217 offset:39936
	global_load_lds_dwordx4 v168, s[26:27]
	s_mov_b32 m0, s44
	s_nop 0
	global_load_lds_dwordx4 v172, s[26:27]
	s_waitcnt vmcnt(8)
	s_waitcnt lgkmcnt(0)
	s_setprio 1
	s_barrier
	v_mfma_f32_16x16x32_bf16 v[124:127], v[128:131], v[160:163], v[124:127]
	v_mfma_f32_16x16x32_bf16 v[124:127], v[132:135], v[164:167], v[124:127]
	v_mfma_f32_16x16x32_bf16 v[108:111], v[128:131], v[188:191], v[108:111]
	v_mfma_f32_16x16x32_bf16 v[108:111], v[132:135], v[192:195], v[108:111]
	v_mfma_f32_16x16x32_bf16 v[92:95], v[128:131], v[196:199], v[92:95]
	v_mfma_f32_16x16x32_bf16 v[92:95], v[132:135], v[202:205], v[92:95]
	v_mfma_f32_16x16x32_bf16 v[76:79], v[128:131], v[206:209], v[76:79]
	v_mfma_f32_16x16x32_bf16 v[76:79], v[132:135], v[220:223], v[76:79]
	v_mfma_f32_16x16x32_bf16 v[120:123], v[136:139], v[160:163], v[120:123]
	v_mfma_f32_16x16x32_bf16 v[120:123], v[140:143], v[164:167], v[120:123]
	v_mfma_f32_16x16x32_bf16 v[104:107], v[136:139], v[188:191], v[104:107]
	v_mfma_f32_16x16x32_bf16 v[104:107], v[140:143], v[192:195], v[104:107]
	v_mfma_f32_16x16x32_bf16 v[88:91], v[136:139], v[196:199], v[88:91]
	v_mfma_f32_16x16x32_bf16 v[88:91], v[140:143], v[202:205], v[88:91]
	v_mfma_f32_16x16x32_bf16 v[72:75], v[136:139], v[206:209], v[72:75]
	v_mfma_f32_16x16x32_bf16 v[72:75], v[140:143], v[220:223], v[72:75]
	s_setprio 0
	s_setprio 1
	v_mfma_f32_16x16x32_bf16 v[116:119], v[144:147], v[160:163], v[116:119]
	v_mfma_f32_16x16x32_bf16 v[116:119], v[148:151], v[164:167], v[116:119]
	v_mfma_f32_16x16x32_bf16 v[100:103], v[144:147], v[188:191], v[100:103]
	v_mfma_f32_16x16x32_bf16 v[100:103], v[148:151], v[192:195], v[100:103]
	v_mfma_f32_16x16x32_bf16 v[84:87], v[144:147], v[196:199], v[84:87]
	v_mfma_f32_16x16x32_bf16 v[84:87], v[148:151], v[202:205], v[84:87]
	v_mfma_f32_16x16x32_bf16 v[68:71], v[144:147], v[206:209], v[68:71]
	v_mfma_f32_16x16x32_bf16 v[68:71], v[148:151], v[220:223], v[68:71]
	v_mfma_f32_16x16x32_bf16 v[112:115], v[152:155], v[160:163], v[112:115]
	v_mfma_f32_16x16x32_bf16 v[112:115], v[156:159], v[164:167], v[112:115]
	v_mfma_f32_16x16x32_bf16 v[96:99], v[152:155], v[188:191], v[96:99]
	v_mfma_f32_16x16x32_bf16 v[96:99], v[156:159], v[192:195], v[96:99]
	v_mfma_f32_16x16x32_bf16 v[80:83], v[152:155], v[196:199], v[80:83]
	v_mfma_f32_16x16x32_bf16 v[80:83], v[156:159], v[202:205], v[80:83]
	v_mfma_f32_16x16x32_bf16 v[64:67], v[152:155], v[206:209], v[64:67]
	v_mfma_f32_16x16x32_bf16 v[64:67], v[156:159], v[220:223], v[64:67]
	s_barrier
	s_setprio 0
	s_add_i32 s26, s66, s34
	s_mov_b32 m0, s26
	ds_read_b128 v[160:163], v217 offset:49152
	ds_read_b128 v[164:167], v217 offset:50176
	ds_read_b128 v[188:191], v217 offset:51200
	ds_read_b128 v[192:195], v217 offset:52224
	ds_read_b128 v[196:199], v217 offset:53248
	ds_read_b128 v[202:205], v217 offset:54272
	ds_read_b128 v[206:209], v217 offset:55296
	ds_read_b128 v[220:223], v217 offset:56320
	global_load_lds_dwordx4 v170, s[98:99]
	s_add_i32 m0, s26, 0x2000
	s_add_u32 s14, s14, 0x80080
	s_addc_u32 s15, s15, 0
	s_add_i32 s26, s67, s34
	global_load_lds_dwordx4 v174, s[98:99]
	s_mov_b32 m0, s26
	s_nop 0
	global_load_lds_dwordx4 v170, s[14:15]
	s_add_i32 m0, s26, 0x2000
	s_nop 0
	global_load_lds_dwordx4 v174, s[14:15]
	s_mov_b32 m0, s47
	s_nop 0
	global_load_lds_dwordx4 v168, s[100:101]
	s_mov_b32 m0, s48
	s_nop 0
	global_load_lds_dwordx4 v172, s[100:101]
	s_waitcnt vmcnt(8)
	s_waitcnt lgkmcnt(0)
	s_setprio 1
	s_barrier
	v_mfma_f32_16x16x32_bf16 v[60:63], v[128:131], v[160:163], v[60:63]
	v_mfma_f32_16x16x32_bf16 v[60:63], v[132:135], v[164:167], v[60:63]
	v_mfma_f32_16x16x32_bf16 v[44:47], v[128:131], v[188:191], v[44:47]
	v_mfma_f32_16x16x32_bf16 v[44:47], v[132:135], v[192:195], v[44:47]
	v_mfma_f32_16x16x32_bf16 v[28:31], v[128:131], v[196:199], v[28:31]
	v_mfma_f32_16x16x32_bf16 v[28:31], v[132:135], v[202:205], v[28:31]
	v_mfma_f32_16x16x32_bf16 v[12:15], v[128:131], v[206:209], v[12:15]
	v_mfma_f32_16x16x32_bf16 v[12:15], v[132:135], v[220:223], v[12:15]
	v_mfma_f32_16x16x32_bf16 v[56:59], v[136:139], v[160:163], v[56:59]
	v_mfma_f32_16x16x32_bf16 v[56:59], v[140:143], v[164:167], v[56:59]
	v_mfma_f32_16x16x32_bf16 v[40:43], v[136:139], v[188:191], v[40:43]
	v_mfma_f32_16x16x32_bf16 v[40:43], v[140:143], v[192:195], v[40:43]
	v_mfma_f32_16x16x32_bf16 v[24:27], v[136:139], v[196:199], v[24:27]
	v_mfma_f32_16x16x32_bf16 v[24:27], v[140:143], v[202:205], v[24:27]
	v_mfma_f32_16x16x32_bf16 v[8:11], v[136:139], v[206:209], v[8:11]
	v_mfma_f32_16x16x32_bf16 v[8:11], v[140:143], v[220:223], v[8:11]
	s_setprio 0
	s_setprio 1
	v_mfma_f32_16x16x32_bf16 v[52:55], v[144:147], v[160:163], v[52:55]
	v_mfma_f32_16x16x32_bf16 v[52:55], v[148:151], v[164:167], v[52:55]
	v_mfma_f32_16x16x32_bf16 v[36:39], v[144:147], v[188:191], v[36:39]
	v_mfma_f32_16x16x32_bf16 v[36:39], v[148:151], v[192:195], v[36:39]
	v_mfma_f32_16x16x32_bf16 v[20:23], v[144:147], v[196:199], v[20:23]
	v_mfma_f32_16x16x32_bf16 v[20:23], v[148:151], v[202:205], v[20:23]
	v_mfma_f32_16x16x32_bf16 v[4:7], v[144:147], v[206:209], v[4:7]
	v_mfma_f32_16x16x32_bf16 v[4:7], v[148:151], v[220:223], v[4:7]
	v_mfma_f32_16x16x32_bf16 v[48:51], v[152:155], v[160:163], v[48:51]
	v_mfma_f32_16x16x32_bf16 v[48:51], v[156:159], v[164:167], v[48:51]
	v_mfma_f32_16x16x32_bf16 v[32:35], v[152:155], v[188:191], v[32:35]
	v_mfma_f32_16x16x32_bf16 v[32:35], v[156:159], v[192:195], v[32:35]
	v_mfma_f32_16x16x32_bf16 v[16:19], v[152:155], v[196:199], v[16:19]
	v_mfma_f32_16x16x32_bf16 v[16:19], v[156:159], v[202:205], v[16:19]
	v_mfma_f32_16x16x32_bf16 v[0:3], v[152:155], v[206:209], v[0:3]
	v_mfma_f32_16x16x32_bf16 v[0:3], v[156:159], v[220:223], v[0:3]
	s_barrier
	s_setprio 0
	s_add_i32 s65, s65, 2
	s_add_u32 s40, s40, 0x100
	s_addc_u32 s41, s41, 0
	s_add_u32 s63, s63, 0x100
	s_addc_u32 s64, s64, 0
; #define PG8_STAGE(bufoff, gbase, voff) do { _Pragma("unroll") for (int _i = 0; _i < 2; ++_i) \
;         __builtin_amdgcn_global_load_lds((const unsigned*)((const char*)(gbase) + (voff)[_i]), (PG8_LAS unsigned*)(lds + (bufoff) + ldsw + _i * 8192), 16, 0, 0); } while (0)
; #define PG8_LDA(dst, b, h) do { _Pragma("unroll") for (int m = 0; m < 4; ++m) _Pragma("unroll") for (int k = 0; k < 2; ++k) dst[m][k] = *(const PG8_LAS bf16x8*)(lds + PG8_SA(b, h) + aoff + m * 2048 + k * 1024); } while (0)
; #define PG8_LDB(dst, b, h) do { _Pragma("unroll") for (int n = 0; n < 2; ++n) _Pragma("unroll") for (int k = 0; k < 2; ++k) dst[n][k] = *(const PG8_LAS bf16x8*)(lds + PG8_SB(b, h) + boff + n * 2048 + k * 1024); } while (0)
; #define PG8_MMA(ai, bj, At, Bt) do { __builtin_amdgcn_s_setprio(1); _Pragma("unroll") for (int m = 0; m < 4; ++m) _Pragma("unroll") for (int n = 0; n < 2; ++n) _Pragma("unroll") for (int k = 0; k < 2; ++k) \
;         acc[ai][bj][m][n] = __builtin_amdgcn_mfma_f32_16x16x32_bf16(Bt[n][k], At[m][k], acc[ai][bj][m][n], 0, 0, 0); __builtin_amdgcn_s_setprio(0); } while (0)
; #define PG8_WAIT_V(n) asm volatile("s_waitcnt vmcnt(" #n ")" ::: "memory")
; #define PG8_BAR __builtin_amdgcn_s_barrier()
; template <class Epi, class Sched, bool ALIGN_EPI = false, bool SP2 = false, bool DUAL = false>
; __device__ __forceinline__ void gemm_phase(PG8_LAS unsigned char* lds, const Gemm g, const Sched& S, const Epi& E) {
;     ...
;         for (int t = 0; t < nt; t += 2) {
;             const bool last = (t == nt - 2);
;             const char* a1 = cA + (size_t)(t + 1) * kstep;
;             const char* a2 = last ? nA : cA + (size_t)(t + 2) * kstep; const char* b2 = last ? nB : cB + (size_t)(t + 2) * kstep;
;             const char* a3 = a2 + kstep; const char* b3 = b2 + kstep;
;             if (last && has_next) S.a_ready(nxt);
;             if constexpr (SP2) {
;             PG8_LDB(B0, 0, 0); PG8_LDB(B1, 0, 1); PG8_SCHED; PG8_LDA(At, 0, 0); PG8_STAGE(PG8_SA(1, 1), a1 + hstep, voffA);
;             PG8_WAIT_V(8); PG8_WAIT_L(0); PG8_BAR; PG8_MMA(0, 0, At, B0); PG8_MMA(0, 1, At, B1); PG8_BAR; PG8_SCHED;
;             PG8_LDA(At, 0, 1); PG8_STAGE(PG8_SB(0, 0), b2, voffB); PG8_STAGE(PG8_SB(0, 1), b2 + hstep, voffB); PG8_STAGE(PG8_SA(0, 0), a2, voffA);
;             PG8_WAIT_V(8); PG8_WAIT_L(0); PG8_BAR; PG8_MMA(1, 0, At, B0); PG8_MMA(1, 1, At, B1); PG8_BAR; PG8_SCHED;
.LBB0_992:
	ds_read_b128 v[128:131], v215
	ds_read_b128 v[132:135], v215 offset:1024
	ds_read_b128 v[136:139], v215 offset:2048
	ds_read_b128 v[140:143], v215 offset:3072
	ds_read_b128 v[144:147], v216
	ds_read_b128 v[148:151], v216 offset:1024
	ds_read_b128 v[152:155], v216 offset:2048
	ds_read_b128 v[156:159], v216 offset:3072
	s_add_u32 s14, s40, 0xfff80080
	s_addc_u32 s15, s41, -1
	s_cmp_eq_u32 s65, 28
	s_cselect_b32 s27, s25, s15
	s_cselect_b32 s26, s28, s14
	s_cselect_b32 s15, s23, s64
	s_cselect_b32 s14, s29, s63
	s_add_i32 m0, s39, 0xc000
	ds_read_b128 v[160:163], v217
	ds_read_b128 v[164:167], v217 offset:1024
	ds_read_b128 v[188:191], v217 offset:2048
	ds_read_b128 v[192:195], v217 offset:3072
	ds_read_b128 v[196:199], v217 offset:4096
	ds_read_b128 v[202:205], v217 offset:5120
	ds_read_b128 v[206:209], v217 offset:6144
	ds_read_b128 v[220:223], v217 offset:7168
	global_load_lds_dwordx4 v180, s[40:41]
	s_add_i32 m0, s39, 0xe000
	s_nop 0
	global_load_lds_dwordx4 v182, s[40:41]
	s_waitcnt vmcnt(8)
	s_waitcnt lgkmcnt(0)
	s_setprio 1
	s_barrier
	v_mfma_f32_16x16x32_bf16 v[124:127], v[128:131], v[160:163], v[124:127]
	v_mfma_f32_16x16x32_bf16 v[124:127], v[132:135], v[164:167], v[124:127]
	v_mfma_f32_16x16x32_bf16 v[108:111], v[128:131], v[188:191], v[108:111]
	v_mfma_f32_16x16x32_bf16 v[108:111], v[132:135], v[192:195], v[108:111]
	v_mfma_f32_16x16x32_bf16 v[92:95], v[128:131], v[196:199], v[92:95]
	v_mfma_f32_16x16x32_bf16 v[92:95], v[132:135], v[202:205], v[92:95]
	v_mfma_f32_16x16x32_bf16 v[76:79], v[128:131], v[206:209], v[76:79]
	v_mfma_f32_16x16x32_bf16 v[76:79], v[132:135], v[220:223], v[76:79]
	v_mfma_f32_16x16x32_bf16 v[120:123], v[136:139], v[160:163], v[120:123]
	v_mfma_f32_16x16x32_bf16 v[120:123], v[140:143], v[164:167], v[120:123]
	v_mfma_f32_16x16x32_bf16 v[104:107], v[136:139], v[188:191], v[104:107]
	v_mfma_f32_16x16x32_bf16 v[104:107], v[140:143], v[192:195], v[104:107]
	v_mfma_f32_16x16x32_bf16 v[88:91], v[136:139], v[196:199], v[88:91]
	v_mfma_f32_16x16x32_bf16 v[88:91], v[140:143], v[202:205], v[88:91]
	v_mfma_f32_16x16x32_bf16 v[72:75], v[136:139], v[206:209], v[72:75]
	v_mfma_f32_16x16x32_bf16 v[72:75], v[140:143], v[220:223], v[72:75]
	s_setprio 0
	s_setprio 1
	v_mfma_f32_16x16x32_bf16 v[116:119], v[144:147], v[160:163], v[116:119]
	v_mfma_f32_16x16x32_bf16 v[116:119], v[148:151], v[164:167], v[116:119]
	v_mfma_f32_16x16x32_bf16 v[100:103], v[144:147], v[188:191], v[100:103]
	v_mfma_f32_16x16x32_bf16 v[100:103], v[148:151], v[192:195], v[100:103]
	v_mfma_f32_16x16x32_bf16 v[84:87], v[144:147], v[196:199], v[84:87]
	v_mfma_f32_16x16x32_bf16 v[84:87], v[148:151], v[202:205], v[84:87]
	v_mfma_f32_16x16x32_bf16 v[68:71], v[144:147], v[206:209], v[68:71]
	v_mfma_f32_16x16x32_bf16 v[68:71], v[148:151], v[220:223], v[68:71]
	v_mfma_f32_16x16x32_bf16 v[112:115], v[152:155], v[160:163], v[112:115]
	v_mfma_f32_16x16x32_bf16 v[112:115], v[156:159], v[164:167], v[112:115]
	v_mfma_f32_16x16x32_bf16 v[96:99], v[152:155], v[188:191], v[96:99]
	v_mfma_f32_16x16x32_bf16 v[96:99], v[156:159], v[192:195], v[96:99]
	v_mfma_f32_16x16x32_bf16 v[80:83], v[152:155], v[196:199], v[80:83]
	v_mfma_f32_16x16x32_bf16 v[80:83], v[156:159], v[202:205], v[80:83]
	v_mfma_f32_16x16x32_bf16 v[64:67], v[152:155], v[206:209], v[64:67]
	v_mfma_f32_16x16x32_bf16 v[64:67], v[156:159], v[220:223], v[64:67]
	s_barrier
	s_setprio 0
	s_add_u32 s98, s14, 0x80
	s_addc_u32 s99, s15, 0
	s_add_u32 s100, s26, 0x80
	s_addc_u32 s101, s27, 0
	s_add_i32 s66, s50, s34
	s_mov_b32 m0, s66
	ds_read_b128 v[160:163], v217 offset:16384
	ds_read_b128 v[164:167], v217 offset:17408
	ds_read_b128 v[188:191], v217 offset:18432
	ds_read_b128 v[192:195], v217 offset:19456
	ds_read_b128 v[196:199], v217 offset:20480
	ds_read_b128 v[202:205], v217 offset:21504
	ds_read_b128 v[206:209], v217 offset:22528
	ds_read_b128 v[220:223], v217 offset:23552
	global_load_lds_dwordx4 v170, s[14:15]
	s_add_i32 m0, s66, 0x2000
	s_add_u32 s66, s14, 0x80000
	s_addc_u32 s67, s15, 0
	s_add_i32 s68, s51, s34
	global_load_lds_dwordx4 v174, s[14:15]
	s_mov_b32 m0, s68
	s_nop 0
	global_load_lds_dwordx4 v170, s[66:67]
	s_add_i32 m0, s68, 0x2000
	s_nop 0
	global_load_lds_dwordx4 v174, s[66:67]
	s_mov_b32 m0, s39
	s_nop 0
	global_load_lds_dwordx4 v168, s[26:27]
	s_mov_b32 m0, s42
	s_nop 0
	global_load_lds_dwordx4 v172, s[26:27]
	s_waitcnt vmcnt(8)
	s_waitcnt lgkmcnt(0)
	s_setprio 1
	s_barrier
	v_mfma_f32_16x16x32_bf16 v[60:63], v[128:131], v[160:163], v[60:63]
	v_mfma_f32_16x16x32_bf16 v[60:63], v[132:135], v[164:167], v[60:63]
	v_mfma_f32_16x16x32_bf16 v[44:47], v[128:131], v[188:191], v[44:47]
	v_mfma_f32_16x16x32_bf16 v[44:47], v[132:135], v[192:195], v[44:47]
	v_mfma_f32_16x16x32_bf16 v[28:31], v[128:131], v[196:199], v[28:31]
	v_mfma_f32_16x16x32_bf16 v[28:31], v[132:135], v[202:205], v[28:31]
	v_mfma_f32_16x16x32_bf16 v[12:15], v[128:131], v[206:209], v[12:15]
	v_mfma_f32_16x16x32_bf16 v[12:15], v[132:135], v[220:223], v[12:15]
	v_mfma_f32_16x16x32_bf16 v[56:59], v[136:139], v[160:163], v[56:59]
	v_mfma_f32_16x16x32_bf16 v[56:59], v[140:143], v[164:167], v[56:59]
	v_mfma_f32_16x16x32_bf16 v[40:43], v[136:139], v[188:191], v[40:43]
	v_mfma_f32_16x16x32_bf16 v[40:43], v[140:143], v[192:195], v[40:43]
	v_mfma_f32_16x16x32_bf16 v[24:27], v[136:139], v[196:199], v[24:27]
	v_mfma_f32_16x16x32_bf16 v[24:27], v[140:143], v[202:205], v[24:27]
	v_mfma_f32_16x16x32_bf16 v[8:11], v[136:139], v[206:209], v[8:11]
	v_mfma_f32_16x16x32_bf16 v[8:11], v[140:143], v[220:223], v[8:11]
	s_setprio 0
	s_setprio 1
	v_mfma_f32_16x16x32_bf16 v[52:55], v[144:147], v[160:163], v[52:55]
	v_mfma_f32_16x16x32_bf16 v[52:55], v[148:151], v[164:167], v[52:55]
	v_mfma_f32_16x16x32_bf16 v[36:39], v[144:147], v[188:191], v[36:39]
	v_mfma_f32_16x16x32_bf16 v[36:39], v[148:151], v[192:195], v[36:39]
	v_mfma_f32_16x16x32_bf16 v[20:23], v[144:147], v[196:199], v[20:23]
	v_mfma_f32_16x16x32_bf16 v[20:23], v[148:151], v[202:205], v[20:23]
	v_mfma_f32_16x16x32_bf16 v[4:7], v[144:147], v[206:209], v[4:7]
	v_mfma_f32_16x16x32_bf16 v[4:7], v[148:151], v[220:223], v[4:7]
	v_mfma_f32_16x16x32_bf16 v[48:51], v[152:155], v[160:163], v[48:51]
	v_mfma_f32_16x16x32_bf16 v[48:51], v[156:159], v[164:167], v[48:51]
	v_mfma_f32_16x16x32_bf16 v[32:35], v[152:155], v[188:191], v[32:35]
	v_mfma_f32_16x16x32_bf16 v[32:35], v[156:159], v[192:195], v[32:35]
	v_mfma_f32_16x16x32_bf16 v[16:19], v[152:155], v[196:199], v[16:19]
	v_mfma_f32_16x16x32_bf16 v[16:19], v[156:159], v[202:205], v[16:19]
	v_mfma_f32_16x16x32_bf16 v[0:3], v[152:155], v[206:209], v[0:3]
	v_mfma_f32_16x16x32_bf16 v[0:3], v[156:159], v[220:223], v[0:3]
	s_barrier
; #define PG8_STAGE(bufoff, gbase, voff) do { _Pragma("unroll") for (int _i = 0; _i < 2; ++_i) \
;         __builtin_amdgcn_global_load_lds((const unsigned*)((const char*)(gbase) + (voff)[_i]), (PG8_LAS unsigned*)(lds + (bufoff) + ldsw + _i * 8192), 16, 0, 0); } while (0)
; #define PG8_LDA(dst, b, h) do { _Pragma("unroll") for (int m = 0; m < 4; ++m) _Pragma("unroll") for (int k = 0; k < 2; ++k) dst[m][k] = *(const PG8_LAS bf16x8*)(lds + PG8_SA(b, h) + aoff + m * 2048 + k * 1024); } while (0)
; #define PG8_LDB(dst, b, h) do { _Pragma("unroll") for (int n = 0; n < 2; ++n) _Pragma("unroll") for (int k = 0; k < 2; ++k) dst[n][k] = *(const PG8_LAS bf16x8*)(lds + PG8_SB(b, h) + boff + n * 2048 + k * 1024); } while (0)
; #define PG8_MMA(ai, bj, At, Bt) do { __builtin_amdgcn_s_setprio(1); _Pragma("unroll") for (int m = 0; m < 4; ++m) _Pragma("unroll") for (int n = 0; n < 2; ++n) _Pragma("unroll") for (int k = 0; k < 2; ++k) \
;         acc[ai][bj][m][n] = __builtin_amdgcn_mfma_f32_16x16x32_bf16(Bt[n][k], At[m][k], acc[ai][bj][m][n], 0, 0, 0); __builtin_amdgcn_s_setprio(0); } while (0)
; #define PG8_WAIT_V(n) asm volatile("s_waitcnt vmcnt(" #n ")" ::: "memory")
; #define PG8_WAIT_L(n) asm volatile("s_waitcnt lgkmcnt(" #n ")" ::: "memory")
; #define PG8_BAR __builtin_amdgcn_s_barrier()
; #define PG8_SCHED __builtin_amdgcn_sched_barrier(0)
; template <class Epi, class Sched, bool ALIGN_EPI = false, bool SP2 = false, bool DUAL = false>
; __device__ __forceinline__ void gemm_phase(PG8_LAS unsigned char* lds, const Gemm g, const Sched& S, const Epi& E) {
;     ...
;             PG8_LDB(B0, 1, 0); PG8_LDB(B1, 1, 1); PG8_SCHED; PG8_LDA(At, 1, 0); PG8_STAGE(PG8_SA(0, 1), a2 + hstep, voffA);
;             PG8_WAIT_V(8); PG8_WAIT_L(0); PG8_BAR; PG8_MMA(0, 0, At, B0); PG8_MMA(0, 1, At, B1); PG8_BAR; PG8_SCHED;
;             PG8_LDA(At, 1, 1); PG8_STAGE(PG8_SB(1, 0), b3, voffB); PG8_STAGE(PG8_SB(1, 1), b3 + hstep, voffB); PG8_STAGE(PG8_SA(1, 0), a3, voffA);
;             PG8_WAIT_V(8); PG8_WAIT_L(0); PG8_BAR; PG8_MMA(1, 0, At, B0); PG8_MMA(1, 1, At, B1); PG8_BAR; PG8_SCHED;
	s_setprio 0
	s_add_i32 s66, 0, 0x18000
	s_add_i32 s67, 0, 0x1c000
	v_add_u32_e32 v140, s66, v213
	v_add_u32_e32 v156, s67, v213
	ds_read_b128 v[128:131], v140
	ds_read_b128 v[132:135], v140 offset:1024
	ds_read_b128 v[136:139], v140 offset:2048
	ds_read_b128 v[140:143], v140 offset:3072
	ds_read_b128 v[144:147], v156
	ds_read_b128 v[148:151], v156 offset:1024
	ds_read_b128 v[152:155], v156 offset:2048
	ds_read_b128 v[156:159], v156 offset:3072
	s_add_u32 s26, s26, 0x80000
	s_addc_u32 s27, s27, 0
	s_mov_b32 m0, s43
	ds_read_b128 v[160:163], v217 offset:32768
	ds_read_b128 v[164:167], v217 offset:33792
	ds_read_b128 v[188:191], v217 offset:34816
	ds_read_b128 v[192:195], v217 offset:35840
	ds_read_b128 v[196:199], v217 offset:36864
	ds_read_b128 v[202:205], v217 offset:37888
	ds_read_b128 v[206:209], v217 offset:38912
	ds_read_b128 v[220:223], v217 offset:39936
	global_load_lds_dwordx4 v168, s[26:27]
	s_mov_b32 m0, s44
	s_nop 0
	global_load_lds_dwordx4 v172, s[26:27]
	s_waitcnt vmcnt(8)
	s_waitcnt lgkmcnt(0)
	s_setprio 1
	s_barrier
	v_mfma_f32_16x16x32_bf16 v[124:127], v[128:131], v[160:163], v[124:127]
	v_mfma_f32_16x16x32_bf16 v[124:127], v[132:135], v[164:167], v[124:127]
	v_mfma_f32_16x16x32_bf16 v[108:111], v[128:131], v[188:191], v[108:111]
	v_mfma_f32_16x16x32_bf16 v[108:111], v[132:135], v[192:195], v[108:111]
	v_mfma_f32_16x16x32_bf16 v[92:95], v[128:131], v[196:199], v[92:95]
	v_mfma_f32_16x16x32_bf16 v[92:95], v[132:135], v[202:205], v[92:95]
	v_mfma_f32_16x16x32_bf16 v[76:79], v[128:131], v[206:209], v[76:79]
	v_mfma_f32_16x16x32_bf16 v[76:79], v[132:135], v[220:223], v[76:79]
	v_mfma_f32_16x16x32_bf16 v[120:123], v[136:139], v[160:163], v[120:123]
	v_mfma_f32_16x16x32_bf16 v[120:123], v[140:143], v[164:167], v[120:123]
	v_mfma_f32_16x16x32_bf16 v[104:107], v[136:139], v[188:191], v[104:107]
	v_mfma_f32_16x16x32_bf16 v[104:107], v[140:143], v[192:195], v[104:107]
	v_mfma_f32_16x16x32_bf16 v[88:91], v[136:139], v[196:199], v[88:91]
	v_mfma_f32_16x16x32_bf16 v[88:91], v[140:143], v[202:205], v[88:91]
	v_mfma_f32_16x16x32_bf16 v[72:75], v[136:139], v[206:209], v[72:75]
	v_mfma_f32_16x16x32_bf16 v[72:75], v[140:143], v[220:223], v[72:75]
	s_setprio 0
	s_setprio 1
	v_mfma_f32_16x16x32_bf16 v[116:119], v[144:147], v[160:163], v[116:119]
	v_mfma_f32_16x16x32_bf16 v[116:119], v[148:151], v[164:167], v[116:119]
	v_mfma_f32_16x16x32_bf16 v[100:103], v[144:147], v[188:191], v[100:103]
	v_mfma_f32_16x16x32_bf16 v[100:103], v[148:151], v[192:195], v[100:103]
	v_mfma_f32_16x16x32_bf16 v[84:87], v[144:147], v[196:199], v[84:87]
	v_mfma_f32_16x16x32_bf16 v[84:87], v[148:151], v[202:205], v[84:87]
	v_mfma_f32_16x16x32_bf16 v[68:71], v[144:147], v[206:209], v[68:71]
	v_mfma_f32_16x16x32_bf16 v[68:71], v[148:151], v[220:223], v[68:71]
	v_mfma_f32_16x16x32_bf16 v[112:115], v[152:155], v[160:163], v[112:115]
	v_mfma_f32_16x16x32_bf16 v[112:115], v[156:159], v[164:167], v[112:115]
	v_mfma_f32_16x16x32_bf16 v[96:99], v[152:155], v[188:191], v[96:99]
	v_mfma_f32_16x16x32_bf16 v[96:99], v[156:159], v[192:195], v[96:99]
	v_mfma_f32_16x16x32_bf16 v[80:83], v[152:155], v[196:199], v[80:83]
	v_mfma_f32_16x16x32_bf16 v[80:83], v[156:159], v[202:205], v[80:83]
	v_mfma_f32_16x16x32_bf16 v[64:67], v[152:155], v[206:209], v[64:67]
	v_mfma_f32_16x16x32_bf16 v[64:67], v[156:159], v[220:223], v[64:67]
	s_barrier
	s_setprio 0
	s_add_i32 s26, s66, s34
	s_mov_b32 m0, s26
	ds_read_b128 v[160:163], v217 offset:49152
	ds_read_b128 v[164:167], v217 offset:50176
	ds_read_b128 v[188:191], v217 offset:51200
	ds_read_b128 v[192:195], v217 offset:52224
	ds_read_b128 v[196:199], v217 offset:53248
	ds_read_b128 v[202:205], v217 offset:54272
	ds_read_b128 v[206:209], v217 offset:55296
	ds_read_b128 v[220:223], v217 offset:56320
	global_load_lds_dwordx4 v170, s[98:99]
	s_add_i32 m0, s26, 0x2000
	s_add_u32 s14, s14, 0x80080
	s_addc_u32 s15, s15, 0
	s_add_i32 s26, s67, s34
	global_load_lds_dwordx4 v174, s[98:99]
	s_mov_b32 m0, s26
	s_nop 0
	global_load_lds_dwordx4 v170, s[14:15]
	s_add_i32 m0, s26, 0x2000
	s_nop 0
	global_load_lds_dwordx4 v174, s[14:15]
	s_mov_b32 m0, s47
	s_nop 0
	global_load_lds_dwordx4 v168, s[100:101]
	s_mov_b32 m0, s48
	s_nop 0
	global_load_lds_dwordx4 v172, s[100:101]
	s_waitcnt vmcnt(8)
	s_waitcnt lgkmcnt(0)
	s_setprio 1
	s_barrier
; #define PG8_STAGE(bufoff, gbase, voff) do { _Pragma("unroll") for (int _i = 0; _i < 2; ++_i) \
;         __builtin_amdgcn_global_load_lds((const unsigned*)((const char*)(gbase) + (voff)[_i]), (PG8_LAS unsigned*)(lds + (bufoff) + ldsw + _i * 8192), 16, 0, 0); } while (0)
; #define PG8_LDA(dst, b, h) do { _Pragma("unroll") for (int m = 0; m < 4; ++m) _Pragma("unroll") for (int k = 0; k < 2; ++k) dst[m][k] = *(const PG8_LAS bf16x8*)(lds + PG8_SA(b, h) + aoff + m * 2048 + k * 1024); } while (0)
; #define PG8_MMA(ai, bj, At, Bt) do { __builtin_amdgcn_s_setprio(1); _Pragma("unroll") for (int m = 0; m < 4; ++m) _Pragma("unroll") for (int n = 0; n < 2; ++n) _Pragma("unroll") for (int k = 0; k < 2; ++k) \
;         acc[ai][bj][m][n] = __builtin_amdgcn_mfma_f32_16x16x32_bf16(Bt[n][k], At[m][k], acc[ai][bj][m][n], 0, 0, 0); __builtin_amdgcn_s_setprio(0); } while (0)
; #define PG8_WAIT_V(n) asm volatile("s_waitcnt vmcnt(" #n ")" ::: "memory")
; #define PG8_WAIT_L(n) asm volatile("s_waitcnt lgkmcnt(" #n ")" ::: "memory")
; #define PG8_BAR __builtin_amdgcn_s_barrier()
; #define PG8_SCHED __builtin_amdgcn_sched_barrier(0)
; template <class Epi, class Sched, bool ALIGN_EPI = false, bool SP2 = false, bool DUAL = false>
; __device__ __forceinline__ void gemm_phase(PG8_LAS unsigned char* lds, const Gemm g, const Sched& S, const Epi& E) {
;     ...
;             PG8_WAIT_V(8); PG8_WAIT_L(0); PG8_BAR; PG8_MMA(0, 0, At, B0); PG8_MMA(0, 1, At, B1); PG8_BAR; PG8_SCHED;
;             PG8_LDA(At, 1, 1); PG8_STAGE(PG8_SB(1, 0), b3, voffB); PG8_STAGE(PG8_SB(1, 1), b3 + hstep, voffB); PG8_STAGE(PG8_SA(1, 0), a3, voffA);
;             PG8_WAIT_V(8); PG8_WAIT_L(0); PG8_BAR; PG8_MMA(1, 0, At, B0); PG8_MMA(1, 1, At, B1); PG8_BAR; PG8_SCHED;
;     __device__ __forceinline__ void operator()(const f32x4 (&acc)[2][2][4][2], const Unit& u, int wr, int wc, int fr, int fq) const {
;         const int rowb = u.pm * BM + wr * 64 + fr, col = u.pn * HALF + wc * 32 + fq * 8;
;         f32x4 p[2][4][2];
; #pragma unroll
;         for (int ai = 0; ai < 2; ++ai)
; #pragma unroll
;             for (int m = 0; m < 4; ++m) { const float* sp = ss2 + (size_t)(rowb + ai * HALF + m * 16) * 32 + fq * 8; p[ai][m][0] = *(const f32x4*)sp; p[ai][m][1] = *(const f32x4*)(sp + 4); }
	v_mfma_f32_16x16x32_bf16 v[60:63], v[128:131], v[160:163], v[60:63]
	v_mfma_f32_16x16x32_bf16 v[60:63], v[132:135], v[164:167], v[60:63]
	v_mfma_f32_16x16x32_bf16 v[44:47], v[128:131], v[188:191], v[44:47]
	v_mfma_f32_16x16x32_bf16 v[44:47], v[132:135], v[192:195], v[44:47]
	v_mfma_f32_16x16x32_bf16 v[28:31], v[128:131], v[196:199], v[28:31]
	v_mfma_f32_16x16x32_bf16 v[28:31], v[132:135], v[202:205], v[28:31]
	v_mfma_f32_16x16x32_bf16 v[12:15], v[128:131], v[206:209], v[12:15]
	v_mfma_f32_16x16x32_bf16 v[12:15], v[132:135], v[220:223], v[12:15]
	v_mfma_f32_16x16x32_bf16 v[56:59], v[136:139], v[160:163], v[56:59]
	v_mfma_f32_16x16x32_bf16 v[56:59], v[140:143], v[164:167], v[56:59]
	v_mfma_f32_16x16x32_bf16 v[40:43], v[136:139], v[188:191], v[40:43]
	v_mfma_f32_16x16x32_bf16 v[40:43], v[140:143], v[192:195], v[40:43]
	v_mfma_f32_16x16x32_bf16 v[24:27], v[136:139], v[196:199], v[24:27]
	v_mfma_f32_16x16x32_bf16 v[24:27], v[140:143], v[202:205], v[24:27]
	v_mfma_f32_16x16x32_bf16 v[8:11], v[136:139], v[206:209], v[8:11]
	v_mfma_f32_16x16x32_bf16 v[8:11], v[140:143], v[220:223], v[8:11]
	s_setprio 0
	s_setprio 1
	v_mfma_f32_16x16x32_bf16 v[52:55], v[144:147], v[160:163], v[52:55]
	v_mfma_f32_16x16x32_bf16 v[52:55], v[148:151], v[164:167], v[52:55]
	v_mfma_f32_16x16x32_bf16 v[36:39], v[144:147], v[188:191], v[36:39]
	v_mfma_f32_16x16x32_bf16 v[36:39], v[148:151], v[192:195], v[36:39]
	v_mfma_f32_16x16x32_bf16 v[20:23], v[144:147], v[196:199], v[20:23]
	v_mfma_f32_16x16x32_bf16 v[20:23], v[148:151], v[202:205], v[20:23]
	v_mfma_f32_16x16x32_bf16 v[4:7], v[144:147], v[206:209], v[4:7]
	v_mfma_f32_16x16x32_bf16 v[4:7], v[148:151], v[220:223], v[4:7]
	v_mfma_f32_16x16x32_bf16 v[48:51], v[152:155], v[160:163], v[48:51]
	v_mfma_f32_16x16x32_bf16 v[48:51], v[156:159], v[164:167], v[48:51]
	v_mfma_f32_16x16x32_bf16 v[32:35], v[152:155], v[188:191], v[32:35]
	v_mfma_f32_16x16x32_bf16 v[32:35], v[156:159], v[192:195], v[32:35]
	v_mfma_f32_16x16x32_bf16 v[16:19], v[152:155], v[196:199], v[16:19]
	v_mfma_f32_16x16x32_bf16 v[16:19], v[156:159], v[202:205], v[16:19]
	v_mfma_f32_16x16x32_bf16 v[0:3], v[152:155], v[206:209], v[0:3]
	v_mfma_f32_16x16x32_bf16 v[0:3], v[156:159], v[220:223], v[0:3]
	s_barrier
	s_setprio 0
	s_add_i32 s65, s65, 2
	s_add_u32 s40, s40, 0x100
	s_addc_u32 s41, s41, 0
	s_add_u32 s63, s63, 0x100
	s_addc_u32 s64, s64, 0
	s_cmp_gt_u32 s65, 29
	s_cbranch_scc0 .LBB0_992
	v_lshl_add_u32 v144, s38, 8, v212
	v_ashrrev_i32_e32 v145, 31, v144
	v_or_b32_e32 v206, 16, v144
	v_lshlrev_b64 v[128:129], 7, v[144:145]
	v_ashrrev_i32_e32 v207, 31, v206
	v_lshl_add_u64 v[132:133], v[178:179], 0, v[128:129]
	v_lshlrev_b64 v[136:137], 7, v[206:207]
	global_load_dwordx4 v[128:131], v[132:133], off
	s_nop 0
	global_load_dwordx4 v[132:135], v[132:133], off offset:16
	v_lshl_add_u64 v[140:141], v[178:179], 0, v[136:137]
	global_load_dwordx4 v[136:139], v[140:141], off
	s_nop 0
	global_load_dwordx4 v[140:143], v[140:141], off offset:16
	v_readlane_b32 s64, v254, 20
	v_readlane_b32 s70, v254, 26
	v_readlane_b32 s71, v254, 27
	v_readlane_b32 s72, v254, 28
	v_readlane_b32 s73, v254, 29
	v_readlane_b32 s74, v254, 30
	v_readlane_b32 s75, v254, 31
	v_readlane_b32 s76, v254, 32
	v_readlane_b32 s77, v254, 33
	s_and_b64 vcc, exec, s[16:17]
	s_mov_b64 s[70:71], s[74:75]
	s_mov_b64 s[72:73], s[76:77]
	v_readlane_b32 s65, v254, 21
	v_readlane_b32 s66, v254, 22
	v_readlane_b32 s67, v254, 23
	v_readlane_b32 s68, v254, 24
	v_readlane_b32 s69, v254, 25
	v_readlane_b32 s78, v254, 34
	v_readlane_b32 s79, v254, 35
	s_cbranch_vccz .LBB0_995
	s_barrier

;     __device__ bool next(int i, Unit& u) const { if (!base.next(i >> 1, u)) return false; u.sub = i & 1; return true; }
; #define PG8_STAGE(bufoff, gbase, voff) do { _Pragma("unroll") for (int _i = 0; _i < 2; ++_i) \
;         __builtin_amdgcn_global_load_lds((const unsigned*)((const char*)(gbase) + (voff)[_i]), (PG8_LAS unsigned*)(lds + (bufoff) + ldsw + _i * 8192), 16, 0, 0); } while (0)
; #define PG8_LDA(dst, b, h) do { _Pragma("unroll") for (int m = 0; m < 4; ++m) _Pragma("unroll") for (int k = 0; k < 2; ++k) dst[m][k] = *(const PG8_LAS bf16x8*)(lds + PG8_SA(b, h) + aoff + m * 2048 + k * 1024); } while (0)
; #define PG8_LDB(dst, b, h) do { _Pragma("unroll") for (int n = 0; n < 2; ++n) _Pragma("unroll") for (int k = 0; k < 2; ++k) dst[n][k] = *(const PG8_LAS bf16x8*)(lds + PG8_SB(b, h) + boff + n * 2048 + k * 1024); } while (0)
; #define PG8_WAIT_V(n) asm volatile("s_waitcnt vmcnt(" #n ")" ::: "memory")
; template <class Epi, class Sched, bool ALIGN_EPI = false, bool SP2 = false, bool DUAL = false>
; __device__ __forceinline__ void gemm_phase(PG8_LAS unsigned char* lds, const Gemm g, const Sched& S, const Epi& E) {
;     ...
;         const bool has_next = S.next(ui + 1, nxt);
;         const char* nA = has_next ? (const char*)((DUAL && nxt.sub) ? g.A2 : g.A) + (size_t)nxt.pm * tstep : cA; const char* nB = has_next ? (const char*)((DUAL && nxt.sub) ? g.Bt2 : g.Bt) + (size_t)nxt.pn * tstep : cB;
;         for (int t = 0; t < nt; t += 2) {
;             const bool last = (t == nt - 2);
;             const char* a1 = cA + (size_t)(t + 1) * kstep;
;             const char* a2 = last ? nA : cA + (size_t)(t + 2) * kstep; const char* b2 = last ? nB : cB + (size_t)(t + 2) * kstep;
;             const char* a3 = a2 + kstep; const char* b3 = b2 + kstep;
;             if (last && has_next) S.a_ready(nxt);
;             if constexpr (SP2) {
;             PG8_LDB(B0, 0, 0); PG8_LDB(B1, 0, 1); PG8_SCHED; PG8_LDA(At, 0, 0); PG8_STAGE(PG8_SA(1, 1), a1 + hstep, voffA);
;             PG8_WAIT_V(8); PG8_WAIT_L(0); PG8_BAR; PG8_MMA(0, 0, At, B0); PG8_MMA(0, 1, At, B1); PG8_BAR; PG8_SCHED;
;             PG8_LDA(At, 0, 1); PG8_STAGE(PG8_SB(0, 0), b2, voffB); PG8_STAGE(PG8_SB(0, 1), b2 + hstep, voffB); PG8_STAGE(PG8_SA(0, 0), a2, voffA);
;             PG8_WAIT_V(8); PG8_WAIT_L(0); PG8_BAR; PG8_MMA(1, 0, At, B0); PG8_MMA(1, 1, At, B1); PG8_BAR; PG8_SCHED;
.LBB0_1192:
	s_add_u32 s24, s24, 0x160080
	s_addc_u32 s25, s25, 0
	s_add_u32 s46, s14, 0x100
	s_addc_u32 s47, s15, 0
	s_mov_b32 s48, -2
	s_add_u32 s14, s24, 0xffea0080
	s_addc_u32 s15, s25, -1
	s_cmpk_eq_i32 s48, 0x54
	s_cselect_b32 s27, s5, s15
	s_cselect_b32 s26, s4, s14
	s_cselect_b32 s15, s23, s47
	s_cselect_b32 s14, s22, s46
	s_waitcnt vmcnt(8)
	s_waitcnt lgkmcnt(0)
	s_setprio 1
	s_barrier
	v_mfma_f32_16x16x32_bf16 v[124:127], v[128:131], v[160:163], 0
	v_mfma_f32_16x16x32_bf16 v[124:127], v[132:135], v[182:185], v[124:127]
	v_mfma_f32_16x16x32_bf16 v[112:115], v[128:131], v[186:189], 0
	v_mfma_f32_16x16x32_bf16 v[112:115], v[132:135], v[190:193], v[112:115]
	v_mfma_f32_16x16x32_bf16 v[96:99], v[128:131], v[204:207], 0
	v_mfma_f32_16x16x32_bf16 v[96:99], v[132:135], v[208:211], v[96:99]
	v_mfma_f32_16x16x32_bf16 v[80:83], v[128:131], v[212:215], 0
	v_mfma_f32_16x16x32_bf16 v[80:83], v[132:135], v[216:219], v[80:83]
	v_mfma_f32_16x16x32_bf16 v[120:123], v[136:139], v[160:163], 0
	v_mfma_f32_16x16x32_bf16 v[120:123], v[140:143], v[182:185], v[120:123]
	v_mfma_f32_16x16x32_bf16 v[104:107], v[136:139], v[186:189], 0
	v_mfma_f32_16x16x32_bf16 v[104:107], v[140:143], v[190:193], v[104:107]
	v_mfma_f32_16x16x32_bf16 v[88:91], v[136:139], v[204:207], 0
	v_mfma_f32_16x16x32_bf16 v[88:91], v[140:143], v[208:211], v[88:91]
	v_mfma_f32_16x16x32_bf16 v[72:75], v[136:139], v[212:215], 0
	v_mfma_f32_16x16x32_bf16 v[72:75], v[140:143], v[216:219], v[72:75]
	s_setprio 0
	s_setprio 1
	v_mfma_f32_16x16x32_bf16 v[116:119], v[144:147], v[160:163], 0
	v_mfma_f32_16x16x32_bf16 v[116:119], v[148:151], v[182:185], v[116:119]
	v_mfma_f32_16x16x32_bf16 v[100:103], v[144:147], v[186:189], 0
	v_mfma_f32_16x16x32_bf16 v[100:103], v[148:151], v[190:193], v[100:103]
	v_mfma_f32_16x16x32_bf16 v[84:87], v[144:147], v[204:207], 0
	v_mfma_f32_16x16x32_bf16 v[84:87], v[148:151], v[208:211], v[84:87]
	v_mfma_f32_16x16x32_bf16 v[68:71], v[144:147], v[212:215], 0
	v_mfma_f32_16x16x32_bf16 v[68:71], v[148:151], v[216:219], v[68:71]
	v_mfma_f32_16x16x32_bf16 v[108:111], v[152:155], v[160:163], 0
	v_mfma_f32_16x16x32_bf16 v[108:111], v[156:159], v[182:185], v[108:111]
	v_mfma_f32_16x16x32_bf16 v[92:95], v[152:155], v[186:189], 0
	v_mfma_f32_16x16x32_bf16 v[92:95], v[156:159], v[190:193], v[92:95]
	v_mfma_f32_16x16x32_bf16 v[76:79], v[152:155], v[204:207], 0
	v_mfma_f32_16x16x32_bf16 v[76:79], v[156:159], v[208:211], v[76:79]
	v_mfma_f32_16x16x32_bf16 v[64:67], v[152:155], v[212:215], 0
	v_mfma_f32_16x16x32_bf16 v[64:67], v[156:159], v[216:219], v[64:67]
	s_barrier
	s_setprio 0
	s_add_u32 s98, s14, 0x80
	s_addc_u32 s99, s15, 0
	s_add_u32 s100, s26, 0x80
	s_addc_u32 s101, s27, 0
	s_add_i32 m0, s31, 0xc000
	s_nop 0
	global_load_lds_dwordx4 v172, s[24:25]
	s_add_i32 m0, s31, 0xe000
	s_nop 0
	global_load_lds_dwordx4 v174, s[24:25]
	s_add_i32 s49, s40, s30
	s_mov_b32 m0, s49
	ds_read_b128 v[160:163], v203 offset:16384
	ds_read_b128 v[182:185], v203 offset:17408
	ds_read_b128 v[186:189], v203 offset:18432
	ds_read_b128 v[190:193], v203 offset:19456
	ds_read_b128 v[204:207], v203 offset:20480
	ds_read_b128 v[208:211], v203 offset:21504
	ds_read_b128 v[212:215], v203 offset:22528
	ds_read_b128 v[216:219], v203 offset:23552
	global_load_lds_dwordx4 v166, s[14:15]
	s_add_i32 m0, s49, 0x2000
	s_add_u32 s50, s14, 0x160000
	s_addc_u32 s51, s15, 0
	s_add_i32 s49, s41, s30
	global_load_lds_dwordx4 v170, s[14:15]
	s_mov_b32 m0, s49
	s_nop 0
	global_load_lds_dwordx4 v166, s[50:51]
	s_add_i32 m0, s49, 0x2000
	s_nop 0
	global_load_lds_dwordx4 v170, s[50:51]
	s_mov_b32 m0, s31
	s_nop 0
	global_load_lds_dwordx4 v164, s[26:27]
	s_mov_b32 m0, s33
	s_nop 0
	global_load_lds_dwordx4 v168, s[26:27]
	s_waitcnt vmcnt(8)
	s_waitcnt lgkmcnt(0)
	s_setprio 1
	s_barrier
	v_mfma_f32_16x16x32_bf16 v[60:63], v[128:131], v[160:163], 0
	v_mfma_f32_16x16x32_bf16 v[60:63], v[132:135], v[182:185], v[60:63]
	v_mfma_f32_16x16x32_bf16 v[48:51], v[128:131], v[186:189], 0
	v_mfma_f32_16x16x32_bf16 v[48:51], v[132:135], v[190:193], v[48:51]
	v_mfma_f32_16x16x32_bf16 v[32:35], v[128:131], v[204:207], 0
	v_mfma_f32_16x16x32_bf16 v[32:35], v[132:135], v[208:211], v[32:35]
	v_mfma_f32_16x16x32_bf16 v[16:19], v[128:131], v[212:215], 0
	v_mfma_f32_16x16x32_bf16 v[16:19], v[132:135], v[216:219], v[16:19]
	v_mfma_f32_16x16x32_bf16 v[56:59], v[136:139], v[160:163], 0
	v_mfma_f32_16x16x32_bf16 v[56:59], v[140:143], v[182:185], v[56:59]
	v_mfma_f32_16x16x32_bf16 v[40:43], v[136:139], v[186:189], 0
	v_mfma_f32_16x16x32_bf16 v[40:43], v[140:143], v[190:193], v[40:43]
	v_mfma_f32_16x16x32_bf16 v[24:27], v[136:139], v[204:207], 0
	v_mfma_f32_16x16x32_bf16 v[24:27], v[140:143], v[208:211], v[24:27]
	v_mfma_f32_16x16x32_bf16 v[8:11], v[136:139], v[212:215], 0
	v_mfma_f32_16x16x32_bf16 v[8:11], v[140:143], v[216:219], v[8:11]
	s_setprio 0
	s_setprio 1
	v_mfma_f32_16x16x32_bf16 v[52:55], v[144:147], v[160:163], 0
	v_mfma_f32_16x16x32_bf16 v[52:55], v[148:151], v[182:185], v[52:55]
	v_mfma_f32_16x16x32_bf16 v[36:39], v[144:147], v[186:189], 0
	v_mfma_f32_16x16x32_bf16 v[36:39], v[148:151], v[190:193], v[36:39]
	v_mfma_f32_16x16x32_bf16 v[20:23], v[144:147], v[204:207], 0
	v_mfma_f32_16x16x32_bf16 v[20:23], v[148:151], v[208:211], v[20:23]
	v_mfma_f32_16x16x32_bf16 v[4:7], v[144:147], v[212:215], 0
	v_mfma_f32_16x16x32_bf16 v[4:7], v[148:151], v[216:219], v[4:7]
	v_mfma_f32_16x16x32_bf16 v[44:47], v[152:155], v[160:163], 0
	v_mfma_f32_16x16x32_bf16 v[44:47], v[156:159], v[182:185], v[44:47]
	v_mfma_f32_16x16x32_bf16 v[28:31], v[152:155], v[186:189], 0
	v_mfma_f32_16x16x32_bf16 v[28:31], v[156:159], v[190:193], v[28:31]
	v_mfma_f32_16x16x32_bf16 v[12:15], v[152:155], v[204:207], 0
	v_mfma_f32_16x16x32_bf16 v[12:15], v[156:159], v[208:211], v[12:15]
	v_mfma_f32_16x16x32_bf16 v[0:3], v[152:155], v[212:215], 0
	v_mfma_f32_16x16x32_bf16 v[0:3], v[156:159], v[216:219], v[0:3]
	s_barrier
; #define PG8_STAGE(bufoff, gbase, voff) do { _Pragma("unroll") for (int _i = 0; _i < 2; ++_i) \
;         __builtin_amdgcn_global_load_lds((const unsigned*)((const char*)(gbase) + (voff)[_i]), (PG8_LAS unsigned*)(lds + (bufoff) + ldsw + _i * 8192), 16, 0, 0); } while (0)
; #define PG8_LDA(dst, b, h) do { _Pragma("unroll") for (int m = 0; m < 4; ++m) _Pragma("unroll") for (int k = 0; k < 2; ++k) dst[m][k] = *(const PG8_LAS bf16x8*)(lds + PG8_SA(b, h) + aoff + m * 2048 + k * 1024); } while (0)
; #define PG8_LDB(dst, b, h) do { _Pragma("unroll") for (int n = 0; n < 2; ++n) _Pragma("unroll") for (int k = 0; k < 2; ++k) dst[n][k] = *(const PG8_LAS bf16x8*)(lds + PG8_SB(b, h) + boff + n * 2048 + k * 1024); } while (0)
; #define PG8_MMA(ai, bj, At, Bt) do { __builtin_amdgcn_s_setprio(1); _Pragma("unroll") for (int m = 0; m < 4; ++m) _Pragma("unroll") for (int n = 0; n < 2; ++n) _Pragma("unroll") for (int k = 0; k < 2; ++k) \
;         acc[ai][bj][m][n] = __builtin_amdgcn_mfma_f32_16x16x32_bf16(Bt[n][k], At[m][k], acc[ai][bj][m][n], 0, 0, 0); __builtin_amdgcn_s_setprio(0); } while (0)
; #define PG8_WAIT_V(n) asm volatile("s_waitcnt vmcnt(" #n ")" ::: "memory")
; #define PG8_WAIT_L(n) asm volatile("s_waitcnt lgkmcnt(" #n ")" ::: "memory")
; #define PG8_BAR __builtin_amdgcn_s_barrier()
; #define PG8_SCHED __builtin_amdgcn_sched_barrier(0)
; template <class Epi, class Sched, bool ALIGN_EPI = false, bool SP2 = false, bool DUAL = false>
; __device__ __forceinline__ void gemm_phase(PG8_LAS unsigned char* lds, const Gemm g, const Sched& S, const Epi& E) {
;     ...
;             PG8_LDB(B0, 1, 0); PG8_LDB(B1, 1, 1); PG8_SCHED; PG8_LDA(At, 1, 0); PG8_STAGE(PG8_SA(0, 1), a2 + hstep, voffA);
;             PG8_WAIT_V(8); PG8_WAIT_L(0); PG8_BAR; PG8_MMA(0, 0, At, B0); PG8_MMA(0, 1, At, B1); PG8_BAR; PG8_SCHED;
;             PG8_LDA(At, 1, 1); PG8_STAGE(PG8_SB(1, 0), b3, voffB); PG8_STAGE(PG8_SB(1, 1), b3 + hstep, voffB); PG8_STAGE(PG8_SA(1, 0), a3, voffA);
;             PG8_WAIT_V(8); PG8_WAIT_L(0); PG8_BAR; PG8_MMA(1, 0, At, B0); PG8_MMA(1, 1, At, B1); PG8_BAR; PG8_SCHED;
	s_setprio 0
	s_add_i32 s49, 0, 0x18000
	s_add_i32 s50, 0, 0x1c000
	v_add_u32_e32 v140, s49, v198
	v_add_u32_e32 v156, s50, v198
	ds_read_b128 v[128:131], v140
	ds_read_b128 v[132:135], v140 offset:1024
	ds_read_b128 v[136:139], v140 offset:2048
	ds_read_b128 v[140:143], v140 offset:3072
	ds_read_b128 v[144:147], v156
	ds_read_b128 v[148:151], v156 offset:1024
	ds_read_b128 v[152:155], v156 offset:2048
	ds_read_b128 v[156:159], v156 offset:3072
	s_add_u32 s26, s26, 0x160000
	s_addc_u32 s27, s27, 0
	s_mov_b32 m0, s34
	ds_read_b128 v[160:163], v203 offset:32768
	ds_read_b128 v[182:185], v203 offset:33792
	ds_read_b128 v[186:189], v203 offset:34816
	ds_read_b128 v[190:193], v203 offset:35840
	ds_read_b128 v[204:207], v203 offset:36864
	ds_read_b128 v[208:211], v203 offset:37888
	ds_read_b128 v[212:215], v203 offset:38912
	ds_read_b128 v[216:219], v203 offset:39936
	global_load_lds_dwordx4 v164, s[26:27]
	s_mov_b32 m0, s35
	s_nop 0
	global_load_lds_dwordx4 v168, s[26:27]
	s_waitcnt vmcnt(8)
	s_waitcnt lgkmcnt(0)
	s_setprio 1
	s_barrier
	v_mfma_f32_16x16x32_bf16 v[124:127], v[128:131], v[160:163], v[124:127]
	v_mfma_f32_16x16x32_bf16 v[124:127], v[132:135], v[182:185], v[124:127]
	v_mfma_f32_16x16x32_bf16 v[112:115], v[128:131], v[186:189], v[112:115]
	v_mfma_f32_16x16x32_bf16 v[112:115], v[132:135], v[190:193], v[112:115]
	v_mfma_f32_16x16x32_bf16 v[96:99], v[128:131], v[204:207], v[96:99]
	v_mfma_f32_16x16x32_bf16 v[96:99], v[132:135], v[208:211], v[96:99]
	v_mfma_f32_16x16x32_bf16 v[80:83], v[128:131], v[212:215], v[80:83]
	v_mfma_f32_16x16x32_bf16 v[80:83], v[132:135], v[216:219], v[80:83]
	v_mfma_f32_16x16x32_bf16 v[120:123], v[136:139], v[160:163], v[120:123]
	v_mfma_f32_16x16x32_bf16 v[120:123], v[140:143], v[182:185], v[120:123]
	v_mfma_f32_16x16x32_bf16 v[104:107], v[136:139], v[186:189], v[104:107]
	v_mfma_f32_16x16x32_bf16 v[104:107], v[140:143], v[190:193], v[104:107]
	v_mfma_f32_16x16x32_bf16 v[88:91], v[136:139], v[204:207], v[88:91]
	v_mfma_f32_16x16x32_bf16 v[88:91], v[140:143], v[208:211], v[88:91]
	v_mfma_f32_16x16x32_bf16 v[72:75], v[136:139], v[212:215], v[72:75]
	v_mfma_f32_16x16x32_bf16 v[72:75], v[140:143], v[216:219], v[72:75]
	s_setprio 0
	s_setprio 1
	v_mfma_f32_16x16x32_bf16 v[116:119], v[144:147], v[160:163], v[116:119]
	v_mfma_f32_16x16x32_bf16 v[116:119], v[148:151], v[182:185], v[116:119]
	v_mfma_f32_16x16x32_bf16 v[100:103], v[144:147], v[186:189], v[100:103]
	v_mfma_f32_16x16x32_bf16 v[100:103], v[148:151], v[190:193], v[100:103]
	v_mfma_f32_16x16x32_bf16 v[84:87], v[144:147], v[204:207], v[84:87]
	v_mfma_f32_16x16x32_bf16 v[84:87], v[148:151], v[208:211], v[84:87]
	v_mfma_f32_16x16x32_bf16 v[68:71], v[144:147], v[212:215], v[68:71]
	v_mfma_f32_16x16x32_bf16 v[68:71], v[148:151], v[216:219], v[68:71]
	v_mfma_f32_16x16x32_bf16 v[108:111], v[152:155], v[160:163], v[108:111]
	v_mfma_f32_16x16x32_bf16 v[108:111], v[156:159], v[182:185], v[108:111]
	v_mfma_f32_16x16x32_bf16 v[92:95], v[152:155], v[186:189], v[92:95]
	v_mfma_f32_16x16x32_bf16 v[92:95], v[156:159], v[190:193], v[92:95]
	v_mfma_f32_16x16x32_bf16 v[76:79], v[152:155], v[204:207], v[76:79]
	v_mfma_f32_16x16x32_bf16 v[76:79], v[156:159], v[208:211], v[76:79]
	v_mfma_f32_16x16x32_bf16 v[64:67], v[152:155], v[212:215], v[64:67]
	v_mfma_f32_16x16x32_bf16 v[64:67], v[156:159], v[216:219], v[64:67]
	s_barrier
	s_setprio 0
	s_add_i32 s26, s49, s30
	s_mov_b32 m0, s26
	ds_read_b128 v[160:163], v203 offset:49152
	ds_read_b128 v[182:185], v203 offset:50176
	ds_read_b128 v[186:189], v203 offset:51200
	ds_read_b128 v[190:193], v203 offset:52224
	ds_read_b128 v[204:207], v203 offset:53248
	ds_read_b128 v[208:211], v203 offset:54272
	ds_read_b128 v[212:215], v203 offset:55296
	ds_read_b128 v[216:219], v203 offset:56320
	global_load_lds_dwordx4 v166, s[98:99]
	s_add_i32 m0, s26, 0x2000
	s_add_u32 s14, s14, 0x160080
	s_addc_u32 s15, s15, 0
	s_add_i32 s26, s50, s30
	global_load_lds_dwordx4 v170, s[98:99]
	s_mov_b32 m0, s26
	s_nop 0
	global_load_lds_dwordx4 v166, s[14:15]
	s_add_i32 m0, s26, 0x2000
	s_nop 0
	global_load_lds_dwordx4 v170, s[14:15]
	s_mov_b32 m0, s37
	s_nop 0
	global_load_lds_dwordx4 v164, s[100:101]
	s_mov_b32 m0, s38
	s_nop 0
	global_load_lds_dwordx4 v168, s[100:101]
	s_waitcnt vmcnt(8)
	s_waitcnt lgkmcnt(0)
	s_setprio 1
	s_barrier
	v_mfma_f32_16x16x32_bf16 v[60:63], v[128:131], v[160:163], v[60:63]
	v_mfma_f32_16x16x32_bf16 v[60:63], v[132:135], v[182:185], v[60:63]
	v_mfma_f32_16x16x32_bf16 v[48:51], v[128:131], v[186:189], v[48:51]
	v_mfma_f32_16x16x32_bf16 v[48:51], v[132:135], v[190:193], v[48:51]
	v_mfma_f32_16x16x32_bf16 v[32:35], v[128:131], v[204:207], v[32:35]
	v_mfma_f32_16x16x32_bf16 v[32:35], v[132:135], v[208:211], v[32:35]
	v_mfma_f32_16x16x32_bf16 v[16:19], v[128:131], v[212:215], v[16:19]
	v_mfma_f32_16x16x32_bf16 v[16:19], v[132:135], v[216:219], v[16:19]
	v_mfma_f32_16x16x32_bf16 v[56:59], v[136:139], v[160:163], v[56:59]
	v_mfma_f32_16x16x32_bf16 v[56:59], v[140:143], v[182:185], v[56:59]
	v_mfma_f32_16x16x32_bf16 v[40:43], v[136:139], v[186:189], v[40:43]
	v_mfma_f32_16x16x32_bf16 v[40:43], v[140:143], v[190:193], v[40:43]
	v_mfma_f32_16x16x32_bf16 v[24:27], v[136:139], v[204:207], v[24:27]
	v_mfma_f32_16x16x32_bf16 v[24:27], v[140:143], v[208:211], v[24:27]
	v_mfma_f32_16x16x32_bf16 v[8:11], v[136:139], v[212:215], v[8:11]
	v_mfma_f32_16x16x32_bf16 v[8:11], v[140:143], v[216:219], v[8:11]
	s_setprio 0
	s_setprio 1
	v_mfma_f32_16x16x32_bf16 v[52:55], v[144:147], v[160:163], v[52:55]
	v_mfma_f32_16x16x32_bf16 v[52:55], v[148:151], v[182:185], v[52:55]
	v_mfma_f32_16x16x32_bf16 v[36:39], v[144:147], v[186:189], v[36:39]
	v_mfma_f32_16x16x32_bf16 v[36:39], v[148:151], v[190:193], v[36:39]
	v_mfma_f32_16x16x32_bf16 v[20:23], v[144:147], v[204:207], v[20:23]
	v_mfma_f32_16x16x32_bf16 v[20:23], v[148:151], v[208:211], v[20:23]
	v_mfma_f32_16x16x32_bf16 v[4:7], v[144:147], v[212:215], v[4:7]
	v_mfma_f32_16x16x32_bf16 v[4:7], v[148:151], v[216:219], v[4:7]
	v_mfma_f32_16x16x32_bf16 v[44:47], v[152:155], v[160:163], v[44:47]
	v_mfma_f32_16x16x32_bf16 v[44:47], v[156:159], v[182:185], v[44:47]
	v_mfma_f32_16x16x32_bf16 v[28:31], v[152:155], v[186:189], v[28:31]
	v_mfma_f32_16x16x32_bf16 v[28:31], v[156:159], v[190:193], v[28:31]
	v_mfma_f32_16x16x32_bf16 v[12:15], v[152:155], v[204:207], v[12:15]
	v_mfma_f32_16x16x32_bf16 v[12:15], v[156:159], v[208:211], v[12:15]
	v_mfma_f32_16x16x32_bf16 v[0:3], v[152:155], v[212:215], v[0:3]
	v_mfma_f32_16x16x32_bf16 v[0:3], v[156:159], v[216:219], v[0:3]
	s_barrier
	s_setprio 0
	s_add_i32 s48, s48, 2
	s_add_u32 s24, s24, 0x100
	s_addc_u32 s25, s25, 0
	s_add_u32 s46, s46, 0x100
	s_addc_u32 s47, s47, 0
; #define PG8_STAGE(bufoff, gbase, voff) do { _Pragma("unroll") for (int _i = 0; _i < 2; ++_i) \
;         __builtin_amdgcn_global_load_lds((const unsigned*)((const char*)(gbase) + (voff)[_i]), (PG8_LAS unsigned*)(lds + (bufoff) + ldsw + _i * 8192), 16, 0, 0); } while (0)
; #define PG8_LDA(dst, b, h) do { _Pragma("unroll") for (int m = 0; m < 4; ++m) _Pragma("unroll") for (int k = 0; k < 2; ++k) dst[m][k] = *(const PG8_LAS bf16x8*)(lds + PG8_SA(b, h) + aoff + m * 2048 + k * 1024); } while (0)
; #define PG8_LDB(dst, b, h) do { _Pragma("unroll") for (int n = 0; n < 2; ++n) _Pragma("unroll") for (int k = 0; k < 2; ++k) dst[n][k] = *(const PG8_LAS bf16x8*)(lds + PG8_SB(b, h) + boff + n * 2048 + k * 1024); } while (0)
; #define PG8_MMA(ai, bj, At, Bt) do { __builtin_amdgcn_s_setprio(1); _Pragma("unroll") for (int m = 0; m < 4; ++m) _Pragma("unroll") for (int n = 0; n < 2; ++n) _Pragma("unroll") for (int k = 0; k < 2; ++k) \
;         acc[ai][bj][m][n] = __builtin_amdgcn_mfma_f32_16x16x32_bf16(Bt[n][k], At[m][k], acc[ai][bj][m][n], 0, 0, 0); __builtin_amdgcn_s_setprio(0); } while (0)
; #define PG8_WAIT_V(n) asm volatile("s_waitcnt vmcnt(" #n ")" ::: "memory")
; #define PG8_BAR __builtin_amdgcn_s_barrier()
; template <class Epi, class Sched, bool ALIGN_EPI = false, bool SP2 = false, bool DUAL = false>
; __device__ __forceinline__ void gemm_phase(PG8_LAS unsigned char* lds, const Gemm g, const Sched& S, const Epi& E) {
;     ...
;         for (int t = 0; t < nt; t += 2) {
;             const bool last = (t == nt - 2);
;             const char* a1 = cA + (size_t)(t + 1) * kstep;
;             const char* a2 = last ? nA : cA + (size_t)(t + 2) * kstep; const char* b2 = last ? nB : cB + (size_t)(t + 2) * kstep;
;             const char* a3 = a2 + kstep; const char* b3 = b2 + kstep;
;             if (last && has_next) S.a_ready(nxt);
;             if constexpr (SP2) {
;             PG8_LDB(B0, 0, 0); PG8_LDB(B1, 0, 1); PG8_SCHED; PG8_LDA(At, 0, 0); PG8_STAGE(PG8_SA(1, 1), a1 + hstep, voffA);
;             PG8_WAIT_V(8); PG8_WAIT_L(0); PG8_BAR; PG8_MMA(0, 0, At, B0); PG8_MMA(0, 1, At, B1); PG8_BAR; PG8_SCHED;
;             PG8_LDA(At, 0, 1); PG8_STAGE(PG8_SB(0, 0), b2, voffB); PG8_STAGE(PG8_SB(0, 1), b2 + hstep, voffB); PG8_STAGE(PG8_SA(0, 0), a2, voffA);
;             PG8_WAIT_V(8); PG8_WAIT_L(0); PG8_BAR; PG8_MMA(1, 0, At, B0); PG8_MMA(1, 1, At, B1); PG8_BAR; PG8_SCHED;
.LBB0_1193:
	ds_read_b128 v[128:131], v201
	ds_read_b128 v[132:135], v201 offset:1024
	ds_read_b128 v[136:139], v201 offset:2048
	ds_read_b128 v[140:143], v201 offset:3072
	ds_read_b128 v[144:147], v202
	ds_read_b128 v[148:151], v202 offset:1024
	ds_read_b128 v[152:155], v202 offset:2048
	ds_read_b128 v[156:159], v202 offset:3072
	s_add_u32 s14, s24, 0xffea0080
	s_addc_u32 s15, s25, -1
	s_cmpk_eq_i32 s48, 0x54
	s_cselect_b32 s27, s5, s15
	s_cselect_b32 s26, s4, s14
	s_cselect_b32 s15, s23, s47
	s_cselect_b32 s14, s22, s46
	s_add_i32 m0, s31, 0xc000
	ds_read_b128 v[160:163], v203
	ds_read_b128 v[182:185], v203 offset:1024
	ds_read_b128 v[186:189], v203 offset:2048
	ds_read_b128 v[190:193], v203 offset:3072
	ds_read_b128 v[204:207], v203 offset:4096
	ds_read_b128 v[208:211], v203 offset:5120
	ds_read_b128 v[212:215], v203 offset:6144
	ds_read_b128 v[216:219], v203 offset:7168
	global_load_lds_dwordx4 v172, s[24:25]
	s_add_i32 m0, s31, 0xe000
	s_nop 0
	global_load_lds_dwordx4 v174, s[24:25]
	s_waitcnt vmcnt(8)
	s_waitcnt lgkmcnt(0)
	s_setprio 1
	s_barrier
	v_mfma_f32_16x16x32_bf16 v[124:127], v[128:131], v[160:163], v[124:127]
	v_mfma_f32_16x16x32_bf16 v[124:127], v[132:135], v[182:185], v[124:127]
	v_mfma_f32_16x16x32_bf16 v[112:115], v[128:131], v[186:189], v[112:115]
	v_mfma_f32_16x16x32_bf16 v[112:115], v[132:135], v[190:193], v[112:115]
	v_mfma_f32_16x16x32_bf16 v[96:99], v[128:131], v[204:207], v[96:99]
	v_mfma_f32_16x16x32_bf16 v[96:99], v[132:135], v[208:211], v[96:99]
	v_mfma_f32_16x16x32_bf16 v[80:83], v[128:131], v[212:215], v[80:83]
	v_mfma_f32_16x16x32_bf16 v[80:83], v[132:135], v[216:219], v[80:83]
	v_mfma_f32_16x16x32_bf16 v[120:123], v[136:139], v[160:163], v[120:123]
	v_mfma_f32_16x16x32_bf16 v[120:123], v[140:143], v[182:185], v[120:123]
	v_mfma_f32_16x16x32_bf16 v[104:107], v[136:139], v[186:189], v[104:107]
	v_mfma_f32_16x16x32_bf16 v[104:107], v[140:143], v[190:193], v[104:107]
	v_mfma_f32_16x16x32_bf16 v[88:91], v[136:139], v[204:207], v[88:91]
	v_mfma_f32_16x16x32_bf16 v[88:91], v[140:143], v[208:211], v[88:91]
	v_mfma_f32_16x16x32_bf16 v[72:75], v[136:139], v[212:215], v[72:75]
	v_mfma_f32_16x16x32_bf16 v[72:75], v[140:143], v[216:219], v[72:75]
	s_setprio 0
	s_setprio 1
	v_mfma_f32_16x16x32_bf16 v[116:119], v[144:147], v[160:163], v[116:119]
	v_mfma_f32_16x16x32_bf16 v[116:119], v[148:151], v[182:185], v[116:119]
	v_mfma_f32_16x16x32_bf16 v[100:103], v[144:147], v[186:189], v[100:103]
	v_mfma_f32_16x16x32_bf16 v[100:103], v[148:151], v[190:193], v[100:103]
	v_mfma_f32_16x16x32_bf16 v[84:87], v[144:147], v[204:207], v[84:87]
	v_mfma_f32_16x16x32_bf16 v[84:87], v[148:151], v[208:211], v[84:87]
	v_mfma_f32_16x16x32_bf16 v[68:71], v[144:147], v[212:215], v[68:71]
	v_mfma_f32_16x16x32_bf16 v[68:71], v[148:151], v[216:219], v[68:71]
	v_mfma_f32_16x16x32_bf16 v[108:111], v[152:155], v[160:163], v[108:111]
	v_mfma_f32_16x16x32_bf16 v[108:111], v[156:159], v[182:185], v[108:111]
	v_mfma_f32_16x16x32_bf16 v[92:95], v[152:155], v[186:189], v[92:95]
	v_mfma_f32_16x16x32_bf16 v[92:95], v[156:159], v[190:193], v[92:95]
	v_mfma_f32_16x16x32_bf16 v[76:79], v[152:155], v[204:207], v[76:79]
	v_mfma_f32_16x16x32_bf16 v[76:79], v[156:159], v[208:211], v[76:79]
	v_mfma_f32_16x16x32_bf16 v[64:67], v[152:155], v[212:215], v[64:67]
	v_mfma_f32_16x16x32_bf16 v[64:67], v[156:159], v[216:219], v[64:67]
	s_barrier
	s_setprio 0
	s_add_u32 s98, s14, 0x80
	s_addc_u32 s99, s15, 0
	s_add_u32 s100, s26, 0x80
	s_addc_u32 s101, s27, 0
	s_add_i32 s49, s40, s30
	s_mov_b32 m0, s49
	ds_read_b128 v[160:163], v203 offset:16384
	ds_read_b128 v[182:185], v203 offset:17408
	ds_read_b128 v[186:189], v203 offset:18432
	ds_read_b128 v[190:193], v203 offset:19456
	ds_read_b128 v[204:207], v203 offset:20480
	ds_read_b128 v[208:211], v203 offset:21504
	ds_read_b128 v[212:215], v203 offset:22528
	ds_read_b128 v[216:219], v203 offset:23552
	global_load_lds_dwordx4 v166, s[14:15]
	s_add_i32 m0, s49, 0x2000
	s_add_u32 s50, s14, 0x160000
	s_addc_u32 s51, s15, 0
	s_add_i32 s49, s41, s30
	global_load_lds_dwordx4 v170, s[14:15]
	s_mov_b32 m0, s49
	s_nop 0
	global_load_lds_dwordx4 v166, s[50:51]
	s_add_i32 m0, s49, 0x2000
	s_nop 0
	global_load_lds_dwordx4 v170, s[50:51]
	s_mov_b32 m0, s31
	s_nop 0
	global_load_lds_dwordx4 v164, s[26:27]
	s_mov_b32 m0, s33
	s_nop 0
	global_load_lds_dwordx4 v168, s[26:27]
	s_waitcnt vmcnt(8)
	s_waitcnt lgkmcnt(0)
	s_setprio 1
	s_barrier
	v_mfma_f32_16x16x32_bf16 v[60:63], v[128:131], v[160:163], v[60:63]
	v_mfma_f32_16x16x32_bf16 v[60:63], v[132:135], v[182:185], v[60:63]
	v_mfma_f32_16x16x32_bf16 v[48:51], v[128:131], v[186:189], v[48:51]
	v_mfma_f32_16x16x32_bf16 v[48:51], v[132:135], v[190:193], v[48:51]
	v_mfma_f32_16x16x32_bf16 v[32:35], v[128:131], v[204:207], v[32:35]
	v_mfma_f32_16x16x32_bf16 v[32:35], v[132:135], v[208:211], v[32:35]
	v_mfma_f32_16x16x32_bf16 v[16:19], v[128:131], v[212:215], v[16:19]
	v_mfma_f32_16x16x32_bf16 v[16:19], v[132:135], v[216:219], v[16:19]
	v_mfma_f32_16x16x32_bf16 v[56:59], v[136:139], v[160:163], v[56:59]
	v_mfma_f32_16x16x32_bf16 v[56:59], v[140:143], v[182:185], v[56:59]
	v_mfma_f32_16x16x32_bf16 v[40:43], v[136:139], v[186:189], v[40:43]
	v_mfma_f32_16x16x32_bf16 v[40:43], v[140:143], v[190:193], v[40:43]
	v_mfma_f32_16x16x32_bf16 v[24:27], v[136:139], v[204:207], v[24:27]
	v_mfma_f32_16x16x32_bf16 v[24:27], v[140:143], v[208:211], v[24:27]
	v_mfma_f32_16x16x32_bf16 v[8:11], v[136:139], v[212:215], v[8:11]
	v_mfma_f32_16x16x32_bf16 v[8:11], v[140:143], v[216:219], v[8:11]
	s_setprio 0
	s_setprio 1
	v_mfma_f32_16x16x32_bf16 v[52:55], v[144:147], v[160:163], v[52:55]
	v_mfma_f32_16x16x32_bf16 v[52:55], v[148:151], v[182:185], v[52:55]
	v_mfma_f32_16x16x32_bf16 v[36:39], v[144:147], v[186:189], v[36:39]
	v_mfma_f32_16x16x32_bf16 v[36:39], v[148:151], v[190:193], v[36:39]
	v_mfma_f32_16x16x32_bf16 v[20:23], v[144:147], v[204:207], v[20:23]
	v_mfma_f32_16x16x32_bf16 v[20:23], v[148:151], v[208:211], v[20:23]
	v_mfma_f32_16x16x32_bf16 v[4:7], v[144:147], v[212:215], v[4:7]
	v_mfma_f32_16x16x32_bf16 v[4:7], v[148:151], v[216:219], v[4:7]
	v_mfma_f32_16x16x32_bf16 v[44:47], v[152:155], v[160:163], v[44:47]
	v_mfma_f32_16x16x32_bf16 v[44:47], v[156:159], v[182:185], v[44:47]
	v_mfma_f32_16x16x32_bf16 v[28:31], v[152:155], v[186:189], v[28:31]
	v_mfma_f32_16x16x32_bf16 v[28:31], v[156:159], v[190:193], v[28:31]
	v_mfma_f32_16x16x32_bf16 v[12:15], v[152:155], v[204:207], v[12:15]
	v_mfma_f32_16x16x32_bf16 v[12:15], v[156:159], v[208:211], v[12:15]
	v_mfma_f32_16x16x32_bf16 v[0:3], v[152:155], v[212:215], v[0:3]
	v_mfma_f32_16x16x32_bf16 v[0:3], v[156:159], v[216:219], v[0:3]
	s_barrier
; #define PG8_STAGE(bufoff, gbase, voff) do { _Pragma("unroll") for (int _i = 0; _i < 2; ++_i) \
;         __builtin_amdgcn_global_load_lds((const unsigned*)((const char*)(gbase) + (voff)[_i]), (PG8_LAS unsigned*)(lds + (bufoff) + ldsw + _i * 8192), 16, 0, 0); } while (0)
; #define PG8_LDA(dst, b, h) do { _Pragma("unroll") for (int m = 0; m < 4; ++m) _Pragma("unroll") for (int k = 0; k < 2; ++k) dst[m][k] = *(const PG8_LAS bf16x8*)(lds + PG8_SA(b, h) + aoff + m * 2048 + k * 1024); } while (0)
; #define PG8_LDB(dst, b, h) do { _Pragma("unroll") for (int n = 0; n < 2; ++n) _Pragma("unroll") for (int k = 0; k < 2; ++k) dst[n][k] = *(const PG8_LAS bf16x8*)(lds + PG8_SB(b, h) + boff + n * 2048 + k * 1024); } while (0)
; #define PG8_MMA(ai, bj, At, Bt) do { __builtin_amdgcn_s_setprio(1); _Pragma("unroll") for (int m = 0; m < 4; ++m) _Pragma("unroll") for (int n = 0; n < 2; ++n) _Pragma("unroll") for (int k = 0; k < 2; ++k) \
;         acc[ai][bj][m][n] = __builtin_amdgcn_mfma_f32_16x16x32_bf16(Bt[n][k], At[m][k], acc[ai][bj][m][n], 0, 0, 0); __builtin_amdgcn_s_setprio(0); } while (0)
; #define PG8_WAIT_V(n) asm volatile("s_waitcnt vmcnt(" #n ")" ::: "memory")
; #define PG8_WAIT_L(n) asm volatile("s_waitcnt lgkmcnt(" #n ")" ::: "memory")
; #define PG8_BAR __builtin_amdgcn_s_barrier()
; #define PG8_SCHED __builtin_amdgcn_sched_barrier(0)
; template <class Epi, class Sched, bool ALIGN_EPI = false, bool SP2 = false, bool DUAL = false>
; __device__ __forceinline__ void gemm_phase(PG8_LAS unsigned char* lds, const Gemm g, const Sched& S, const Epi& E) {
;     ...
;             PG8_LDB(B0, 1, 0); PG8_LDB(B1, 1, 1); PG8_SCHED; PG8_LDA(At, 1, 0); PG8_STAGE(PG8_SA(0, 1), a2 + hstep, voffA);
;             PG8_WAIT_V(8); PG8_WAIT_L(0); PG8_BAR; PG8_MMA(0, 0, At, B0); PG8_MMA(0, 1, At, B1); PG8_BAR; PG8_SCHED;
;             PG8_LDA(At, 1, 1); PG8_STAGE(PG8_SB(1, 0), b3, voffB); PG8_STAGE(PG8_SB(1, 1), b3 + hstep, voffB); PG8_STAGE(PG8_SA(1, 0), a3, voffA);
;             PG8_WAIT_V(8); PG8_WAIT_L(0); PG8_BAR; PG8_MMA(1, 0, At, B0); PG8_MMA(1, 1, At, B1); PG8_BAR; PG8_SCHED;
	s_setprio 0
	s_add_i32 s49, 0, 0x18000
	s_add_i32 s50, 0, 0x1c000
	v_add_u32_e32 v140, s49, v198
	v_add_u32_e32 v156, s50, v198
	ds_read_b128 v[128:131], v140
	ds_read_b128 v[132:135], v140 offset:1024
	ds_read_b128 v[136:139], v140 offset:2048
	ds_read_b128 v[140:143], v140 offset:3072
	ds_read_b128 v[144:147], v156
	ds_read_b128 v[148:151], v156 offset:1024
	ds_read_b128 v[152:155], v156 offset:2048
	ds_read_b128 v[156:159], v156 offset:3072
	s_add_u32 s26, s26, 0x160000
	s_addc_u32 s27, s27, 0
	s_mov_b32 m0, s34
	ds_read_b128 v[160:163], v203 offset:32768
	ds_read_b128 v[182:185], v203 offset:33792
	ds_read_b128 v[186:189], v203 offset:34816
	ds_read_b128 v[190:193], v203 offset:35840
	ds_read_b128 v[204:207], v203 offset:36864
	ds_read_b128 v[208:211], v203 offset:37888
	ds_read_b128 v[212:215], v203 offset:38912
	ds_read_b128 v[216:219], v203 offset:39936
	global_load_lds_dwordx4 v164, s[26:27]
	s_mov_b32 m0, s35
	s_nop 0
	global_load_lds_dwordx4 v168, s[26:27]
	s_waitcnt vmcnt(8)
	s_waitcnt lgkmcnt(0)
	s_setprio 1
	s_barrier
	v_mfma_f32_16x16x32_bf16 v[124:127], v[128:131], v[160:163], v[124:127]
	v_mfma_f32_16x16x32_bf16 v[124:127], v[132:135], v[182:185], v[124:127]
	v_mfma_f32_16x16x32_bf16 v[112:115], v[128:131], v[186:189], v[112:115]
	v_mfma_f32_16x16x32_bf16 v[112:115], v[132:135], v[190:193], v[112:115]
	v_mfma_f32_16x16x32_bf16 v[96:99], v[128:131], v[204:207], v[96:99]
	v_mfma_f32_16x16x32_bf16 v[96:99], v[132:135], v[208:211], v[96:99]
	v_mfma_f32_16x16x32_bf16 v[80:83], v[128:131], v[212:215], v[80:83]
	v_mfma_f32_16x16x32_bf16 v[80:83], v[132:135], v[216:219], v[80:83]
	v_mfma_f32_16x16x32_bf16 v[120:123], v[136:139], v[160:163], v[120:123]
	v_mfma_f32_16x16x32_bf16 v[120:123], v[140:143], v[182:185], v[120:123]
	v_mfma_f32_16x16x32_bf16 v[104:107], v[136:139], v[186:189], v[104:107]
	v_mfma_f32_16x16x32_bf16 v[104:107], v[140:143], v[190:193], v[104:107]
	v_mfma_f32_16x16x32_bf16 v[88:91], v[136:139], v[204:207], v[88:91]
	v_mfma_f32_16x16x32_bf16 v[88:91], v[140:143], v[208:211], v[88:91]
	v_mfma_f32_16x16x32_bf16 v[72:75], v[136:139], v[212:215], v[72:75]
	v_mfma_f32_16x16x32_bf16 v[72:75], v[140:143], v[216:219], v[72:75]
	s_setprio 0
	s_setprio 1
	v_mfma_f32_16x16x32_bf16 v[116:119], v[144:147], v[160:163], v[116:119]
	v_mfma_f32_16x16x32_bf16 v[116:119], v[148:151], v[182:185], v[116:119]
	v_mfma_f32_16x16x32_bf16 v[100:103], v[144:147], v[186:189], v[100:103]
	v_mfma_f32_16x16x32_bf16 v[100:103], v[148:151], v[190:193], v[100:103]
	v_mfma_f32_16x16x32_bf16 v[84:87], v[144:147], v[204:207], v[84:87]
	v_mfma_f32_16x16x32_bf16 v[84:87], v[148:151], v[208:211], v[84:87]
	v_mfma_f32_16x16x32_bf16 v[68:71], v[144:147], v[212:215], v[68:71]
	v_mfma_f32_16x16x32_bf16 v[68:71], v[148:151], v[216:219], v[68:71]
	v_mfma_f32_16x16x32_bf16 v[108:111], v[152:155], v[160:163], v[108:111]
	v_mfma_f32_16x16x32_bf16 v[108:111], v[156:159], v[182:185], v[108:111]
	v_mfma_f32_16x16x32_bf16 v[92:95], v[152:155], v[186:189], v[92:95]
	v_mfma_f32_16x16x32_bf16 v[92:95], v[156:159], v[190:193], v[92:95]
	v_mfma_f32_16x16x32_bf16 v[76:79], v[152:155], v[204:207], v[76:79]
	v_mfma_f32_16x16x32_bf16 v[76:79], v[156:159], v[208:211], v[76:79]
	v_mfma_f32_16x16x32_bf16 v[64:67], v[152:155], v[212:215], v[64:67]
	v_mfma_f32_16x16x32_bf16 v[64:67], v[156:159], v[216:219], v[64:67]
	s_barrier
	s_setprio 0
	s_add_i32 s26, s49, s30
	s_mov_b32 m0, s26
	ds_read_b128 v[160:163], v203 offset:49152
	ds_read_b128 v[182:185], v203 offset:50176
	ds_read_b128 v[186:189], v203 offset:51200
	ds_read_b128 v[190:193], v203 offset:52224
	ds_read_b128 v[204:207], v203 offset:53248
	ds_read_b128 v[208:211], v203 offset:54272
	ds_read_b128 v[212:215], v203 offset:55296
	ds_read_b128 v[216:219], v203 offset:56320
	global_load_lds_dwordx4 v166, s[98:99]
	s_add_i32 m0, s26, 0x2000
	s_add_u32 s14, s14, 0x160080
	s_addc_u32 s15, s15, 0
	s_add_i32 s26, s50, s30
	global_load_lds_dwordx4 v170, s[98:99]
	s_mov_b32 m0, s26
	s_nop 0
	global_load_lds_dwordx4 v166, s[14:15]
	s_add_i32 m0, s26, 0x2000
	s_nop 0
	global_load_lds_dwordx4 v170, s[14:15]
	s_mov_b32 m0, s37
	s_nop 0
	global_load_lds_dwordx4 v164, s[100:101]
	s_mov_b32 m0, s38
	s_nop 0
	global_load_lds_dwordx4 v168, s[100:101]
	s_waitcnt vmcnt(8)
	s_waitcnt lgkmcnt(0)
	s_setprio 1
	s_barrier
	v_mfma_f32_16x16x32_bf16 v[60:63], v[128:131], v[160:163], v[60:63]
	v_mfma_f32_16x16x32_bf16 v[60:63], v[132:135], v[182:185], v[60:63]
	v_mfma_f32_16x16x32_bf16 v[48:51], v[128:131], v[186:189], v[48:51]
	v_mfma_f32_16x16x32_bf16 v[48:51], v[132:135], v[190:193], v[48:51]
	v_mfma_f32_16x16x32_bf16 v[32:35], v[128:131], v[204:207], v[32:35]
	v_mfma_f32_16x16x32_bf16 v[32:35], v[132:135], v[208:211], v[32:35]
	v_mfma_f32_16x16x32_bf16 v[16:19], v[128:131], v[212:215], v[16:19]
	v_mfma_f32_16x16x32_bf16 v[16:19], v[132:135], v[216:219], v[16:19]
	v_mfma_f32_16x16x32_bf16 v[56:59], v[136:139], v[160:163], v[56:59]
	v_mfma_f32_16x16x32_bf16 v[56:59], v[140:143], v[182:185], v[56:59]
	v_mfma_f32_16x16x32_bf16 v[40:43], v[136:139], v[186:189], v[40:43]
	v_mfma_f32_16x16x32_bf16 v[40:43], v[140:143], v[190:193], v[40:43]
	v_mfma_f32_16x16x32_bf16 v[24:27], v[136:139], v[204:207], v[24:27]
	v_mfma_f32_16x16x32_bf16 v[24:27], v[140:143], v[208:211], v[24:27]
	v_mfma_f32_16x16x32_bf16 v[8:11], v[136:139], v[212:215], v[8:11]
	v_mfma_f32_16x16x32_bf16 v[8:11], v[140:143], v[216:219], v[8:11]
	s_setprio 0
	s_setprio 1
	v_mfma_f32_16x16x32_bf16 v[52:55], v[144:147], v[160:163], v[52:55]
	v_mfma_f32_16x16x32_bf16 v[52:55], v[148:151], v[182:185], v[52:55]
	v_mfma_f32_16x16x32_bf16 v[36:39], v[144:147], v[186:189], v[36:39]
	v_mfma_f32_16x16x32_bf16 v[36:39], v[148:151], v[190:193], v[36:39]
	v_mfma_f32_16x16x32_bf16 v[20:23], v[144:147], v[204:207], v[20:23]
	v_mfma_f32_16x16x32_bf16 v[20:23], v[148:151], v[208:211], v[20:23]
	v_mfma_f32_16x16x32_bf16 v[4:7], v[144:147], v[212:215], v[4:7]
	v_mfma_f32_16x16x32_bf16 v[4:7], v[148:151], v[216:219], v[4:7]
	v_mfma_f32_16x16x32_bf16 v[44:47], v[152:155], v[160:163], v[44:47]
	v_mfma_f32_16x16x32_bf16 v[44:47], v[156:159], v[182:185], v[44:47]
	v_mfma_f32_16x16x32_bf16 v[28:31], v[152:155], v[186:189], v[28:31]
	v_mfma_f32_16x16x32_bf16 v[28:31], v[156:159], v[190:193], v[28:31]
	v_mfma_f32_16x16x32_bf16 v[12:15], v[152:155], v[204:207], v[12:15]
	v_mfma_f32_16x16x32_bf16 v[12:15], v[156:159], v[208:211], v[12:15]
	v_mfma_f32_16x16x32_bf16 v[0:3], v[152:155], v[212:215], v[0:3]
	v_mfma_f32_16x16x32_bf16 v[0:3], v[156:159], v[216:219], v[0:3]
	s_barrier
	s_setprio 0
	s_add_i32 s48, s48, 2
	s_add_u32 s24, s24, 0x100
	s_addc_u32 s25, s25, 0
	s_add_u32 s46, s46, 0x100
	s_addc_u32 s47, s47, 0
	s_cmpk_gt_u32 s48, 0x55
	s_cbranch_scc0 .LBB0_1193
	s_and_b64 vcc, exec, s[20:21]
	s_cbranch_vccz .LBB0_1196
	s_barrier

; __global__ void __launch_bounds__(512) fwd_kernel(Prm P) {
	.amdhsa_kernel _Z10fwd_kernel3Prm
		.amdhsa_group_segment_fixed_size 0
		.amdhsa_private_segment_fixed_size 0
		.amdhsa_kernarg_size 432
		.amdhsa_user_sgpr_count 2
		.amdhsa_user_sgpr_dispatch_ptr 0
		.amdhsa_user_sgpr_queue_ptr 0
		.amdhsa_user_sgpr_kernarg_segment_ptr 1
		.amdhsa_user_sgpr_dispatch_id 0
		.amdhsa_user_sgpr_kernarg_preload_length 0
		.amdhsa_user_sgpr_kernarg_preload_offset 0
		.amdhsa_user_sgpr_private_segment_size 0
		.amdhsa_uses_dynamic_stack 0
		.amdhsa_enable_private_segment 0
		.amdhsa_system_sgpr_workgroup_id_x 1
		.amdhsa_system_sgpr_workgroup_id_y 0
		.amdhsa_system_sgpr_workgroup_id_z 0
		.amdhsa_system_sgpr_workgroup_info 0
		.amdhsa_system_vgpr_workitem_id 2
		.amdhsa_next_free_vgpr 256
		.amdhsa_next_free_sgpr 102
		.amdhsa_accum_offset 256
		.amdhsa_reserve_vcc 1
		.amdhsa_float_round_mode_32 0
		.amdhsa_float_round_mode_16_64 0
		.amdhsa_float_denorm_mode_32 3
		.amdhsa_float_denorm_mode_16_64 3
		.amdhsa_dx10_clamp 1
		.amdhsa_ieee_mode 1
		.amdhsa_fp16_overflow 0
		.amdhsa_tg_split 0
		.amdhsa_exception_fp_ieee_invalid_op 0
		.amdhsa_exception_fp_denorm_src 0
		.amdhsa_exception_fp_ieee_div_zero 0
		.amdhsa_exception_fp_ieee_overflow 0
		.amdhsa_exception_fp_ieee_underflow 0
		.amdhsa_exception_fp_ieee_inexact 0
		.amdhsa_exception_int_div_zero 0
	.end_amdhsa_kernel

; __global__ void __launch_bounds__(512) fwd_kernel(Prm P) {
.Lfunc_end0:
	.size	_Z10fwd_kernel3Prm, .Lfunc_end0-_Z10fwd_kernel3Prm
	.set _Z10fwd_kernel3Prm.num_vgpr, 256
	.set _Z10fwd_kernel3Prm.num_agpr, 0
	.set _Z10fwd_kernel3Prm.numbered_sgpr, 102
	.set _Z10fwd_kernel3Prm.num_named_barrier, 0
	.set _Z10fwd_kernel3Prm.private_seg_size, 0
	.set _Z10fwd_kernel3Prm.uses_vcc, 1
	.set _Z10fwd_kernel3Prm.uses_flat_scratch, 0
	.set _Z10fwd_kernel3Prm.has_dyn_sized_stack, 0
	.set _Z10fwd_kernel3Prm.has_recursion, 0
	.set _Z10fwd_kernel3Prm.has_indirect_call, 0

amdhsa.kernels:
  - .agpr_count:     0
    .args:
      - .offset:         0
        .size:           176
        .value_kind:     by_value
      - .offset:         176
        .size:           4
        .value_kind:     hidden_block_count_x
      - .offset:         180
        .size:           4
        .value_kind:     hidden_block_count_y
      - .offset:         184
        .size:           4
        .value_kind:     hidden_block_count_z
      - .offset:         188
        .size:           2
        .value_kind:     hidden_group_size_x
      - .offset:         190
        .size:           2
        .value_kind:     hidden_group_size_y
      - .offset:         192
        .size:           2
        .value_kind:     hidden_group_size_z
      - .offset:         194
        .size:           2
        .value_kind:     hidden_remainder_x
      - .offset:         196
        .size:           2
        .value_kind:     hidden_remainder_y
      - .offset:         198
        .size:           2
        .value_kind:     hidden_remainder_z
      - .offset:         216
        .size:           8
        .value_kind:     hidden_global_offset_x
      - .offset:         224
        .size:           8
        .value_kind:     hidden_global_offset_y
      - .offset:         232
        .size:           8
        .value_kind:     hidden_global_offset_z
      - .offset:         240
        .size:           2
        .value_kind:     hidden_grid_dims
      - .offset:         264
        .size:           8
        .value_kind:     hidden_multigrid_sync_arg
      - .offset:         296
        .size:           4
        .value_kind:     hidden_dynamic_lds_size
    .group_segment_fixed_size: 0
    .kernarg_segment_align: 8
    .kernarg_segment_size: 432
    .language:       OpenCL C
    .language_version:
      - 2
      - 0
    .max_flat_workgroup_size: 512
    .name:           _Z10fwd_kernel3Prm
    .private_segment_fixed_size: 0
    .sgpr_count:     108
    .sgpr_spill_count: 80
    .symbol:         _Z10fwd_kernel3Prm.kd
    .uniform_work_group_size: 1
    .uses_dynamic_stack: false
    .vgpr_count:     256
    .vgpr_spill_count: 0
    .wavefront_size: 64
